# 8-phase loops: s_setprio 1 around each phase's MFMAs
# speedup vs baseline: 1.0000x; 1.0000x over previous
; template <bool SWAP>
; DI void gemm_mainloop(f32x16 (&acc)[4][2], const u16* __restrict__ A, int lda, int rlo, int rhi,
;                       const u16* __restrict__ B, int ldb, int K, char* lds, const u16* zero_line) {
;     ...
;   for (int kt = 0; kt < nk; ++kt) {
;     const char* st = lds + (kt & 1) * 65536;
;     ldfrag(st, 0, 0);
;     mma(1);
;     pat_rd();
;     if (kt + 1 < nk) glds(kt + 1, (kt + 1) & 1);
;     ldfrag(st, 1, 1);
;     mma(0);
;     pat_rd();
;     ldfrag(st, 2, 0);
;     mma(1);
;     pat_rd();
;     ldfrag(st, 3, 1);
;     mma(0);
;     pat_rd();
;     asm volatile("s_waitcnt vmcnt(0)" ::: "memory");
;     __syncthreads();
.Lg8_u0u:
	v_add3_u32 v166, v248, v244, 0
	v_add3_u32 v167, v248, v245, 0
	v_add3_u32 v175, v248, v246, 0
	v_add3_u32 v185, v248, v247, 0
	ds_read_b128 v[130:133], v166
	ds_read_b128 v[134:137], v167
	ds_read_b128 v[138:141], v175
	ds_read_b128 v[142:145], v185
	ds_read_b128 v[146:149], v166 offset:4096
	ds_read_b128 v[150:153], v167 offset:4096
	ds_read_b128 v[158:161], v175 offset:4096
	ds_read_b128 v[162:165], v185 offset:4096
	s_add_u32 m0, s100, 0x14000
	s_nop 0
	global_load_lds_dwordx4 v237, s[18:19]
	v_add_u32_e32 v237, 0x80, v237
	s_add_u32 m0, s100, 0x16000
	s_nop 0
	global_load_lds_dwordx4 v239, s[18:19]
	v_add_u32_e32 v239, 0x80, v239
	s_barrier
	s_waitcnt lgkmcnt(0)
	s_setprio 1
	v_mfma_f32_32x32x16_bf16 v[114:129], v[176:179], v[130:133], v[114:129]
	v_mfma_f32_32x32x16_bf16 v[82:97], v[176:179], v[146:149], v[82:97]
	v_mfma_f32_32x32x16_bf16 v[114:129], v[180:183], v[134:137], v[114:129]
	v_mfma_f32_32x32x16_bf16 v[82:97], v[180:183], v[150:153], v[82:97]
	v_mfma_f32_32x32x16_bf16 v[114:129], v[186:189], v[138:141], v[114:129]
	v_mfma_f32_32x32x16_bf16 v[82:97], v[186:189], v[158:161], v[82:97]
	v_mfma_f32_32x32x16_bf16 v[114:129], v[190:193], v[142:145], v[114:129]
	v_mfma_f32_32x32x16_bf16 v[82:97], v[190:193], v[162:165], v[82:97]
	s_setprio 0
	s_barrier
	v_add3_u32 v166, v249, v244, 0
	v_add3_u32 v167, v249, v245, 0
	v_add3_u32 v175, v249, v246, 0
	v_add3_u32 v185, v249, v247, 0
	ds_read_b128 v[194:197], v166 offset:49152
	ds_read_b128 v[198:201], v167 offset:49152
	ds_read_b128 v[228:231], v175 offset:49152
	ds_read_b128 v[232:235], v185 offset:49152
	s_add_u32 m0, s100, 0x8000
	s_nop 0
	global_load_lds_dwordx4 v240, s[22:23]
	v_add_u32_e32 v240, 0x80, v240
	s_add_u32 m0, s100, 0xa000
	s_nop 0
	global_load_lds_dwordx4 v242, s[22:23]
	v_add_u32_e32 v242, 0x80, v242
	s_barrier
	s_waitcnt lgkmcnt(0)
	s_setprio 1
	v_mfma_f32_32x32x16_bf16 v[98:113], v[194:197], v[130:133], v[98:113]
	v_mfma_f32_32x32x16_bf16 v[66:81], v[194:197], v[146:149], v[66:81]
	v_mfma_f32_32x32x16_bf16 v[98:113], v[198:201], v[134:137], v[98:113]
	v_mfma_f32_32x32x16_bf16 v[66:81], v[198:201], v[150:153], v[66:81]
	v_mfma_f32_32x32x16_bf16 v[98:113], v[228:231], v[138:141], v[98:113]
	v_mfma_f32_32x32x16_bf16 v[66:81], v[228:231], v[158:161], v[66:81]
	v_mfma_f32_32x32x16_bf16 v[98:113], v[232:235], v[142:145], v[98:113]
	v_mfma_f32_32x32x16_bf16 v[66:81], v[232:235], v[162:165], v[66:81]
	s_setprio 0
	s_barrier
	v_add3_u32 v166, v248, v244, 0
	v_add3_u32 v167, v248, v245, 0
	v_add3_u32 v175, v248, v246, 0
	v_add3_u32 v185, v248, v247, 0
	ds_read_b128 v[130:133], v166 offset:16384
	ds_read_b128 v[134:137], v167 offset:16384
	ds_read_b128 v[138:141], v175 offset:16384
	ds_read_b128 v[142:145], v185 offset:16384
	ds_read_b128 v[146:149], v166 offset:20480
	ds_read_b128 v[150:153], v167 offset:20480
	ds_read_b128 v[158:161], v175 offset:20480
	ds_read_b128 v[162:165], v185 offset:20480
	s_add_u32 m0, s100, 0x0
	s_nop 0
	global_load_lds_dwordx4 v236, s[18:19]
	v_add_u32_e32 v236, 0x80, v236
	s_add_u32 m0, s100, 0x2000
	s_nop 0
	global_load_lds_dwordx4 v238, s[18:19]
	v_add_u32_e32 v238, 0x80, v238
	s_waitcnt vmcnt(10)
	s_barrier
	s_waitcnt lgkmcnt(0)
	s_setprio 1
	v_mfma_f32_32x32x16_bf16 v[50:65], v[176:179], v[130:133], v[50:65]
	v_mfma_f32_32x32x16_bf16 v[18:33], v[176:179], v[146:149], v[18:33]
	v_mfma_f32_32x32x16_bf16 v[50:65], v[180:183], v[134:137], v[50:65]
	v_mfma_f32_32x32x16_bf16 v[18:33], v[180:183], v[150:153], v[18:33]
	v_mfma_f32_32x32x16_bf16 v[50:65], v[186:189], v[138:141], v[50:65]
	v_mfma_f32_32x32x16_bf16 v[18:33], v[186:189], v[158:161], v[18:33]
	v_mfma_f32_32x32x16_bf16 v[50:65], v[190:193], v[142:145], v[50:65]
	v_mfma_f32_32x32x16_bf16 v[18:33], v[190:193], v[162:165], v[18:33]
	s_setprio 0
	s_barrier
	v_add3_u32 v166, v249, v244, s21
	v_add3_u32 v167, v249, v245, s21
	v_add3_u32 v175, v249, v246, s21
	v_add3_u32 v185, v249, v247, s21
	ds_read_b128 v[176:179], v166 offset:32768
	ds_read_b128 v[180:183], v167 offset:32768
	ds_read_b128 v[186:189], v175 offset:32768
	ds_read_b128 v[190:193], v185 offset:32768
	s_add_u32 m0, s100, 0xc000
	s_nop 0
	global_load_lds_dwordx4 v241, s[22:23]
	v_add_u32_e32 v241, 0x80, v241
	s_add_u32 m0, s100, 0xe000
	s_nop 0
	global_load_lds_dwordx4 v243, s[22:23]
	v_add_u32_e32 v243, 0x80, v243
	s_waitcnt vmcnt(6)
	s_barrier
	s_waitcnt lgkmcnt(0)
	s_setprio 1
	v_mfma_f32_32x32x16_bf16 v[34:49], v[194:197], v[130:133], v[34:49]
	v_mfma_f32_32x32x16_bf16 v[2:17], v[194:197], v[146:149], v[2:17]
	v_mfma_f32_32x32x16_bf16 v[34:49], v[198:201], v[134:137], v[34:49]
	v_mfma_f32_32x32x16_bf16 v[2:17], v[198:201], v[150:153], v[2:17]
	v_mfma_f32_32x32x16_bf16 v[34:49], v[228:231], v[138:141], v[34:49]
	v_mfma_f32_32x32x16_bf16 v[2:17], v[228:231], v[158:161], v[2:17]
	v_mfma_f32_32x32x16_bf16 v[34:49], v[232:235], v[142:145], v[34:49]
	v_mfma_f32_32x32x16_bf16 v[2:17], v[232:235], v[162:165], v[2:17]
	s_setprio 0
	s_barrier
	v_add3_u32 v166, v248, v244, s21
	v_add3_u32 v167, v248, v245, s21
	v_add3_u32 v175, v248, v246, s21
	v_add3_u32 v185, v248, v247, s21
	ds_read_b128 v[130:133], v166
	ds_read_b128 v[134:137], v167
	ds_read_b128 v[138:141], v175
	ds_read_b128 v[142:145], v185
	ds_read_b128 v[146:149], v166 offset:4096
	ds_read_b128 v[150:153], v167 offset:4096
	ds_read_b128 v[158:161], v175 offset:4096
	ds_read_b128 v[162:165], v185 offset:4096
	s_add_u32 m0, s100, 0x4000
	s_nop 0
	global_load_lds_dwordx4 v237, s[18:19]
	v_add_u32_e32 v237, 0x80, v237
	s_add_u32 m0, s100, 0x6000
	s_nop 0
	global_load_lds_dwordx4 v239, s[18:19]
	v_add_u32_e32 v239, 0x80, v239
	s_barrier
; template <bool SWAP>
; DI void gemm_mainloop(f32x16 (&acc)[4][2], const u16* __restrict__ A, int lda, int rlo, int rhi,
;                       const u16* __restrict__ B, int ldb, int K, char* lds, const u16* zero_line) {
;     ...
;   for (int kt = 0; kt < nk; ++kt) {
;     const char* st = lds + (kt & 1) * 65536;
;     ldfrag(st, 0, 0);
;     mma(1);
;     pat_rd();
;     if (kt + 1 < nk) glds(kt + 1, (kt + 1) & 1);
;     ldfrag(st, 1, 1);
;     mma(0);
;     pat_rd();
;     ldfrag(st, 2, 0);
;     mma(1);
;     pat_rd();
;     ldfrag(st, 3, 1);
;     mma(0);
;     pat_rd();
;     asm volatile("s_waitcnt vmcnt(0)" ::: "memory");
;     __syncthreads();
	s_waitcnt lgkmcnt(0)
	s_setprio 1
	v_mfma_f32_32x32x16_bf16 v[114:129], v[176:179], v[130:133], v[114:129]
	v_mfma_f32_32x32x16_bf16 v[82:97], v[176:179], v[146:149], v[82:97]
	v_mfma_f32_32x32x16_bf16 v[114:129], v[180:183], v[134:137], v[114:129]
	v_mfma_f32_32x32x16_bf16 v[82:97], v[180:183], v[150:153], v[82:97]
	v_mfma_f32_32x32x16_bf16 v[114:129], v[186:189], v[138:141], v[114:129]
	v_mfma_f32_32x32x16_bf16 v[82:97], v[186:189], v[158:161], v[82:97]
	v_mfma_f32_32x32x16_bf16 v[114:129], v[190:193], v[142:145], v[114:129]
	v_mfma_f32_32x32x16_bf16 v[82:97], v[190:193], v[162:165], v[82:97]
	s_setprio 0
	s_barrier
	v_add3_u32 v166, v249, v244, s21
	v_add3_u32 v167, v249, v245, s21
	v_add3_u32 v175, v249, v246, s21
	v_add3_u32 v185, v249, v247, s21
	ds_read_b128 v[194:197], v166 offset:49152
	ds_read_b128 v[198:201], v167 offset:49152
	ds_read_b128 v[228:231], v175 offset:49152
	ds_read_b128 v[232:235], v185 offset:49152
	s_add_u32 m0, s100, 0x18000
	s_nop 0
	global_load_lds_dwordx4 v240, s[22:23]
	v_add_u32_e32 v240, 0x80, v240
	s_add_u32 m0, s100, 0x1a000
	s_nop 0
	global_load_lds_dwordx4 v242, s[22:23]
	v_add_u32_e32 v242, 0x80, v242
	s_barrier
	s_waitcnt lgkmcnt(0)
	s_setprio 1
	v_mfma_f32_32x32x16_bf16 v[98:113], v[194:197], v[130:133], v[98:113]
	v_mfma_f32_32x32x16_bf16 v[66:81], v[194:197], v[146:149], v[66:81]
	v_mfma_f32_32x32x16_bf16 v[98:113], v[198:201], v[134:137], v[98:113]
	v_mfma_f32_32x32x16_bf16 v[66:81], v[198:201], v[150:153], v[66:81]
	v_mfma_f32_32x32x16_bf16 v[98:113], v[228:231], v[138:141], v[98:113]
	v_mfma_f32_32x32x16_bf16 v[66:81], v[228:231], v[158:161], v[66:81]
	v_mfma_f32_32x32x16_bf16 v[98:113], v[232:235], v[142:145], v[98:113]
	v_mfma_f32_32x32x16_bf16 v[66:81], v[232:235], v[162:165], v[66:81]
	s_setprio 0
	s_barrier
	v_add3_u32 v166, v248, v244, s21
	v_add3_u32 v167, v248, v245, s21
	v_add3_u32 v175, v248, v246, s21
	v_add3_u32 v185, v248, v247, s21
	ds_read_b128 v[130:133], v166 offset:16384
	ds_read_b128 v[134:137], v167 offset:16384
	ds_read_b128 v[138:141], v175 offset:16384
	ds_read_b128 v[142:145], v185 offset:16384
	ds_read_b128 v[146:149], v166 offset:20480
	ds_read_b128 v[150:153], v167 offset:20480
	ds_read_b128 v[158:161], v175 offset:20480
	ds_read_b128 v[162:165], v185 offset:20480
	s_add_u32 m0, s100, 0x10000
	s_nop 0
	global_load_lds_dwordx4 v236, s[18:19]
	v_add_u32_e32 v236, 0x80, v236
	s_add_u32 m0, s100, 0x12000
	s_nop 0
	global_load_lds_dwordx4 v238, s[18:19]
	v_add_u32_e32 v238, 0x80, v238
	s_waitcnt vmcnt(10)
	s_barrier
	s_waitcnt lgkmcnt(0)
	s_setprio 1
	v_mfma_f32_32x32x16_bf16 v[50:65], v[176:179], v[130:133], v[50:65]
	v_mfma_f32_32x32x16_bf16 v[18:33], v[176:179], v[146:149], v[18:33]
	v_mfma_f32_32x32x16_bf16 v[50:65], v[180:183], v[134:137], v[50:65]
	v_mfma_f32_32x32x16_bf16 v[18:33], v[180:183], v[150:153], v[18:33]
	v_mfma_f32_32x32x16_bf16 v[50:65], v[186:189], v[138:141], v[50:65]
	v_mfma_f32_32x32x16_bf16 v[18:33], v[186:189], v[158:161], v[18:33]
	v_mfma_f32_32x32x16_bf16 v[50:65], v[190:193], v[142:145], v[50:65]
	v_mfma_f32_32x32x16_bf16 v[18:33], v[190:193], v[162:165], v[18:33]
	s_setprio 0
	s_barrier
	v_add3_u32 v166, v249, v244, 0
	v_add3_u32 v167, v249, v245, 0
	v_add3_u32 v175, v249, v246, 0
	v_add3_u32 v185, v249, v247, 0
	ds_read_b128 v[176:179], v166 offset:32768
	ds_read_b128 v[180:183], v167 offset:32768
	ds_read_b128 v[186:189], v175 offset:32768
	ds_read_b128 v[190:193], v185 offset:32768
	s_add_u32 m0, s100, 0x1c000
	s_nop 0
	global_load_lds_dwordx4 v241, s[22:23]
	v_add_u32_e32 v241, 0x80, v241
	s_add_u32 m0, s100, 0x1e000
	s_nop 0
	global_load_lds_dwordx4 v243, s[22:23]
	v_add_u32_e32 v243, 0x80, v243
	s_waitcnt vmcnt(6)
	s_barrier
	s_waitcnt lgkmcnt(0)
	s_setprio 1
	v_mfma_f32_32x32x16_bf16 v[34:49], v[194:197], v[130:133], v[34:49]
	v_mfma_f32_32x32x16_bf16 v[2:17], v[194:197], v[146:149], v[2:17]
	v_mfma_f32_32x32x16_bf16 v[34:49], v[198:201], v[134:137], v[34:49]
	v_mfma_f32_32x32x16_bf16 v[2:17], v[198:201], v[150:153], v[2:17]
	v_mfma_f32_32x32x16_bf16 v[34:49], v[228:231], v[138:141], v[34:49]
	v_mfma_f32_32x32x16_bf16 v[2:17], v[228:231], v[158:161], v[2:17]
	v_mfma_f32_32x32x16_bf16 v[34:49], v[232:235], v[142:145], v[34:49]
	v_mfma_f32_32x32x16_bf16 v[2:17], v[232:235], v[162:165], v[2:17]
	s_setprio 0
	s_barrier
	s_add_i32 s29, s29, 2
	s_cmp_lt_u32 s29, 14
	s_cbranch_scc1 .Lg8_u0u
	v_add3_u32 v166, v248, v244, 0
	v_add3_u32 v167, v248, v245, 0
	v_add3_u32 v175, v248, v246, 0
	v_add3_u32 v185, v248, v247, 0
	ds_read_b128 v[130:133], v166
	ds_read_b128 v[134:137], v167
	ds_read_b128 v[138:141], v175
	ds_read_b128 v[142:145], v185
	ds_read_b128 v[146:149], v166 offset:4096
	ds_read_b128 v[150:153], v167 offset:4096
	ds_read_b128 v[158:161], v175 offset:4096
	ds_read_b128 v[162:165], v185 offset:4096
	s_add_u32 m0, s100, 0x14000
	s_nop 0
	global_load_lds_dwordx4 v237, s[18:19]
	v_add_u32_e32 v237, 0x80, v237
	s_add_u32 m0, s100, 0x16000
	s_nop 0
	global_load_lds_dwordx4 v239, s[18:19]
	v_add_u32_e32 v239, 0x80, v239
	s_barrier
	s_waitcnt lgkmcnt(0)
	v_mfma_f32_32x32x16_bf16 v[114:129], v[176:179], v[130:133], v[114:129]
	v_mfma_f32_32x32x16_bf16 v[82:97], v[176:179], v[146:149], v[82:97]
	v_mfma_f32_32x32x16_bf16 v[114:129], v[180:183], v[134:137], v[114:129]
	v_mfma_f32_32x32x16_bf16 v[82:97], v[180:183], v[150:153], v[82:97]
	v_mfma_f32_32x32x16_bf16 v[114:129], v[186:189], v[138:141], v[114:129]
	v_mfma_f32_32x32x16_bf16 v[82:97], v[186:189], v[158:161], v[82:97]
	v_mfma_f32_32x32x16_bf16 v[114:129], v[190:193], v[142:145], v[114:129]
	v_mfma_f32_32x32x16_bf16 v[82:97], v[190:193], v[162:165], v[82:97]
	s_barrier
; template <bool SWAP>
; DI void gemm_mainloop(f32x16 (&acc)[4][2], const u16* __restrict__ A, int lda, int rlo, int rhi,
;                       const u16* __restrict__ B, int ldb, int K, char* lds, const u16* zero_line) {
;     ...
;   for (int kt = 0; kt < nk; ++kt) {
;     const char* st = lds + (kt & 1) * 65536;
;     ldfrag(st, 0, 0);
;     mma(1);
;     pat_rd();
;     if (kt + 1 < nk) glds(kt + 1, (kt + 1) & 1);
;     ldfrag(st, 1, 1);
;     mma(0);
;     pat_rd();
;     ldfrag(st, 2, 0);
;     mma(1);
;     pat_rd();
;     ldfrag(st, 3, 1);
;     mma(0);
;     pat_rd();
;     asm volatile("s_waitcnt vmcnt(0)" ::: "memory");
;     __syncthreads();
;   }
;   mma(1);
	v_add3_u32 v166, v249, v244, 0
	v_add3_u32 v167, v249, v245, 0
	v_add3_u32 v175, v249, v246, 0
	v_add3_u32 v185, v249, v247, 0
	ds_read_b128 v[194:197], v166 offset:49152
	ds_read_b128 v[198:201], v167 offset:49152
	ds_read_b128 v[228:231], v175 offset:49152
	ds_read_b128 v[232:235], v185 offset:49152
	s_barrier
	s_waitcnt lgkmcnt(0)
	v_mfma_f32_32x32x16_bf16 v[98:113], v[194:197], v[130:133], v[98:113]
	v_mfma_f32_32x32x16_bf16 v[66:81], v[194:197], v[146:149], v[66:81]
	v_mfma_f32_32x32x16_bf16 v[98:113], v[198:201], v[134:137], v[98:113]
	v_mfma_f32_32x32x16_bf16 v[66:81], v[198:201], v[150:153], v[66:81]
	v_mfma_f32_32x32x16_bf16 v[98:113], v[228:231], v[138:141], v[98:113]
	v_mfma_f32_32x32x16_bf16 v[66:81], v[228:231], v[158:161], v[66:81]
	v_mfma_f32_32x32x16_bf16 v[98:113], v[232:235], v[142:145], v[98:113]
	v_mfma_f32_32x32x16_bf16 v[66:81], v[232:235], v[162:165], v[66:81]
	s_barrier
	v_add3_u32 v166, v248, v244, 0
	v_add3_u32 v167, v248, v245, 0
	v_add3_u32 v175, v248, v246, 0
	v_add3_u32 v185, v248, v247, 0
	ds_read_b128 v[130:133], v166 offset:16384
	ds_read_b128 v[134:137], v167 offset:16384
	ds_read_b128 v[138:141], v175 offset:16384
	ds_read_b128 v[142:145], v185 offset:16384
	ds_read_b128 v[146:149], v166 offset:20480
	ds_read_b128 v[150:153], v167 offset:20480
	ds_read_b128 v[158:161], v175 offset:20480
	ds_read_b128 v[162:165], v185 offset:20480
	s_waitcnt vmcnt(4)
	s_barrier
	s_waitcnt lgkmcnt(0)
	v_mfma_f32_32x32x16_bf16 v[50:65], v[176:179], v[130:133], v[50:65]
	v_mfma_f32_32x32x16_bf16 v[18:33], v[176:179], v[146:149], v[18:33]
	v_mfma_f32_32x32x16_bf16 v[50:65], v[180:183], v[134:137], v[50:65]
	v_mfma_f32_32x32x16_bf16 v[18:33], v[180:183], v[150:153], v[18:33]
	v_mfma_f32_32x32x16_bf16 v[50:65], v[186:189], v[138:141], v[50:65]
	v_mfma_f32_32x32x16_bf16 v[18:33], v[186:189], v[158:161], v[18:33]
	v_mfma_f32_32x32x16_bf16 v[50:65], v[190:193], v[142:145], v[50:65]
	v_mfma_f32_32x32x16_bf16 v[18:33], v[190:193], v[162:165], v[18:33]
	v_mfma_f32_32x32x16_bf16 v[34:49], v[194:197], v[130:133], v[34:49]
	v_mfma_f32_32x32x16_bf16 v[2:17], v[194:197], v[146:149], v[2:17]
	v_mfma_f32_32x32x16_bf16 v[34:49], v[198:201], v[134:137], v[34:49]
	v_mfma_f32_32x32x16_bf16 v[2:17], v[198:201], v[150:153], v[2:17]
	v_mfma_f32_32x32x16_bf16 v[34:49], v[228:231], v[138:141], v[34:49]
	v_mfma_f32_32x32x16_bf16 v[2:17], v[228:231], v[158:161], v[2:17]
	v_mfma_f32_32x32x16_bf16 v[34:49], v[232:235], v[142:145], v[34:49]
	v_mfma_f32_32x32x16_bf16 v[2:17], v[232:235], v[162:165], v[2:17]
	s_barrier
	v_add3_u32 v166, v249, v244, s21
	v_add3_u32 v167, v249, v245, s21
	v_add3_u32 v175, v249, v246, s21
	v_add3_u32 v185, v249, v247, s21
	ds_read_b128 v[176:179], v166 offset:32768
	ds_read_b128 v[180:183], v167 offset:32768
	ds_read_b128 v[186:189], v175 offset:32768
	ds_read_b128 v[190:193], v185 offset:32768
	v_add3_u32 v166, v248, v244, s21
	v_add3_u32 v167, v248, v245, s21
	v_add3_u32 v175, v248, v246, s21
	v_add3_u32 v185, v248, v247, s21
	ds_read_b128 v[130:133], v166
	ds_read_b128 v[134:137], v167
	ds_read_b128 v[138:141], v175
	ds_read_b128 v[142:145], v185
	ds_read_b128 v[146:149], v166 offset:4096
	ds_read_b128 v[150:153], v167 offset:4096
	ds_read_b128 v[158:161], v175 offset:4096
	ds_read_b128 v[162:165], v185 offset:4096
	s_waitcnt vmcnt(2)
	s_barrier
	s_waitcnt lgkmcnt(0)
	v_mfma_f32_32x32x16_bf16 v[114:129], v[176:179], v[130:133], v[114:129]
	v_mfma_f32_32x32x16_bf16 v[82:97], v[176:179], v[146:149], v[82:97]
	v_mfma_f32_32x32x16_bf16 v[114:129], v[180:183], v[134:137], v[114:129]
	v_mfma_f32_32x32x16_bf16 v[82:97], v[180:183], v[150:153], v[82:97]
	v_mfma_f32_32x32x16_bf16 v[114:129], v[186:189], v[138:141], v[114:129]
	v_mfma_f32_32x32x16_bf16 v[82:97], v[186:189], v[158:161], v[82:97]
	v_mfma_f32_32x32x16_bf16 v[114:129], v[190:193], v[142:145], v[114:129]
	v_mfma_f32_32x32x16_bf16 v[82:97], v[190:193], v[162:165], v[82:97]
	s_barrier
	v_add3_u32 v166, v249, v244, s21
	v_add3_u32 v167, v249, v245, s21
	v_add3_u32 v175, v249, v246, s21
	v_add3_u32 v185, v249, v247, s21
	ds_read_b128 v[194:197], v166 offset:49152
	ds_read_b128 v[198:201], v167 offset:49152
	ds_read_b128 v[228:231], v175 offset:49152
	ds_read_b128 v[232:235], v185 offset:49152
	s_waitcnt vmcnt(0)
	s_barrier
	s_waitcnt lgkmcnt(0)
	v_mfma_f32_32x32x16_bf16 v[98:113], v[194:197], v[130:133], v[98:113]
	v_mfma_f32_32x32x16_bf16 v[66:81], v[194:197], v[146:149], v[66:81]
	v_mfma_f32_32x32x16_bf16 v[98:113], v[198:201], v[134:137], v[98:113]
	v_mfma_f32_32x32x16_bf16 v[66:81], v[198:201], v[150:153], v[66:81]
	v_mfma_f32_32x32x16_bf16 v[98:113], v[228:231], v[138:141], v[98:113]
	v_mfma_f32_32x32x16_bf16 v[66:81], v[228:231], v[158:161], v[66:81]
	v_mfma_f32_32x32x16_bf16 v[98:113], v[232:235], v[142:145], v[98:113]
	v_mfma_f32_32x32x16_bf16 v[66:81], v[232:235], v[162:165], v[66:81]
	s_barrier
	v_add3_u32 v166, v248, v244, s21
	v_add3_u32 v167, v248, v245, s21
	v_add3_u32 v175, v248, v246, s21
	v_add3_u32 v185, v248, v247, s21
	ds_read_b128 v[130:133], v166 offset:16384
	ds_read_b128 v[134:137], v167 offset:16384
	ds_read_b128 v[138:141], v175 offset:16384
	ds_read_b128 v[142:145], v185 offset:16384
	ds_read_b128 v[146:149], v166 offset:20480
	ds_read_b128 v[150:153], v167 offset:20480
	ds_read_b128 v[158:161], v175 offset:20480
	ds_read_b128 v[162:165], v185 offset:20480
	s_barrier
	s_waitcnt lgkmcnt(0)
	v_mfma_f32_32x32x16_bf16 v[50:65], v[176:179], v[130:133], v[50:65]
	v_mfma_f32_32x32x16_bf16 v[18:33], v[176:179], v[146:149], v[18:33]
	v_mfma_f32_32x32x16_bf16 v[50:65], v[180:183], v[134:137], v[50:65]
	v_mfma_f32_32x32x16_bf16 v[18:33], v[180:183], v[150:153], v[18:33]
	v_mfma_f32_32x32x16_bf16 v[50:65], v[186:189], v[138:141], v[50:65]
	v_mfma_f32_32x32x16_bf16 v[18:33], v[186:189], v[158:161], v[18:33]
	v_mfma_f32_32x32x16_bf16 v[50:65], v[190:193], v[142:145], v[50:65]
	v_mfma_f32_32x32x16_bf16 v[18:33], v[190:193], v[162:165], v[18:33]
	v_mfma_f32_32x32x16_bf16 v[34:49], v[194:197], v[130:133], v[34:49]
	v_mfma_f32_32x32x16_bf16 v[2:17], v[194:197], v[146:149], v[2:17]
	v_mfma_f32_32x32x16_bf16 v[34:49], v[198:201], v[134:137], v[34:49]
	v_mfma_f32_32x32x16_bf16 v[2:17], v[198:201], v[150:153], v[2:17]
	v_mfma_f32_32x32x16_bf16 v[34:49], v[228:231], v[138:141], v[34:49]
	v_mfma_f32_32x32x16_bf16 v[2:17], v[228:231], v[158:161], v[2:17]
	v_mfma_f32_32x32x16_bf16 v[34:49], v[232:235], v[142:145], v[34:49]
	v_mfma_f32_32x32x16_bf16 v[2:17], v[232:235], v[162:165], v[2:17]
	s_barrier
	s_cmp_eq_u32 s101, 0
	s_cbranch_scc0 .Lg8_u0u_p1
	s_barrier

; template <bool SWAP>
; DI void gemm_mainloop(f32x16 (&acc)[4][2], const u16* __restrict__ A, int lda, int rlo, int rhi,
;                       const u16* __restrict__ B, int ldb, int K, char* lds, const u16* zero_line) {
;     ...
;   auto glds = [&](int kt, int st) {
;     char* as_ = lds + st * 65536 + tid * 16;
; #pragma unroll
;     for (int i = 0; i < 4; ++i) {
;       const int rr = lr + 64 * i;
;       const u16* srca = (rr >= rlo && rr < rhi) ? (ap + (ptrdiff_t)(64 * i) * lda + kt * 64) : (zero_line + lc * 8);
;       __builtin_amdgcn_global_load_lds((const unsigned*)srca, (lds_u32*)(as_ + i * 8192), 16, 0, 0);
;       __builtin_amdgcn_global_load_lds((const unsigned*)(bp + (ptrdiff_t)(64 * i) * ldb + kt * 64), (lds_u32*)(as_ + 32768 + i * 8192), 16, 0, 0);
;     }
;   };
;     ...
;   for (int kt = 0; kt < nk; ++kt) {
;     const char* st = lds + (kt & 1) * 65536;
;     ldfrag(st, 0, 0);
;     mma(1);
;     pat_rd();
;     if (kt + 1 < nk) glds(kt + 1, (kt + 1) & 1);
;     ldfrag(st, 1, 1);
;     mma(0);
;     pat_rd();
;     ldfrag(st, 2, 0);
;     mma(1);
;     pat_rd();
;     ldfrag(st, 3, 1);
;     mma(0);
;     pat_rd();
;     asm volatile("s_waitcnt vmcnt(0)" ::: "memory");
;     __syncthreads();
.Lg8_u0m:
	v_add3_u32 v166, v248, v244, 0
	v_add3_u32 v167, v248, v245, 0
	v_add3_u32 v175, v248, v246, 0
	v_add3_u32 v185, v248, v247, 0
	ds_read_b128 v[130:133], v166
	ds_read_b128 v[134:137], v167
	ds_read_b128 v[138:141], v175
	ds_read_b128 v[142:145], v185
	ds_read_b128 v[146:149], v166 offset:4096
	ds_read_b128 v[150:153], v167 offset:4096
	ds_read_b128 v[158:161], v175 offset:4096
	ds_read_b128 v[162:165], v185 offset:4096
	s_add_u32 m0, s100, 0x14000
	s_mov_b64 exec, s[12:13]
	global_load_lds_dwordx4 v237, s[18:19]
	s_mov_b64 exec, -1
	v_add_u32_e32 v237, 0x80, v237
	s_add_u32 m0, s100, 0x16000
	s_mov_b64 exec, s[16:17]
	global_load_lds_dwordx4 v239, s[18:19]
	s_mov_b64 exec, -1
	v_add_u32_e32 v239, 0x80, v239
	s_barrier
	s_waitcnt lgkmcnt(0)
	s_setprio 1
	v_mfma_f32_32x32x16_bf16 v[114:129], v[176:179], v[130:133], v[114:129]
	v_mfma_f32_32x32x16_bf16 v[82:97], v[176:179], v[146:149], v[82:97]
	v_mfma_f32_32x32x16_bf16 v[114:129], v[180:183], v[134:137], v[114:129]
	v_mfma_f32_32x32x16_bf16 v[82:97], v[180:183], v[150:153], v[82:97]
	v_mfma_f32_32x32x16_bf16 v[114:129], v[186:189], v[138:141], v[114:129]
	v_mfma_f32_32x32x16_bf16 v[82:97], v[186:189], v[158:161], v[82:97]
	v_mfma_f32_32x32x16_bf16 v[114:129], v[190:193], v[142:145], v[114:129]
	v_mfma_f32_32x32x16_bf16 v[82:97], v[190:193], v[162:165], v[82:97]
	s_setprio 0
	s_barrier
	v_add3_u32 v166, v249, v244, 0
	v_add3_u32 v167, v249, v245, 0
	v_add3_u32 v175, v249, v246, 0
	v_add3_u32 v185, v249, v247, 0
	ds_read_b128 v[194:197], v166 offset:49152
	ds_read_b128 v[198:201], v167 offset:49152
	ds_read_b128 v[228:231], v175 offset:49152
	ds_read_b128 v[232:235], v185 offset:49152
	s_add_u32 m0, s100, 0x8000
	s_nop 0
	global_load_lds_dwordx4 v240, s[22:23]
	v_add_u32_e32 v240, 0x80, v240
	s_add_u32 m0, s100, 0xa000
	s_nop 0
	global_load_lds_dwordx4 v242, s[22:23]
	v_add_u32_e32 v242, 0x80, v242
	s_barrier
	s_waitcnt lgkmcnt(0)
	s_setprio 1
	v_mfma_f32_32x32x16_bf16 v[98:113], v[194:197], v[130:133], v[98:113]
	v_mfma_f32_32x32x16_bf16 v[66:81], v[194:197], v[146:149], v[66:81]
	v_mfma_f32_32x32x16_bf16 v[98:113], v[198:201], v[134:137], v[98:113]
	v_mfma_f32_32x32x16_bf16 v[66:81], v[198:201], v[150:153], v[66:81]
	v_mfma_f32_32x32x16_bf16 v[98:113], v[228:231], v[138:141], v[98:113]
	v_mfma_f32_32x32x16_bf16 v[66:81], v[228:231], v[158:161], v[66:81]
	v_mfma_f32_32x32x16_bf16 v[98:113], v[232:235], v[142:145], v[98:113]
	v_mfma_f32_32x32x16_bf16 v[66:81], v[232:235], v[162:165], v[66:81]
	s_setprio 0
	s_barrier
	v_add3_u32 v166, v248, v244, 0
	v_add3_u32 v167, v248, v245, 0
	v_add3_u32 v175, v248, v246, 0
	v_add3_u32 v185, v248, v247, 0
	ds_read_b128 v[130:133], v166 offset:16384
	ds_read_b128 v[134:137], v167 offset:16384
	ds_read_b128 v[138:141], v175 offset:16384
	ds_read_b128 v[142:145], v185 offset:16384
	ds_read_b128 v[146:149], v166 offset:20480
	ds_read_b128 v[150:153], v167 offset:20480
	ds_read_b128 v[158:161], v175 offset:20480
	ds_read_b128 v[162:165], v185 offset:20480
	s_add_u32 m0, s100, 0x0
	s_mov_b64 exec, s[10:11]
	global_load_lds_dwordx4 v236, s[18:19]
	s_mov_b64 exec, -1
	v_add_u32_e32 v236, 0x80, v236
	s_add_u32 m0, s100, 0x2000
	s_mov_b64 exec, s[14:15]
	global_load_lds_dwordx4 v238, s[18:19]
	s_mov_b64 exec, -1
	v_add_u32_e32 v238, 0x80, v238
	s_waitcnt vmcnt(10)
	s_barrier
	s_waitcnt lgkmcnt(0)
	s_setprio 1
	v_mfma_f32_32x32x16_bf16 v[50:65], v[176:179], v[130:133], v[50:65]
	v_mfma_f32_32x32x16_bf16 v[18:33], v[176:179], v[146:149], v[18:33]
	v_mfma_f32_32x32x16_bf16 v[50:65], v[180:183], v[134:137], v[50:65]
	v_mfma_f32_32x32x16_bf16 v[18:33], v[180:183], v[150:153], v[18:33]
	v_mfma_f32_32x32x16_bf16 v[50:65], v[186:189], v[138:141], v[50:65]
	v_mfma_f32_32x32x16_bf16 v[18:33], v[186:189], v[158:161], v[18:33]
	v_mfma_f32_32x32x16_bf16 v[50:65], v[190:193], v[142:145], v[50:65]
	v_mfma_f32_32x32x16_bf16 v[18:33], v[190:193], v[162:165], v[18:33]
	s_setprio 0
	s_barrier
	v_add3_u32 v166, v249, v244, s21
	v_add3_u32 v167, v249, v245, s21
	v_add3_u32 v175, v249, v246, s21
	v_add3_u32 v185, v249, v247, s21
	ds_read_b128 v[176:179], v166 offset:32768
	ds_read_b128 v[180:183], v167 offset:32768
	ds_read_b128 v[186:189], v175 offset:32768
	ds_read_b128 v[190:193], v185 offset:32768
	s_add_u32 m0, s100, 0xc000
	s_nop 0
	global_load_lds_dwordx4 v241, s[22:23]
	v_add_u32_e32 v241, 0x80, v241
	s_add_u32 m0, s100, 0xe000
	s_nop 0
	global_load_lds_dwordx4 v243, s[22:23]
	v_add_u32_e32 v243, 0x80, v243
	s_waitcnt vmcnt(6)
	s_barrier
	s_waitcnt lgkmcnt(0)
	s_setprio 1
	v_mfma_f32_32x32x16_bf16 v[34:49], v[194:197], v[130:133], v[34:49]
	v_mfma_f32_32x32x16_bf16 v[2:17], v[194:197], v[146:149], v[2:17]
	v_mfma_f32_32x32x16_bf16 v[34:49], v[198:201], v[134:137], v[34:49]
	v_mfma_f32_32x32x16_bf16 v[2:17], v[198:201], v[150:153], v[2:17]
	v_mfma_f32_32x32x16_bf16 v[34:49], v[228:231], v[138:141], v[34:49]
	v_mfma_f32_32x32x16_bf16 v[2:17], v[228:231], v[158:161], v[2:17]
	v_mfma_f32_32x32x16_bf16 v[34:49], v[232:235], v[142:145], v[34:49]
	v_mfma_f32_32x32x16_bf16 v[2:17], v[232:235], v[162:165], v[2:17]
	s_setprio 0
	s_barrier
	v_add3_u32 v166, v248, v244, s21
	v_add3_u32 v167, v248, v245, s21
	v_add3_u32 v175, v248, v246, s21
	v_add3_u32 v185, v248, v247, s21
	ds_read_b128 v[130:133], v166
	ds_read_b128 v[134:137], v167
	ds_read_b128 v[138:141], v175
	ds_read_b128 v[142:145], v185
	ds_read_b128 v[146:149], v166 offset:4096
	ds_read_b128 v[150:153], v167 offset:4096
	ds_read_b128 v[158:161], v175 offset:4096
	ds_read_b128 v[162:165], v185 offset:4096
	s_add_u32 m0, s100, 0x4000
	s_mov_b64 exec, s[12:13]
	global_load_lds_dwordx4 v237, s[18:19]
	s_mov_b64 exec, -1
	v_add_u32_e32 v237, 0x80, v237
	s_add_u32 m0, s100, 0x6000
	s_mov_b64 exec, s[16:17]
	global_load_lds_dwordx4 v239, s[18:19]
	s_mov_b64 exec, -1
	v_add_u32_e32 v239, 0x80, v239
	s_barrier
; template <bool SWAP>
; DI void gemm_mainloop(f32x16 (&acc)[4][2], const u16* __restrict__ A, int lda, int rlo, int rhi,
;                       const u16* __restrict__ B, int ldb, int K, char* lds, const u16* zero_line) {
;     ...
;   auto glds = [&](int kt, int st) {
;     char* as_ = lds + st * 65536 + tid * 16;
; #pragma unroll
;     for (int i = 0; i < 4; ++i) {
;       const int rr = lr + 64 * i;
;       const u16* srca = (rr >= rlo && rr < rhi) ? (ap + (ptrdiff_t)(64 * i) * lda + kt * 64) : (zero_line + lc * 8);
;       __builtin_amdgcn_global_load_lds((const unsigned*)srca, (lds_u32*)(as_ + i * 8192), 16, 0, 0);
;       __builtin_amdgcn_global_load_lds((const unsigned*)(bp + (ptrdiff_t)(64 * i) * ldb + kt * 64), (lds_u32*)(as_ + 32768 + i * 8192), 16, 0, 0);
;     }
;   };
;     ...
;   for (int kt = 0; kt < nk; ++kt) {
;     const char* st = lds + (kt & 1) * 65536;
;     ldfrag(st, 0, 0);
;     mma(1);
;     pat_rd();
;     if (kt + 1 < nk) glds(kt + 1, (kt + 1) & 1);
;     ldfrag(st, 1, 1);
;     mma(0);
;     pat_rd();
;     ldfrag(st, 2, 0);
;     mma(1);
;     pat_rd();
;     ldfrag(st, 3, 1);
;     mma(0);
;     pat_rd();
;     asm volatile("s_waitcnt vmcnt(0)" ::: "memory");
;     __syncthreads();
	s_waitcnt lgkmcnt(0)
	s_setprio 1
	v_mfma_f32_32x32x16_bf16 v[114:129], v[176:179], v[130:133], v[114:129]
	v_mfma_f32_32x32x16_bf16 v[82:97], v[176:179], v[146:149], v[82:97]
	v_mfma_f32_32x32x16_bf16 v[114:129], v[180:183], v[134:137], v[114:129]
	v_mfma_f32_32x32x16_bf16 v[82:97], v[180:183], v[150:153], v[82:97]
	v_mfma_f32_32x32x16_bf16 v[114:129], v[186:189], v[138:141], v[114:129]
	v_mfma_f32_32x32x16_bf16 v[82:97], v[186:189], v[158:161], v[82:97]
	v_mfma_f32_32x32x16_bf16 v[114:129], v[190:193], v[142:145], v[114:129]
	v_mfma_f32_32x32x16_bf16 v[82:97], v[190:193], v[162:165], v[82:97]
	s_setprio 0
	s_barrier
	v_add3_u32 v166, v249, v244, s21
	v_add3_u32 v167, v249, v245, s21
	v_add3_u32 v175, v249, v246, s21
	v_add3_u32 v185, v249, v247, s21
	ds_read_b128 v[194:197], v166 offset:49152
	ds_read_b128 v[198:201], v167 offset:49152
	ds_read_b128 v[228:231], v175 offset:49152
	ds_read_b128 v[232:235], v185 offset:49152
	s_add_u32 m0, s100, 0x18000
	s_nop 0
	global_load_lds_dwordx4 v240, s[22:23]
	v_add_u32_e32 v240, 0x80, v240
	s_add_u32 m0, s100, 0x1a000
	s_nop 0
	global_load_lds_dwordx4 v242, s[22:23]
	v_add_u32_e32 v242, 0x80, v242
	s_barrier
	s_waitcnt lgkmcnt(0)
	s_setprio 1
	v_mfma_f32_32x32x16_bf16 v[98:113], v[194:197], v[130:133], v[98:113]
	v_mfma_f32_32x32x16_bf16 v[66:81], v[194:197], v[146:149], v[66:81]
	v_mfma_f32_32x32x16_bf16 v[98:113], v[198:201], v[134:137], v[98:113]
	v_mfma_f32_32x32x16_bf16 v[66:81], v[198:201], v[150:153], v[66:81]
	v_mfma_f32_32x32x16_bf16 v[98:113], v[228:231], v[138:141], v[98:113]
	v_mfma_f32_32x32x16_bf16 v[66:81], v[228:231], v[158:161], v[66:81]
	v_mfma_f32_32x32x16_bf16 v[98:113], v[232:235], v[142:145], v[98:113]
	v_mfma_f32_32x32x16_bf16 v[66:81], v[232:235], v[162:165], v[66:81]
	s_setprio 0
	s_barrier
	v_add3_u32 v166, v248, v244, s21
	v_add3_u32 v167, v248, v245, s21
	v_add3_u32 v175, v248, v246, s21
	v_add3_u32 v185, v248, v247, s21
	ds_read_b128 v[130:133], v166 offset:16384
	ds_read_b128 v[134:137], v167 offset:16384
	ds_read_b128 v[138:141], v175 offset:16384
	ds_read_b128 v[142:145], v185 offset:16384
	ds_read_b128 v[146:149], v166 offset:20480
	ds_read_b128 v[150:153], v167 offset:20480
	ds_read_b128 v[158:161], v175 offset:20480
	ds_read_b128 v[162:165], v185 offset:20480
	s_add_u32 m0, s100, 0x10000
	s_mov_b64 exec, s[10:11]
	global_load_lds_dwordx4 v236, s[18:19]
	s_mov_b64 exec, -1
	v_add_u32_e32 v236, 0x80, v236
	s_add_u32 m0, s100, 0x12000
	s_mov_b64 exec, s[14:15]
	global_load_lds_dwordx4 v238, s[18:19]
	s_mov_b64 exec, -1
	v_add_u32_e32 v238, 0x80, v238
	s_waitcnt vmcnt(10)
	s_barrier
	s_waitcnt lgkmcnt(0)
	s_setprio 1
	v_mfma_f32_32x32x16_bf16 v[50:65], v[176:179], v[130:133], v[50:65]
	v_mfma_f32_32x32x16_bf16 v[18:33], v[176:179], v[146:149], v[18:33]
	v_mfma_f32_32x32x16_bf16 v[50:65], v[180:183], v[134:137], v[50:65]
	v_mfma_f32_32x32x16_bf16 v[18:33], v[180:183], v[150:153], v[18:33]
	v_mfma_f32_32x32x16_bf16 v[50:65], v[186:189], v[138:141], v[50:65]
	v_mfma_f32_32x32x16_bf16 v[18:33], v[186:189], v[158:161], v[18:33]
	v_mfma_f32_32x32x16_bf16 v[50:65], v[190:193], v[142:145], v[50:65]
	v_mfma_f32_32x32x16_bf16 v[18:33], v[190:193], v[162:165], v[18:33]
	s_setprio 0
	s_barrier
	v_add3_u32 v166, v249, v244, 0
	v_add3_u32 v167, v249, v245, 0
	v_add3_u32 v175, v249, v246, 0
	v_add3_u32 v185, v249, v247, 0
	ds_read_b128 v[176:179], v166 offset:32768
	ds_read_b128 v[180:183], v167 offset:32768
	ds_read_b128 v[186:189], v175 offset:32768
	ds_read_b128 v[190:193], v185 offset:32768
	s_add_u32 m0, s100, 0x1c000
	s_nop 0
	global_load_lds_dwordx4 v241, s[22:23]
	v_add_u32_e32 v241, 0x80, v241
	s_add_u32 m0, s100, 0x1e000
	s_nop 0
	global_load_lds_dwordx4 v243, s[22:23]
	v_add_u32_e32 v243, 0x80, v243
	s_waitcnt vmcnt(6)
	s_barrier
	s_waitcnt lgkmcnt(0)
	s_setprio 1
	v_mfma_f32_32x32x16_bf16 v[34:49], v[194:197], v[130:133], v[34:49]
	v_mfma_f32_32x32x16_bf16 v[2:17], v[194:197], v[146:149], v[2:17]
	v_mfma_f32_32x32x16_bf16 v[34:49], v[198:201], v[134:137], v[34:49]
	v_mfma_f32_32x32x16_bf16 v[2:17], v[198:201], v[150:153], v[2:17]
	v_mfma_f32_32x32x16_bf16 v[34:49], v[228:231], v[138:141], v[34:49]
	v_mfma_f32_32x32x16_bf16 v[2:17], v[228:231], v[158:161], v[2:17]
	v_mfma_f32_32x32x16_bf16 v[34:49], v[232:235], v[142:145], v[34:49]
	v_mfma_f32_32x32x16_bf16 v[2:17], v[232:235], v[162:165], v[2:17]
	s_setprio 0
	s_barrier
	s_add_i32 s29, s29, 2
	s_cmp_lt_u32 s29, 14
	s_cbranch_scc1 .Lg8_u0m
	v_add3_u32 v166, v248, v244, 0
	v_add3_u32 v167, v248, v245, 0
	v_add3_u32 v175, v248, v246, 0
	v_add3_u32 v185, v248, v247, 0
	ds_read_b128 v[130:133], v166
	ds_read_b128 v[134:137], v167
	ds_read_b128 v[138:141], v175
	ds_read_b128 v[142:145], v185
	ds_read_b128 v[146:149], v166 offset:4096
	ds_read_b128 v[150:153], v167 offset:4096
	ds_read_b128 v[158:161], v175 offset:4096
	ds_read_b128 v[162:165], v185 offset:4096
	s_add_u32 m0, s100, 0x14000
	s_mov_b64 exec, s[12:13]
	global_load_lds_dwordx4 v237, s[18:19]
	s_mov_b64 exec, -1
	v_add_u32_e32 v237, 0x80, v237
	s_add_u32 m0, s100, 0x16000
	s_mov_b64 exec, s[16:17]
	global_load_lds_dwordx4 v239, s[18:19]
	s_mov_b64 exec, -1
	v_add_u32_e32 v239, 0x80, v239
	s_barrier
	s_waitcnt lgkmcnt(0)
	v_mfma_f32_32x32x16_bf16 v[114:129], v[176:179], v[130:133], v[114:129]
	v_mfma_f32_32x32x16_bf16 v[82:97], v[176:179], v[146:149], v[82:97]
	v_mfma_f32_32x32x16_bf16 v[114:129], v[180:183], v[134:137], v[114:129]
	v_mfma_f32_32x32x16_bf16 v[82:97], v[180:183], v[150:153], v[82:97]
	v_mfma_f32_32x32x16_bf16 v[114:129], v[186:189], v[138:141], v[114:129]
	v_mfma_f32_32x32x16_bf16 v[82:97], v[186:189], v[158:161], v[82:97]
	v_mfma_f32_32x32x16_bf16 v[114:129], v[190:193], v[142:145], v[114:129]
	v_mfma_f32_32x32x16_bf16 v[82:97], v[190:193], v[162:165], v[82:97]
	s_barrier
; template <bool SWAP>
; DI void gemm_mainloop(f32x16 (&acc)[4][2], const u16* __restrict__ A, int lda, int rlo, int rhi,
;                       const u16* __restrict__ B, int ldb, int K, char* lds, const u16* zero_line) {
;     ...
;   for (int kt = 0; kt < nk; ++kt) {
;     const char* st = lds + (kt & 1) * 65536;
;     ldfrag(st, 0, 0);
;     mma(1);
;     pat_rd();
;     if (kt + 1 < nk) glds(kt + 1, (kt + 1) & 1);
;     ldfrag(st, 1, 1);
;     mma(0);
;     pat_rd();
;     ldfrag(st, 2, 0);
;     mma(1);
;     pat_rd();
;     ldfrag(st, 3, 1);
;     mma(0);
;     pat_rd();
;     asm volatile("s_waitcnt vmcnt(0)" ::: "memory");
;     __syncthreads();
;   }
;   mma(1);
	v_add3_u32 v166, v249, v244, 0
	v_add3_u32 v167, v249, v245, 0
	v_add3_u32 v175, v249, v246, 0
	v_add3_u32 v185, v249, v247, 0
	ds_read_b128 v[194:197], v166 offset:49152
	ds_read_b128 v[198:201], v167 offset:49152
	ds_read_b128 v[228:231], v175 offset:49152
	ds_read_b128 v[232:235], v185 offset:49152
	s_barrier
	s_waitcnt lgkmcnt(0)
	v_mfma_f32_32x32x16_bf16 v[98:113], v[194:197], v[130:133], v[98:113]
	v_mfma_f32_32x32x16_bf16 v[66:81], v[194:197], v[146:149], v[66:81]
	v_mfma_f32_32x32x16_bf16 v[98:113], v[198:201], v[134:137], v[98:113]
	v_mfma_f32_32x32x16_bf16 v[66:81], v[198:201], v[150:153], v[66:81]
	v_mfma_f32_32x32x16_bf16 v[98:113], v[228:231], v[138:141], v[98:113]
	v_mfma_f32_32x32x16_bf16 v[66:81], v[228:231], v[158:161], v[66:81]
	v_mfma_f32_32x32x16_bf16 v[98:113], v[232:235], v[142:145], v[98:113]
	v_mfma_f32_32x32x16_bf16 v[66:81], v[232:235], v[162:165], v[66:81]
	s_barrier
	v_add3_u32 v166, v248, v244, 0
	v_add3_u32 v167, v248, v245, 0
	v_add3_u32 v175, v248, v246, 0
	v_add3_u32 v185, v248, v247, 0
	ds_read_b128 v[130:133], v166 offset:16384
	ds_read_b128 v[134:137], v167 offset:16384
	ds_read_b128 v[138:141], v175 offset:16384
	ds_read_b128 v[142:145], v185 offset:16384
	ds_read_b128 v[146:149], v166 offset:20480
	ds_read_b128 v[150:153], v167 offset:20480
	ds_read_b128 v[158:161], v175 offset:20480
	ds_read_b128 v[162:165], v185 offset:20480
	s_waitcnt vmcnt(4)
	s_barrier
	s_waitcnt lgkmcnt(0)
	v_mfma_f32_32x32x16_bf16 v[50:65], v[176:179], v[130:133], v[50:65]
	v_mfma_f32_32x32x16_bf16 v[18:33], v[176:179], v[146:149], v[18:33]
	v_mfma_f32_32x32x16_bf16 v[50:65], v[180:183], v[134:137], v[50:65]
	v_mfma_f32_32x32x16_bf16 v[18:33], v[180:183], v[150:153], v[18:33]
	v_mfma_f32_32x32x16_bf16 v[50:65], v[186:189], v[138:141], v[50:65]
	v_mfma_f32_32x32x16_bf16 v[18:33], v[186:189], v[158:161], v[18:33]
	v_mfma_f32_32x32x16_bf16 v[50:65], v[190:193], v[142:145], v[50:65]
	v_mfma_f32_32x32x16_bf16 v[18:33], v[190:193], v[162:165], v[18:33]
	v_mfma_f32_32x32x16_bf16 v[34:49], v[194:197], v[130:133], v[34:49]
	v_mfma_f32_32x32x16_bf16 v[2:17], v[194:197], v[146:149], v[2:17]
	v_mfma_f32_32x32x16_bf16 v[34:49], v[198:201], v[134:137], v[34:49]
	v_mfma_f32_32x32x16_bf16 v[2:17], v[198:201], v[150:153], v[2:17]
	v_mfma_f32_32x32x16_bf16 v[34:49], v[228:231], v[138:141], v[34:49]
	v_mfma_f32_32x32x16_bf16 v[2:17], v[228:231], v[158:161], v[2:17]
	v_mfma_f32_32x32x16_bf16 v[34:49], v[232:235], v[142:145], v[34:49]
	v_mfma_f32_32x32x16_bf16 v[2:17], v[232:235], v[162:165], v[2:17]
	s_barrier
	v_add3_u32 v166, v249, v244, s21
	v_add3_u32 v167, v249, v245, s21
	v_add3_u32 v175, v249, v246, s21
	v_add3_u32 v185, v249, v247, s21
	ds_read_b128 v[176:179], v166 offset:32768
	ds_read_b128 v[180:183], v167 offset:32768
	ds_read_b128 v[186:189], v175 offset:32768
	ds_read_b128 v[190:193], v185 offset:32768
	v_add3_u32 v166, v248, v244, s21
	v_add3_u32 v167, v248, v245, s21
	v_add3_u32 v175, v248, v246, s21
	v_add3_u32 v185, v248, v247, s21
	ds_read_b128 v[130:133], v166
	ds_read_b128 v[134:137], v167
	ds_read_b128 v[138:141], v175
	ds_read_b128 v[142:145], v185
	ds_read_b128 v[146:149], v166 offset:4096
	ds_read_b128 v[150:153], v167 offset:4096
	ds_read_b128 v[158:161], v175 offset:4096
	ds_read_b128 v[162:165], v185 offset:4096
	s_waitcnt vmcnt(2)
	s_barrier
	s_waitcnt lgkmcnt(0)
	v_mfma_f32_32x32x16_bf16 v[114:129], v[176:179], v[130:133], v[114:129]
	v_mfma_f32_32x32x16_bf16 v[82:97], v[176:179], v[146:149], v[82:97]
	v_mfma_f32_32x32x16_bf16 v[114:129], v[180:183], v[134:137], v[114:129]
	v_mfma_f32_32x32x16_bf16 v[82:97], v[180:183], v[150:153], v[82:97]
	v_mfma_f32_32x32x16_bf16 v[114:129], v[186:189], v[138:141], v[114:129]
	v_mfma_f32_32x32x16_bf16 v[82:97], v[186:189], v[158:161], v[82:97]
	v_mfma_f32_32x32x16_bf16 v[114:129], v[190:193], v[142:145], v[114:129]
	v_mfma_f32_32x32x16_bf16 v[82:97], v[190:193], v[162:165], v[82:97]
	s_barrier
	v_add3_u32 v166, v249, v244, s21
	v_add3_u32 v167, v249, v245, s21
	v_add3_u32 v175, v249, v246, s21
	v_add3_u32 v185, v249, v247, s21
	ds_read_b128 v[194:197], v166 offset:49152
	ds_read_b128 v[198:201], v167 offset:49152
	ds_read_b128 v[228:231], v175 offset:49152
	ds_read_b128 v[232:235], v185 offset:49152
	s_waitcnt vmcnt(0)
	s_barrier
	s_waitcnt lgkmcnt(0)
	v_mfma_f32_32x32x16_bf16 v[98:113], v[194:197], v[130:133], v[98:113]
	v_mfma_f32_32x32x16_bf16 v[66:81], v[194:197], v[146:149], v[66:81]
	v_mfma_f32_32x32x16_bf16 v[98:113], v[198:201], v[134:137], v[98:113]
	v_mfma_f32_32x32x16_bf16 v[66:81], v[198:201], v[150:153], v[66:81]
	v_mfma_f32_32x32x16_bf16 v[98:113], v[228:231], v[138:141], v[98:113]
	v_mfma_f32_32x32x16_bf16 v[66:81], v[228:231], v[158:161], v[66:81]
	v_mfma_f32_32x32x16_bf16 v[98:113], v[232:235], v[142:145], v[98:113]
	v_mfma_f32_32x32x16_bf16 v[66:81], v[232:235], v[162:165], v[66:81]
	s_barrier
	v_add3_u32 v166, v248, v244, s21
	v_add3_u32 v167, v248, v245, s21
	v_add3_u32 v175, v248, v246, s21
	v_add3_u32 v185, v248, v247, s21
	ds_read_b128 v[130:133], v166 offset:16384
	ds_read_b128 v[134:137], v167 offset:16384
	ds_read_b128 v[138:141], v175 offset:16384
	ds_read_b128 v[142:145], v185 offset:16384
	ds_read_b128 v[146:149], v166 offset:20480
	ds_read_b128 v[150:153], v167 offset:20480
	ds_read_b128 v[158:161], v175 offset:20480
	ds_read_b128 v[162:165], v185 offset:20480
	s_barrier
	s_waitcnt lgkmcnt(0)
	v_mfma_f32_32x32x16_bf16 v[50:65], v[176:179], v[130:133], v[50:65]
	v_mfma_f32_32x32x16_bf16 v[18:33], v[176:179], v[146:149], v[18:33]
	v_mfma_f32_32x32x16_bf16 v[50:65], v[180:183], v[134:137], v[50:65]
	v_mfma_f32_32x32x16_bf16 v[18:33], v[180:183], v[150:153], v[18:33]
	v_mfma_f32_32x32x16_bf16 v[50:65], v[186:189], v[138:141], v[50:65]
	v_mfma_f32_32x32x16_bf16 v[18:33], v[186:189], v[158:161], v[18:33]
	v_mfma_f32_32x32x16_bf16 v[50:65], v[190:193], v[142:145], v[50:65]
	v_mfma_f32_32x32x16_bf16 v[18:33], v[190:193], v[162:165], v[18:33]
	v_mfma_f32_32x32x16_bf16 v[34:49], v[194:197], v[130:133], v[34:49]
	v_mfma_f32_32x32x16_bf16 v[2:17], v[194:197], v[146:149], v[2:17]
	v_mfma_f32_32x32x16_bf16 v[34:49], v[198:201], v[134:137], v[34:49]
	v_mfma_f32_32x32x16_bf16 v[2:17], v[198:201], v[150:153], v[2:17]
	v_mfma_f32_32x32x16_bf16 v[34:49], v[228:231], v[138:141], v[34:49]
	v_mfma_f32_32x32x16_bf16 v[2:17], v[228:231], v[158:161], v[2:17]
	v_mfma_f32_32x32x16_bf16 v[34:49], v[232:235], v[142:145], v[34:49]
	v_mfma_f32_32x32x16_bf16 v[2:17], v[232:235], v[162:165], v[2:17]
	s_barrier
	s_cmp_eq_u32 s101, 0
	s_cbranch_scc0 .Lg8_u0m_p1
	s_barrier

; template <bool SWAP>
; DI void gemm_mainloop(f32x16 (&acc)[4][2], const u16* __restrict__ A, int lda, int rlo, int rhi,
;                       const u16* __restrict__ B, int ldb, int K, char* lds, const u16* zero_line) {
;     ...
;   for (int kt = 0; kt < nk; ++kt) {
;     const char* st = lds + (kt & 1) * 65536;
;     ldfrag(st, 0, 0);
;     mma(1);
;     pat_rd();
;     if (kt + 1 < nk) glds(kt + 1, (kt + 1) & 1);
;     ldfrag(st, 1, 1);
;     mma(0);
;     pat_rd();
;     ldfrag(st, 2, 0);
;     mma(1);
;     pat_rd();
;     ldfrag(st, 3, 1);
;     mma(0);
;     pat_rd();
;     asm volatile("s_waitcnt vmcnt(0)" ::: "memory");
;     __syncthreads();
.Lg8_qa:
	v_add3_u32 v246, v244, v240, 0
	v_add3_u32 v247, v244, v241, 0
	v_add3_u32 v248, v244, v242, 0
	v_add3_u32 v249, v244, v243, 0
	ds_read_b128 v[130:133], v246
	ds_read_b128 v[134:137], v247
	ds_read_b128 v[138:141], v248
	ds_read_b128 v[142:145], v249
	ds_read_b128 v[146:149], v246 offset:4096
	ds_read_b128 v[150:153], v247 offset:4096
	ds_read_b128 v[156:159], v248 offset:4096
	ds_read_b128 v[160:163], v249 offset:4096
	s_add_u32 m0, s100, 0x14000
	s_nop 0
	global_load_lds_dwordx4 v233, s[6:7]
	v_add_u32_e32 v233, 0x80, v233
	s_add_u32 m0, s100, 0x16000
	s_nop 0
	global_load_lds_dwordx4 v235, s[6:7]
	v_add_u32_e32 v235, 0x80, v235
	s_barrier
	s_waitcnt lgkmcnt(0)
	s_setprio 1
	v_mfma_f32_32x32x16_bf16 v[114:129], v[130:133], v[170:173], v[114:129]
	v_mfma_f32_32x32x16_bf16 v[82:97], v[146:149], v[170:173], v[82:97]
	v_mfma_f32_32x32x16_bf16 v[114:129], v[134:137], v[174:177], v[114:129]
	v_mfma_f32_32x32x16_bf16 v[82:97], v[150:153], v[174:177], v[82:97]
	v_mfma_f32_32x32x16_bf16 v[114:129], v[138:141], v[178:181], v[114:129]
	v_mfma_f32_32x32x16_bf16 v[82:97], v[156:159], v[178:181], v[82:97]
	v_mfma_f32_32x32x16_bf16 v[114:129], v[142:145], v[186:189], v[114:129]
	v_mfma_f32_32x32x16_bf16 v[82:97], v[160:163], v[186:189], v[82:97]
	s_setprio 0
	s_barrier
	v_add3_u32 v246, v245, v240, 0
	v_add3_u32 v247, v245, v241, 0
	v_add3_u32 v248, v245, v242, 0
	v_add3_u32 v249, v245, v243, 0
	ds_read_b128 v[190:193], v246 offset:49152
	ds_read_b128 v[194:197], v247 offset:49152
	ds_read_b128 v[198:201], v248 offset:49152
	ds_read_b128 v[228:231], v249 offset:49152
	s_add_u32 m0, s100, 0x8000
	s_nop 0
	global_load_lds_dwordx4 v236, s[8:9]
	v_add_u32_e32 v236, 0x80, v236
	s_add_u32 m0, s100, 0xa000
	s_nop 0
	global_load_lds_dwordx4 v238, s[8:9]
	v_add_u32_e32 v238, 0x80, v238
	s_barrier
	s_waitcnt lgkmcnt(0)
	s_setprio 1
	v_mfma_f32_32x32x16_bf16 v[98:113], v[130:133], v[190:193], v[98:113]
	v_mfma_f32_32x32x16_bf16 v[66:81], v[146:149], v[190:193], v[66:81]
	v_mfma_f32_32x32x16_bf16 v[98:113], v[134:137], v[194:197], v[98:113]
	v_mfma_f32_32x32x16_bf16 v[66:81], v[150:153], v[194:197], v[66:81]
	v_mfma_f32_32x32x16_bf16 v[98:113], v[138:141], v[198:201], v[98:113]
	v_mfma_f32_32x32x16_bf16 v[66:81], v[156:159], v[198:201], v[66:81]
	v_mfma_f32_32x32x16_bf16 v[98:113], v[142:145], v[228:231], v[98:113]
	v_mfma_f32_32x32x16_bf16 v[66:81], v[160:163], v[228:231], v[66:81]
	s_setprio 0
	s_barrier
	v_add3_u32 v246, v244, v240, 0
	v_add3_u32 v247, v244, v241, 0
	v_add3_u32 v248, v244, v242, 0
	v_add3_u32 v249, v244, v243, 0
	ds_read_b128 v[130:133], v246 offset:16384
	ds_read_b128 v[134:137], v247 offset:16384
	ds_read_b128 v[138:141], v248 offset:16384
	ds_read_b128 v[142:145], v249 offset:16384
	ds_read_b128 v[146:149], v246 offset:20480
	ds_read_b128 v[150:153], v247 offset:20480
	ds_read_b128 v[156:159], v248 offset:20480
	ds_read_b128 v[160:163], v249 offset:20480
	s_add_u32 m0, s100, 0x0
	s_nop 0
	global_load_lds_dwordx4 v232, s[6:7]
	v_add_u32_e32 v232, 0x80, v232
	s_add_u32 m0, s100, 0x2000
	s_nop 0
	global_load_lds_dwordx4 v234, s[6:7]
	v_add_u32_e32 v234, 0x80, v234
	s_waitcnt vmcnt(10)
	s_barrier
	s_waitcnt lgkmcnt(0)
	s_setprio 1
	v_mfma_f32_32x32x16_bf16 v[50:65], v[130:133], v[170:173], v[50:65]
	v_mfma_f32_32x32x16_bf16 v[18:33], v[146:149], v[170:173], v[18:33]
	v_mfma_f32_32x32x16_bf16 v[50:65], v[134:137], v[174:177], v[50:65]
	v_mfma_f32_32x32x16_bf16 v[18:33], v[150:153], v[174:177], v[18:33]
	v_mfma_f32_32x32x16_bf16 v[50:65], v[138:141], v[178:181], v[50:65]
	v_mfma_f32_32x32x16_bf16 v[18:33], v[156:159], v[178:181], v[18:33]
	v_mfma_f32_32x32x16_bf16 v[50:65], v[142:145], v[186:189], v[50:65]
	v_mfma_f32_32x32x16_bf16 v[18:33], v[160:163], v[186:189], v[18:33]
	s_setprio 0
	s_barrier
	v_add3_u32 v246, v245, v240, s10
	v_add3_u32 v247, v245, v241, s10
	v_add3_u32 v248, v245, v242, s10
	v_add3_u32 v249, v245, v243, s10
	ds_read_b128 v[170:173], v246 offset:32768
	ds_read_b128 v[174:177], v247 offset:32768
	ds_read_b128 v[178:181], v248 offset:32768
	ds_read_b128 v[186:189], v249 offset:32768
	s_add_u32 m0, s100, 0xc000
	s_nop 0
	global_load_lds_dwordx4 v237, s[8:9]
	v_add_u32_e32 v237, 0x80, v237
	s_add_u32 m0, s100, 0xe000
	s_nop 0
	global_load_lds_dwordx4 v239, s[8:9]
	v_add_u32_e32 v239, 0x80, v239
	s_waitcnt vmcnt(6)
	s_barrier
	s_waitcnt lgkmcnt(0)
	s_setprio 1
	v_mfma_f32_32x32x16_bf16 v[34:49], v[130:133], v[190:193], v[34:49]
	v_mfma_f32_32x32x16_bf16 v[2:17], v[146:149], v[190:193], v[2:17]
	v_mfma_f32_32x32x16_bf16 v[34:49], v[134:137], v[194:197], v[34:49]
	v_mfma_f32_32x32x16_bf16 v[2:17], v[150:153], v[194:197], v[2:17]
	v_mfma_f32_32x32x16_bf16 v[34:49], v[138:141], v[198:201], v[34:49]
	v_mfma_f32_32x32x16_bf16 v[2:17], v[156:159], v[198:201], v[2:17]
	v_mfma_f32_32x32x16_bf16 v[34:49], v[142:145], v[228:231], v[34:49]
	v_mfma_f32_32x32x16_bf16 v[2:17], v[160:163], v[228:231], v[2:17]
	s_setprio 0
	s_barrier
	v_add3_u32 v246, v244, v240, s10
	v_add3_u32 v247, v244, v241, s10
	v_add3_u32 v248, v244, v242, s10
	v_add3_u32 v249, v244, v243, s10
	ds_read_b128 v[130:133], v246
	ds_read_b128 v[134:137], v247
	ds_read_b128 v[138:141], v248
	ds_read_b128 v[142:145], v249
	ds_read_b128 v[146:149], v246 offset:4096
	ds_read_b128 v[150:153], v247 offset:4096
	ds_read_b128 v[156:159], v248 offset:4096
	ds_read_b128 v[160:163], v249 offset:4096
	s_add_u32 m0, s100, 0x4000
	s_nop 0
	global_load_lds_dwordx4 v233, s[6:7]
	v_add_u32_e32 v233, 0x80, v233
	s_add_u32 m0, s100, 0x6000
	s_nop 0
	global_load_lds_dwordx4 v235, s[6:7]
	v_add_u32_e32 v235, 0x80, v235
	s_barrier
; template <bool SWAP>
; DI void gemm_mainloop(f32x16 (&acc)[4][2], const u16* __restrict__ A, int lda, int rlo, int rhi,
;                       const u16* __restrict__ B, int ldb, int K, char* lds, const u16* zero_line) {
;     ...
;   for (int kt = 0; kt < nk; ++kt) {
;     const char* st = lds + (kt & 1) * 65536;
;     ldfrag(st, 0, 0);
;     mma(1);
;     pat_rd();
;     if (kt + 1 < nk) glds(kt + 1, (kt + 1) & 1);
;     ldfrag(st, 1, 1);
;     mma(0);
;     pat_rd();
;     ldfrag(st, 2, 0);
;     mma(1);
;     pat_rd();
;     ldfrag(st, 3, 1);
;     mma(0);
;     pat_rd();
;     asm volatile("s_waitcnt vmcnt(0)" ::: "memory");
;     __syncthreads();
	s_waitcnt lgkmcnt(0)
	s_setprio 1
	v_mfma_f32_32x32x16_bf16 v[114:129], v[130:133], v[170:173], v[114:129]
	v_mfma_f32_32x32x16_bf16 v[82:97], v[146:149], v[170:173], v[82:97]
	v_mfma_f32_32x32x16_bf16 v[114:129], v[134:137], v[174:177], v[114:129]
	v_mfma_f32_32x32x16_bf16 v[82:97], v[150:153], v[174:177], v[82:97]
	v_mfma_f32_32x32x16_bf16 v[114:129], v[138:141], v[178:181], v[114:129]
	v_mfma_f32_32x32x16_bf16 v[82:97], v[156:159], v[178:181], v[82:97]
	v_mfma_f32_32x32x16_bf16 v[114:129], v[142:145], v[186:189], v[114:129]
	v_mfma_f32_32x32x16_bf16 v[82:97], v[160:163], v[186:189], v[82:97]
	s_setprio 0
	s_barrier
	v_add3_u32 v246, v245, v240, s10
	v_add3_u32 v247, v245, v241, s10
	v_add3_u32 v248, v245, v242, s10
	v_add3_u32 v249, v245, v243, s10
	ds_read_b128 v[190:193], v246 offset:49152
	ds_read_b128 v[194:197], v247 offset:49152
	ds_read_b128 v[198:201], v248 offset:49152
	ds_read_b128 v[228:231], v249 offset:49152
	s_add_u32 m0, s100, 0x18000
	s_nop 0
	global_load_lds_dwordx4 v236, s[8:9]
	v_add_u32_e32 v236, 0x80, v236
	s_add_u32 m0, s100, 0x1a000
	s_nop 0
	global_load_lds_dwordx4 v238, s[8:9]
	v_add_u32_e32 v238, 0x80, v238
	s_barrier
	s_waitcnt lgkmcnt(0)
	s_setprio 1
	v_mfma_f32_32x32x16_bf16 v[98:113], v[130:133], v[190:193], v[98:113]
	v_mfma_f32_32x32x16_bf16 v[66:81], v[146:149], v[190:193], v[66:81]
	v_mfma_f32_32x32x16_bf16 v[98:113], v[134:137], v[194:197], v[98:113]
	v_mfma_f32_32x32x16_bf16 v[66:81], v[150:153], v[194:197], v[66:81]
	v_mfma_f32_32x32x16_bf16 v[98:113], v[138:141], v[198:201], v[98:113]
	v_mfma_f32_32x32x16_bf16 v[66:81], v[156:159], v[198:201], v[66:81]
	v_mfma_f32_32x32x16_bf16 v[98:113], v[142:145], v[228:231], v[98:113]
	v_mfma_f32_32x32x16_bf16 v[66:81], v[160:163], v[228:231], v[66:81]
	s_setprio 0
	s_barrier
	v_add3_u32 v246, v244, v240, s10
	v_add3_u32 v247, v244, v241, s10
	v_add3_u32 v248, v244, v242, s10
	v_add3_u32 v249, v244, v243, s10
	ds_read_b128 v[130:133], v246 offset:16384
	ds_read_b128 v[134:137], v247 offset:16384
	ds_read_b128 v[138:141], v248 offset:16384
	ds_read_b128 v[142:145], v249 offset:16384
	ds_read_b128 v[146:149], v246 offset:20480
	ds_read_b128 v[150:153], v247 offset:20480
	ds_read_b128 v[156:159], v248 offset:20480
	ds_read_b128 v[160:163], v249 offset:20480
	s_add_u32 m0, s100, 0x10000
	s_nop 0
	global_load_lds_dwordx4 v232, s[6:7]
	v_add_u32_e32 v232, 0x80, v232
	s_add_u32 m0, s100, 0x12000
	s_nop 0
	global_load_lds_dwordx4 v234, s[6:7]
	v_add_u32_e32 v234, 0x80, v234
	s_waitcnt vmcnt(10)
	s_barrier
	s_waitcnt lgkmcnt(0)
	s_setprio 1
	v_mfma_f32_32x32x16_bf16 v[50:65], v[130:133], v[170:173], v[50:65]
	v_mfma_f32_32x32x16_bf16 v[18:33], v[146:149], v[170:173], v[18:33]
	v_mfma_f32_32x32x16_bf16 v[50:65], v[134:137], v[174:177], v[50:65]
	v_mfma_f32_32x32x16_bf16 v[18:33], v[150:153], v[174:177], v[18:33]
	v_mfma_f32_32x32x16_bf16 v[50:65], v[138:141], v[178:181], v[50:65]
	v_mfma_f32_32x32x16_bf16 v[18:33], v[156:159], v[178:181], v[18:33]
	v_mfma_f32_32x32x16_bf16 v[50:65], v[142:145], v[186:189], v[50:65]
	v_mfma_f32_32x32x16_bf16 v[18:33], v[160:163], v[186:189], v[18:33]
	s_setprio 0
	s_barrier
	v_add3_u32 v246, v245, v240, 0
	v_add3_u32 v247, v245, v241, 0
	v_add3_u32 v248, v245, v242, 0
	v_add3_u32 v249, v245, v243, 0
	ds_read_b128 v[170:173], v246 offset:32768
	ds_read_b128 v[174:177], v247 offset:32768
	ds_read_b128 v[178:181], v248 offset:32768
	ds_read_b128 v[186:189], v249 offset:32768
	s_add_u32 m0, s100, 0x1c000
	s_nop 0
	global_load_lds_dwordx4 v237, s[8:9]
	v_add_u32_e32 v237, 0x80, v237
	s_add_u32 m0, s100, 0x1e000
	s_nop 0
	global_load_lds_dwordx4 v239, s[8:9]
	v_add_u32_e32 v239, 0x80, v239
	s_waitcnt vmcnt(6)
	s_barrier
	s_waitcnt lgkmcnt(0)
	s_setprio 1
	v_mfma_f32_32x32x16_bf16 v[34:49], v[130:133], v[190:193], v[34:49]
	v_mfma_f32_32x32x16_bf16 v[2:17], v[146:149], v[190:193], v[2:17]
	v_mfma_f32_32x32x16_bf16 v[34:49], v[134:137], v[194:197], v[34:49]
	v_mfma_f32_32x32x16_bf16 v[2:17], v[150:153], v[194:197], v[2:17]
	v_mfma_f32_32x32x16_bf16 v[34:49], v[138:141], v[198:201], v[34:49]
	v_mfma_f32_32x32x16_bf16 v[2:17], v[156:159], v[198:201], v[2:17]
	v_mfma_f32_32x32x16_bf16 v[34:49], v[142:145], v[228:231], v[34:49]
	v_mfma_f32_32x32x16_bf16 v[2:17], v[160:163], v[228:231], v[2:17]
	s_setprio 0
	s_barrier
	s_add_i32 s11, s11, 2
	s_cmp_lt_u32 s11, 14
	s_cbranch_scc1 .Lg8_qa
	v_add3_u32 v246, v244, v240, 0
	v_add3_u32 v247, v244, v241, 0
	v_add3_u32 v248, v244, v242, 0
	v_add3_u32 v249, v244, v243, 0
	ds_read_b128 v[130:133], v246
	ds_read_b128 v[134:137], v247
	ds_read_b128 v[138:141], v248
	ds_read_b128 v[142:145], v249
	ds_read_b128 v[146:149], v246 offset:4096
	ds_read_b128 v[150:153], v247 offset:4096
	ds_read_b128 v[156:159], v248 offset:4096
	ds_read_b128 v[160:163], v249 offset:4096
	s_add_u32 m0, s100, 0x14000
	s_nop 0
	global_load_lds_dwordx4 v233, s[6:7]
	v_add_u32_e32 v233, 0x80, v233
	s_add_u32 m0, s100, 0x16000
	s_nop 0
	global_load_lds_dwordx4 v235, s[6:7]
	v_add_u32_e32 v235, 0x80, v235
	s_barrier
	s_waitcnt lgkmcnt(0)
	v_mfma_f32_32x32x16_bf16 v[114:129], v[130:133], v[170:173], v[114:129]
	v_mfma_f32_32x32x16_bf16 v[82:97], v[146:149], v[170:173], v[82:97]
	v_mfma_f32_32x32x16_bf16 v[114:129], v[134:137], v[174:177], v[114:129]
	v_mfma_f32_32x32x16_bf16 v[82:97], v[150:153], v[174:177], v[82:97]
	v_mfma_f32_32x32x16_bf16 v[114:129], v[138:141], v[178:181], v[114:129]
	v_mfma_f32_32x32x16_bf16 v[82:97], v[156:159], v[178:181], v[82:97]
	v_mfma_f32_32x32x16_bf16 v[114:129], v[142:145], v[186:189], v[114:129]
	v_mfma_f32_32x32x16_bf16 v[82:97], v[160:163], v[186:189], v[82:97]
	s_barrier
; template <bool SWAP>
; DI void gemm_mainloop(f32x16 (&acc)[4][2], const u16* __restrict__ A, int lda, int rlo, int rhi,
;                       const u16* __restrict__ B, int ldb, int K, char* lds, const u16* zero_line) {
;     ...
;   for (int kt = 0; kt < nk; ++kt) {
;     const char* st = lds + (kt & 1) * 65536;
;     ldfrag(st, 0, 0);
;     mma(1);
;     pat_rd();
;     if (kt + 1 < nk) glds(kt + 1, (kt + 1) & 1);
;     ldfrag(st, 1, 1);
;     mma(0);
;     pat_rd();
;     ldfrag(st, 2, 0);
;     mma(1);
;     pat_rd();
;     ldfrag(st, 3, 1);
;     mma(0);
;     pat_rd();
;     asm volatile("s_waitcnt vmcnt(0)" ::: "memory");
;     __syncthreads();
;   }
;   mma(1);
	v_add3_u32 v246, v245, v240, 0
	v_add3_u32 v247, v245, v241, 0
	v_add3_u32 v248, v245, v242, 0
	v_add3_u32 v249, v245, v243, 0
	ds_read_b128 v[190:193], v246 offset:49152
	ds_read_b128 v[194:197], v247 offset:49152
	ds_read_b128 v[198:201], v248 offset:49152
	ds_read_b128 v[228:231], v249 offset:49152
	s_barrier
	s_waitcnt lgkmcnt(0)
	v_mfma_f32_32x32x16_bf16 v[98:113], v[130:133], v[190:193], v[98:113]
	v_mfma_f32_32x32x16_bf16 v[66:81], v[146:149], v[190:193], v[66:81]
	v_mfma_f32_32x32x16_bf16 v[98:113], v[134:137], v[194:197], v[98:113]
	v_mfma_f32_32x32x16_bf16 v[66:81], v[150:153], v[194:197], v[66:81]
	v_mfma_f32_32x32x16_bf16 v[98:113], v[138:141], v[198:201], v[98:113]
	v_mfma_f32_32x32x16_bf16 v[66:81], v[156:159], v[198:201], v[66:81]
	v_mfma_f32_32x32x16_bf16 v[98:113], v[142:145], v[228:231], v[98:113]
	v_mfma_f32_32x32x16_bf16 v[66:81], v[160:163], v[228:231], v[66:81]
	s_barrier
	v_add3_u32 v246, v244, v240, 0
	v_add3_u32 v247, v244, v241, 0
	v_add3_u32 v248, v244, v242, 0
	v_add3_u32 v249, v244, v243, 0
	ds_read_b128 v[130:133], v246 offset:16384
	ds_read_b128 v[134:137], v247 offset:16384
	ds_read_b128 v[138:141], v248 offset:16384
	ds_read_b128 v[142:145], v249 offset:16384
	ds_read_b128 v[146:149], v246 offset:20480
	ds_read_b128 v[150:153], v247 offset:20480
	ds_read_b128 v[156:159], v248 offset:20480
	ds_read_b128 v[160:163], v249 offset:20480
	s_waitcnt vmcnt(4)
	s_barrier
	s_waitcnt lgkmcnt(0)
	v_mfma_f32_32x32x16_bf16 v[50:65], v[130:133], v[170:173], v[50:65]
	v_mfma_f32_32x32x16_bf16 v[18:33], v[146:149], v[170:173], v[18:33]
	v_mfma_f32_32x32x16_bf16 v[50:65], v[134:137], v[174:177], v[50:65]
	v_mfma_f32_32x32x16_bf16 v[18:33], v[150:153], v[174:177], v[18:33]
	v_mfma_f32_32x32x16_bf16 v[50:65], v[138:141], v[178:181], v[50:65]
	v_mfma_f32_32x32x16_bf16 v[18:33], v[156:159], v[178:181], v[18:33]
	v_mfma_f32_32x32x16_bf16 v[50:65], v[142:145], v[186:189], v[50:65]
	v_mfma_f32_32x32x16_bf16 v[18:33], v[160:163], v[186:189], v[18:33]
	v_mfma_f32_32x32x16_bf16 v[34:49], v[130:133], v[190:193], v[34:49]
	v_mfma_f32_32x32x16_bf16 v[2:17], v[146:149], v[190:193], v[2:17]
	v_mfma_f32_32x32x16_bf16 v[34:49], v[134:137], v[194:197], v[34:49]
	v_mfma_f32_32x32x16_bf16 v[2:17], v[150:153], v[194:197], v[2:17]
	v_mfma_f32_32x32x16_bf16 v[34:49], v[138:141], v[198:201], v[34:49]
	v_mfma_f32_32x32x16_bf16 v[2:17], v[156:159], v[198:201], v[2:17]
	v_mfma_f32_32x32x16_bf16 v[34:49], v[142:145], v[228:231], v[34:49]
	v_mfma_f32_32x32x16_bf16 v[2:17], v[160:163], v[228:231], v[2:17]
	s_barrier
	v_add3_u32 v246, v245, v240, s10
	v_add3_u32 v247, v245, v241, s10
	v_add3_u32 v248, v245, v242, s10
	v_add3_u32 v249, v245, v243, s10
	ds_read_b128 v[170:173], v246 offset:32768
	ds_read_b128 v[174:177], v247 offset:32768
	ds_read_b128 v[178:181], v248 offset:32768
	ds_read_b128 v[186:189], v249 offset:32768
	v_add3_u32 v246, v244, v240, s10
	v_add3_u32 v247, v244, v241, s10
	v_add3_u32 v248, v244, v242, s10
	v_add3_u32 v249, v244, v243, s10
	ds_read_b128 v[130:133], v246
	ds_read_b128 v[134:137], v247
	ds_read_b128 v[138:141], v248
	ds_read_b128 v[142:145], v249
	ds_read_b128 v[146:149], v246 offset:4096
	ds_read_b128 v[150:153], v247 offset:4096
	ds_read_b128 v[156:159], v248 offset:4096
	ds_read_b128 v[160:163], v249 offset:4096
	s_waitcnt vmcnt(2)
	s_barrier
	s_waitcnt lgkmcnt(0)
	v_mfma_f32_32x32x16_bf16 v[114:129], v[130:133], v[170:173], v[114:129]
	v_mfma_f32_32x32x16_bf16 v[82:97], v[146:149], v[170:173], v[82:97]
	v_mfma_f32_32x32x16_bf16 v[114:129], v[134:137], v[174:177], v[114:129]
	v_mfma_f32_32x32x16_bf16 v[82:97], v[150:153], v[174:177], v[82:97]
	v_mfma_f32_32x32x16_bf16 v[114:129], v[138:141], v[178:181], v[114:129]
	v_mfma_f32_32x32x16_bf16 v[82:97], v[156:159], v[178:181], v[82:97]
	v_mfma_f32_32x32x16_bf16 v[114:129], v[142:145], v[186:189], v[114:129]
	v_mfma_f32_32x32x16_bf16 v[82:97], v[160:163], v[186:189], v[82:97]
	s_barrier
	v_add3_u32 v246, v245, v240, s10
	v_add3_u32 v247, v245, v241, s10
	v_add3_u32 v248, v245, v242, s10
	v_add3_u32 v249, v245, v243, s10
	ds_read_b128 v[190:193], v246 offset:49152
	ds_read_b128 v[194:197], v247 offset:49152
	ds_read_b128 v[198:201], v248 offset:49152
	ds_read_b128 v[228:231], v249 offset:49152
	s_waitcnt vmcnt(0)
	s_barrier
	s_waitcnt lgkmcnt(0)
	v_mfma_f32_32x32x16_bf16 v[98:113], v[130:133], v[190:193], v[98:113]
	v_mfma_f32_32x32x16_bf16 v[66:81], v[146:149], v[190:193], v[66:81]
	v_mfma_f32_32x32x16_bf16 v[98:113], v[134:137], v[194:197], v[98:113]
	v_mfma_f32_32x32x16_bf16 v[66:81], v[150:153], v[194:197], v[66:81]
	v_mfma_f32_32x32x16_bf16 v[98:113], v[138:141], v[198:201], v[98:113]
	v_mfma_f32_32x32x16_bf16 v[66:81], v[156:159], v[198:201], v[66:81]
	v_mfma_f32_32x32x16_bf16 v[98:113], v[142:145], v[228:231], v[98:113]
	v_mfma_f32_32x32x16_bf16 v[66:81], v[160:163], v[228:231], v[66:81]
	s_barrier
	v_add3_u32 v246, v244, v240, s10
	v_add3_u32 v247, v244, v241, s10
	v_add3_u32 v248, v244, v242, s10
	v_add3_u32 v249, v244, v243, s10
	ds_read_b128 v[130:133], v246 offset:16384
	ds_read_b128 v[134:137], v247 offset:16384
	ds_read_b128 v[138:141], v248 offset:16384
	ds_read_b128 v[142:145], v249 offset:16384
	ds_read_b128 v[146:149], v246 offset:20480
	ds_read_b128 v[150:153], v247 offset:20480
	ds_read_b128 v[156:159], v248 offset:20480
	ds_read_b128 v[160:163], v249 offset:20480
	s_barrier
	s_waitcnt lgkmcnt(0)
	v_mfma_f32_32x32x16_bf16 v[50:65], v[130:133], v[170:173], v[50:65]
	v_mfma_f32_32x32x16_bf16 v[18:33], v[146:149], v[170:173], v[18:33]
	v_mfma_f32_32x32x16_bf16 v[50:65], v[134:137], v[174:177], v[50:65]
	v_mfma_f32_32x32x16_bf16 v[18:33], v[150:153], v[174:177], v[18:33]
	v_mfma_f32_32x32x16_bf16 v[50:65], v[138:141], v[178:181], v[50:65]
	v_mfma_f32_32x32x16_bf16 v[18:33], v[156:159], v[178:181], v[18:33]
	v_mfma_f32_32x32x16_bf16 v[50:65], v[142:145], v[186:189], v[50:65]
	v_mfma_f32_32x32x16_bf16 v[18:33], v[160:163], v[186:189], v[18:33]
	v_mfma_f32_32x32x16_bf16 v[34:49], v[130:133], v[190:193], v[34:49]
	v_mfma_f32_32x32x16_bf16 v[2:17], v[146:149], v[190:193], v[2:17]
	v_mfma_f32_32x32x16_bf16 v[34:49], v[134:137], v[194:197], v[34:49]
	v_mfma_f32_32x32x16_bf16 v[2:17], v[150:153], v[194:197], v[2:17]
	v_mfma_f32_32x32x16_bf16 v[34:49], v[138:141], v[198:201], v[34:49]
	v_mfma_f32_32x32x16_bf16 v[2:17], v[156:159], v[198:201], v[2:17]
	v_mfma_f32_32x32x16_bf16 v[34:49], v[142:145], v[228:231], v[34:49]
	v_mfma_f32_32x32x16_bf16 v[2:17], v[160:163], v[228:231], v[2:17]
	s_barrier
	s_cmp_eq_u32 s101, 0
	s_cbranch_scc0 .Lg8_qa_p1
	s_barrier

; template <bool SWAP>
; DI void gemm_mainloop(f32x16 (&acc)[4][2], const u16* __restrict__ A, int lda, int rlo, int rhi,
;                       const u16* __restrict__ B, int ldb, int K, char* lds, const u16* zero_line) {
;     ...
;   for (int kt = 0; kt < nk; ++kt) {
;     const char* st = lds + (kt & 1) * 65536;
;     ldfrag(st, 0, 0);
;     mma(1);
;     pat_rd();
;     if (kt + 1 < nk) glds(kt + 1, (kt + 1) & 1);
;     ldfrag(st, 1, 1);
;     mma(0);
;     pat_rd();
;     ldfrag(st, 2, 0);
;     mma(1);
;     pat_rd();
;     ldfrag(st, 3, 1);
;     mma(0);
;     pat_rd();
;     asm volatile("s_waitcnt vmcnt(0)" ::: "memory");
;     __syncthreads();
.Lg8_qb:
	v_add3_u32 v246, v244, v240, 0
	v_add3_u32 v247, v244, v241, 0
	v_add3_u32 v248, v244, v242, 0
	v_add3_u32 v249, v244, v243, 0
	ds_read_b128 v[130:133], v246
	ds_read_b128 v[134:137], v247
	ds_read_b128 v[138:141], v248
	ds_read_b128 v[142:145], v249
	ds_read_b128 v[146:149], v246 offset:4096
	ds_read_b128 v[150:153], v247 offset:4096
	ds_read_b128 v[156:159], v248 offset:4096
	ds_read_b128 v[160:163], v249 offset:4096
	s_add_u32 m0, s100, 0x14000
	s_nop 0
	global_load_lds_dwordx4 v233, s[6:7]
	v_add_u32_e32 v233, 0x80, v233
	s_add_u32 m0, s100, 0x16000
	s_nop 0
	global_load_lds_dwordx4 v235, s[6:7]
	v_add_u32_e32 v235, 0x80, v235
	s_barrier
	s_waitcnt lgkmcnt(0)
	s_setprio 1
	v_mfma_f32_32x32x16_bf16 v[114:129], v[170:173], v[130:133], v[114:129]
	v_mfma_f32_32x32x16_bf16 v[82:97], v[170:173], v[146:149], v[82:97]
	v_mfma_f32_32x32x16_bf16 v[114:129], v[174:177], v[134:137], v[114:129]
	v_mfma_f32_32x32x16_bf16 v[82:97], v[174:177], v[150:153], v[82:97]
	v_mfma_f32_32x32x16_bf16 v[114:129], v[178:181], v[138:141], v[114:129]
	v_mfma_f32_32x32x16_bf16 v[82:97], v[178:181], v[156:159], v[82:97]
	v_mfma_f32_32x32x16_bf16 v[114:129], v[186:189], v[142:145], v[114:129]
	v_mfma_f32_32x32x16_bf16 v[82:97], v[186:189], v[160:163], v[82:97]
	s_setprio 0
	s_barrier
	v_add3_u32 v246, v245, v240, 0
	v_add3_u32 v247, v245, v241, 0
	v_add3_u32 v248, v245, v242, 0
	v_add3_u32 v249, v245, v243, 0
	ds_read_b128 v[190:193], v246 offset:49152
	ds_read_b128 v[194:197], v247 offset:49152
	ds_read_b128 v[198:201], v248 offset:49152
	ds_read_b128 v[228:231], v249 offset:49152
	s_add_u32 m0, s100, 0x8000
	s_nop 0
	global_load_lds_dwordx4 v236, s[8:9]
	v_add_u32_e32 v236, 0x80, v236
	s_add_u32 m0, s100, 0xa000
	s_nop 0
	global_load_lds_dwordx4 v238, s[8:9]
	v_add_u32_e32 v238, 0x80, v238
	s_barrier
	s_waitcnt lgkmcnt(0)
	s_setprio 1
	v_mfma_f32_32x32x16_bf16 v[98:113], v[190:193], v[130:133], v[98:113]
	v_mfma_f32_32x32x16_bf16 v[66:81], v[190:193], v[146:149], v[66:81]
	v_mfma_f32_32x32x16_bf16 v[98:113], v[194:197], v[134:137], v[98:113]
	v_mfma_f32_32x32x16_bf16 v[66:81], v[194:197], v[150:153], v[66:81]
	v_mfma_f32_32x32x16_bf16 v[98:113], v[198:201], v[138:141], v[98:113]
	v_mfma_f32_32x32x16_bf16 v[66:81], v[198:201], v[156:159], v[66:81]
	v_mfma_f32_32x32x16_bf16 v[98:113], v[228:231], v[142:145], v[98:113]
	v_mfma_f32_32x32x16_bf16 v[66:81], v[228:231], v[160:163], v[66:81]
	s_setprio 0
	s_barrier
	v_add3_u32 v246, v244, v240, 0
	v_add3_u32 v247, v244, v241, 0
	v_add3_u32 v248, v244, v242, 0
	v_add3_u32 v249, v244, v243, 0
	ds_read_b128 v[130:133], v246 offset:16384
	ds_read_b128 v[134:137], v247 offset:16384
	ds_read_b128 v[138:141], v248 offset:16384
	ds_read_b128 v[142:145], v249 offset:16384
	ds_read_b128 v[146:149], v246 offset:20480
	ds_read_b128 v[150:153], v247 offset:20480
	ds_read_b128 v[156:159], v248 offset:20480
	ds_read_b128 v[160:163], v249 offset:20480
	s_add_u32 m0, s100, 0x0
	s_nop 0
	global_load_lds_dwordx4 v232, s[6:7]
	v_add_u32_e32 v232, 0x80, v232
	s_add_u32 m0, s100, 0x2000
	s_nop 0
	global_load_lds_dwordx4 v234, s[6:7]
	v_add_u32_e32 v234, 0x80, v234
	s_waitcnt vmcnt(10)
	s_barrier
	s_waitcnt lgkmcnt(0)
	s_setprio 1
	v_mfma_f32_32x32x16_bf16 v[50:65], v[170:173], v[130:133], v[50:65]
	v_mfma_f32_32x32x16_bf16 v[18:33], v[170:173], v[146:149], v[18:33]
	v_mfma_f32_32x32x16_bf16 v[50:65], v[174:177], v[134:137], v[50:65]
	v_mfma_f32_32x32x16_bf16 v[18:33], v[174:177], v[150:153], v[18:33]
	v_mfma_f32_32x32x16_bf16 v[50:65], v[178:181], v[138:141], v[50:65]
	v_mfma_f32_32x32x16_bf16 v[18:33], v[178:181], v[156:159], v[18:33]
	v_mfma_f32_32x32x16_bf16 v[50:65], v[186:189], v[142:145], v[50:65]
	v_mfma_f32_32x32x16_bf16 v[18:33], v[186:189], v[160:163], v[18:33]
	s_setprio 0
	s_barrier
	v_add3_u32 v246, v245, v240, s10
	v_add3_u32 v247, v245, v241, s10
	v_add3_u32 v248, v245, v242, s10
	v_add3_u32 v249, v245, v243, s10
	ds_read_b128 v[170:173], v246 offset:32768
	ds_read_b128 v[174:177], v247 offset:32768
	ds_read_b128 v[178:181], v248 offset:32768
	ds_read_b128 v[186:189], v249 offset:32768
	s_add_u32 m0, s100, 0xc000
	s_nop 0
	global_load_lds_dwordx4 v237, s[8:9]
	v_add_u32_e32 v237, 0x80, v237
	s_add_u32 m0, s100, 0xe000
	s_nop 0
	global_load_lds_dwordx4 v239, s[8:9]
	v_add_u32_e32 v239, 0x80, v239
	s_waitcnt vmcnt(6)
	s_barrier
	s_waitcnt lgkmcnt(0)
	s_setprio 1
	v_mfma_f32_32x32x16_bf16 v[34:49], v[190:193], v[130:133], v[34:49]
	v_mfma_f32_32x32x16_bf16 v[2:17], v[190:193], v[146:149], v[2:17]
	v_mfma_f32_32x32x16_bf16 v[34:49], v[194:197], v[134:137], v[34:49]
	v_mfma_f32_32x32x16_bf16 v[2:17], v[194:197], v[150:153], v[2:17]
	v_mfma_f32_32x32x16_bf16 v[34:49], v[198:201], v[138:141], v[34:49]
	v_mfma_f32_32x32x16_bf16 v[2:17], v[198:201], v[156:159], v[2:17]
	v_mfma_f32_32x32x16_bf16 v[34:49], v[228:231], v[142:145], v[34:49]
	v_mfma_f32_32x32x16_bf16 v[2:17], v[228:231], v[160:163], v[2:17]
	s_setprio 0
	s_barrier
	v_add3_u32 v246, v244, v240, s10
	v_add3_u32 v247, v244, v241, s10
	v_add3_u32 v248, v244, v242, s10
	v_add3_u32 v249, v244, v243, s10
	ds_read_b128 v[130:133], v246
	ds_read_b128 v[134:137], v247
	ds_read_b128 v[138:141], v248
	ds_read_b128 v[142:145], v249
	ds_read_b128 v[146:149], v246 offset:4096
	ds_read_b128 v[150:153], v247 offset:4096
	ds_read_b128 v[156:159], v248 offset:4096
	ds_read_b128 v[160:163], v249 offset:4096
	s_add_u32 m0, s100, 0x4000
	s_nop 0
	global_load_lds_dwordx4 v233, s[6:7]
	v_add_u32_e32 v233, 0x80, v233
	s_add_u32 m0, s100, 0x6000
	s_nop 0
	global_load_lds_dwordx4 v235, s[6:7]
	v_add_u32_e32 v235, 0x80, v235
	s_barrier
; template <bool SWAP>
; DI void gemm_mainloop(f32x16 (&acc)[4][2], const u16* __restrict__ A, int lda, int rlo, int rhi,
;                       const u16* __restrict__ B, int ldb, int K, char* lds, const u16* zero_line) {
;     ...
;   for (int kt = 0; kt < nk; ++kt) {
;     const char* st = lds + (kt & 1) * 65536;
;     ldfrag(st, 0, 0);
;     mma(1);
;     pat_rd();
;     if (kt + 1 < nk) glds(kt + 1, (kt + 1) & 1);
;     ldfrag(st, 1, 1);
;     mma(0);
;     pat_rd();
;     ldfrag(st, 2, 0);
;     mma(1);
;     pat_rd();
;     ldfrag(st, 3, 1);
;     mma(0);
;     pat_rd();
;     asm volatile("s_waitcnt vmcnt(0)" ::: "memory");
;     __syncthreads();
	s_waitcnt lgkmcnt(0)
	s_setprio 1
	v_mfma_f32_32x32x16_bf16 v[114:129], v[170:173], v[130:133], v[114:129]
	v_mfma_f32_32x32x16_bf16 v[82:97], v[170:173], v[146:149], v[82:97]
	v_mfma_f32_32x32x16_bf16 v[114:129], v[174:177], v[134:137], v[114:129]
	v_mfma_f32_32x32x16_bf16 v[82:97], v[174:177], v[150:153], v[82:97]
	v_mfma_f32_32x32x16_bf16 v[114:129], v[178:181], v[138:141], v[114:129]
	v_mfma_f32_32x32x16_bf16 v[82:97], v[178:181], v[156:159], v[82:97]
	v_mfma_f32_32x32x16_bf16 v[114:129], v[186:189], v[142:145], v[114:129]
	v_mfma_f32_32x32x16_bf16 v[82:97], v[186:189], v[160:163], v[82:97]
	s_setprio 0
	s_barrier
	v_add3_u32 v246, v245, v240, s10
	v_add3_u32 v247, v245, v241, s10
	v_add3_u32 v248, v245, v242, s10
	v_add3_u32 v249, v245, v243, s10
	ds_read_b128 v[190:193], v246 offset:49152
	ds_read_b128 v[194:197], v247 offset:49152
	ds_read_b128 v[198:201], v248 offset:49152
	ds_read_b128 v[228:231], v249 offset:49152
	s_add_u32 m0, s100, 0x18000
	s_nop 0
	global_load_lds_dwordx4 v236, s[8:9]
	v_add_u32_e32 v236, 0x80, v236
	s_add_u32 m0, s100, 0x1a000
	s_nop 0
	global_load_lds_dwordx4 v238, s[8:9]
	v_add_u32_e32 v238, 0x80, v238
	s_barrier
	s_waitcnt lgkmcnt(0)
	s_setprio 1
	v_mfma_f32_32x32x16_bf16 v[98:113], v[190:193], v[130:133], v[98:113]
	v_mfma_f32_32x32x16_bf16 v[66:81], v[190:193], v[146:149], v[66:81]
	v_mfma_f32_32x32x16_bf16 v[98:113], v[194:197], v[134:137], v[98:113]
	v_mfma_f32_32x32x16_bf16 v[66:81], v[194:197], v[150:153], v[66:81]
	v_mfma_f32_32x32x16_bf16 v[98:113], v[198:201], v[138:141], v[98:113]
	v_mfma_f32_32x32x16_bf16 v[66:81], v[198:201], v[156:159], v[66:81]
	v_mfma_f32_32x32x16_bf16 v[98:113], v[228:231], v[142:145], v[98:113]
	v_mfma_f32_32x32x16_bf16 v[66:81], v[228:231], v[160:163], v[66:81]
	s_setprio 0
	s_barrier
	v_add3_u32 v246, v244, v240, s10
	v_add3_u32 v247, v244, v241, s10
	v_add3_u32 v248, v244, v242, s10
	v_add3_u32 v249, v244, v243, s10
	ds_read_b128 v[130:133], v246 offset:16384
	ds_read_b128 v[134:137], v247 offset:16384
	ds_read_b128 v[138:141], v248 offset:16384
	ds_read_b128 v[142:145], v249 offset:16384
	ds_read_b128 v[146:149], v246 offset:20480
	ds_read_b128 v[150:153], v247 offset:20480
	ds_read_b128 v[156:159], v248 offset:20480
	ds_read_b128 v[160:163], v249 offset:20480
	s_add_u32 m0, s100, 0x10000
	s_nop 0
	global_load_lds_dwordx4 v232, s[6:7]
	v_add_u32_e32 v232, 0x80, v232
	s_add_u32 m0, s100, 0x12000
	s_nop 0
	global_load_lds_dwordx4 v234, s[6:7]
	v_add_u32_e32 v234, 0x80, v234
	s_waitcnt vmcnt(10)
	s_barrier
	s_waitcnt lgkmcnt(0)
	s_setprio 1
	v_mfma_f32_32x32x16_bf16 v[50:65], v[170:173], v[130:133], v[50:65]
	v_mfma_f32_32x32x16_bf16 v[18:33], v[170:173], v[146:149], v[18:33]
	v_mfma_f32_32x32x16_bf16 v[50:65], v[174:177], v[134:137], v[50:65]
	v_mfma_f32_32x32x16_bf16 v[18:33], v[174:177], v[150:153], v[18:33]
	v_mfma_f32_32x32x16_bf16 v[50:65], v[178:181], v[138:141], v[50:65]
	v_mfma_f32_32x32x16_bf16 v[18:33], v[178:181], v[156:159], v[18:33]
	v_mfma_f32_32x32x16_bf16 v[50:65], v[186:189], v[142:145], v[50:65]
	v_mfma_f32_32x32x16_bf16 v[18:33], v[186:189], v[160:163], v[18:33]
	s_setprio 0
	s_barrier
	v_add3_u32 v246, v245, v240, 0
	v_add3_u32 v247, v245, v241, 0
	v_add3_u32 v248, v245, v242, 0
	v_add3_u32 v249, v245, v243, 0
	ds_read_b128 v[170:173], v246 offset:32768
	ds_read_b128 v[174:177], v247 offset:32768
	ds_read_b128 v[178:181], v248 offset:32768
	ds_read_b128 v[186:189], v249 offset:32768
	s_add_u32 m0, s100, 0x1c000
	s_nop 0
	global_load_lds_dwordx4 v237, s[8:9]
	v_add_u32_e32 v237, 0x80, v237
	s_add_u32 m0, s100, 0x1e000
	s_nop 0
	global_load_lds_dwordx4 v239, s[8:9]
	v_add_u32_e32 v239, 0x80, v239
	s_waitcnt vmcnt(6)
	s_barrier
	s_waitcnt lgkmcnt(0)
	s_setprio 1
	v_mfma_f32_32x32x16_bf16 v[34:49], v[190:193], v[130:133], v[34:49]
	v_mfma_f32_32x32x16_bf16 v[2:17], v[190:193], v[146:149], v[2:17]
	v_mfma_f32_32x32x16_bf16 v[34:49], v[194:197], v[134:137], v[34:49]
	v_mfma_f32_32x32x16_bf16 v[2:17], v[194:197], v[150:153], v[2:17]
	v_mfma_f32_32x32x16_bf16 v[34:49], v[198:201], v[138:141], v[34:49]
	v_mfma_f32_32x32x16_bf16 v[2:17], v[198:201], v[156:159], v[2:17]
	v_mfma_f32_32x32x16_bf16 v[34:49], v[228:231], v[142:145], v[34:49]
	v_mfma_f32_32x32x16_bf16 v[2:17], v[228:231], v[160:163], v[2:17]
	s_setprio 0
	s_barrier
	s_add_i32 s11, s11, 2
	s_cmp_lt_u32 s11, 14
	s_cbranch_scc1 .Lg8_qb
	v_add3_u32 v246, v244, v240, 0
	v_add3_u32 v247, v244, v241, 0
	v_add3_u32 v248, v244, v242, 0
	v_add3_u32 v249, v244, v243, 0
	ds_read_b128 v[130:133], v246
	ds_read_b128 v[134:137], v247
	ds_read_b128 v[138:141], v248
	ds_read_b128 v[142:145], v249
	ds_read_b128 v[146:149], v246 offset:4096
	ds_read_b128 v[150:153], v247 offset:4096
	ds_read_b128 v[156:159], v248 offset:4096
	ds_read_b128 v[160:163], v249 offset:4096
	s_add_u32 m0, s100, 0x14000
	s_nop 0
	global_load_lds_dwordx4 v233, s[6:7]
	v_add_u32_e32 v233, 0x80, v233
	s_add_u32 m0, s100, 0x16000
	s_nop 0
	global_load_lds_dwordx4 v235, s[6:7]
	v_add_u32_e32 v235, 0x80, v235
	s_barrier
	s_waitcnt lgkmcnt(0)
	v_mfma_f32_32x32x16_bf16 v[114:129], v[170:173], v[130:133], v[114:129]
	v_mfma_f32_32x32x16_bf16 v[82:97], v[170:173], v[146:149], v[82:97]
	v_mfma_f32_32x32x16_bf16 v[114:129], v[174:177], v[134:137], v[114:129]
	v_mfma_f32_32x32x16_bf16 v[82:97], v[174:177], v[150:153], v[82:97]
	v_mfma_f32_32x32x16_bf16 v[114:129], v[178:181], v[138:141], v[114:129]
	v_mfma_f32_32x32x16_bf16 v[82:97], v[178:181], v[156:159], v[82:97]
	v_mfma_f32_32x32x16_bf16 v[114:129], v[186:189], v[142:145], v[114:129]
	v_mfma_f32_32x32x16_bf16 v[82:97], v[186:189], v[160:163], v[82:97]
	s_barrier
; template <bool SWAP>
; DI void gemm_mainloop(f32x16 (&acc)[4][2], const u16* __restrict__ A, int lda, int rlo, int rhi,
;                       const u16* __restrict__ B, int ldb, int K, char* lds, const u16* zero_line) {
;     ...
;   for (int kt = 0; kt < nk; ++kt) {
;     const char* st = lds + (kt & 1) * 65536;
;     ldfrag(st, 0, 0);
;     mma(1);
;     pat_rd();
;     if (kt + 1 < nk) glds(kt + 1, (kt + 1) & 1);
;     ldfrag(st, 1, 1);
;     mma(0);
;     pat_rd();
;     ldfrag(st, 2, 0);
;     mma(1);
;     pat_rd();
;     ldfrag(st, 3, 1);
;     mma(0);
;     pat_rd();
;     asm volatile("s_waitcnt vmcnt(0)" ::: "memory");
;     __syncthreads();
;   }
;   mma(1);
	v_add3_u32 v246, v245, v240, 0
	v_add3_u32 v247, v245, v241, 0
	v_add3_u32 v248, v245, v242, 0
	v_add3_u32 v249, v245, v243, 0
	ds_read_b128 v[190:193], v246 offset:49152
	ds_read_b128 v[194:197], v247 offset:49152
	ds_read_b128 v[198:201], v248 offset:49152
	ds_read_b128 v[228:231], v249 offset:49152
	s_barrier
	s_waitcnt lgkmcnt(0)
	v_mfma_f32_32x32x16_bf16 v[98:113], v[190:193], v[130:133], v[98:113]
	v_mfma_f32_32x32x16_bf16 v[66:81], v[190:193], v[146:149], v[66:81]
	v_mfma_f32_32x32x16_bf16 v[98:113], v[194:197], v[134:137], v[98:113]
	v_mfma_f32_32x32x16_bf16 v[66:81], v[194:197], v[150:153], v[66:81]
	v_mfma_f32_32x32x16_bf16 v[98:113], v[198:201], v[138:141], v[98:113]
	v_mfma_f32_32x32x16_bf16 v[66:81], v[198:201], v[156:159], v[66:81]
	v_mfma_f32_32x32x16_bf16 v[98:113], v[228:231], v[142:145], v[98:113]
	v_mfma_f32_32x32x16_bf16 v[66:81], v[228:231], v[160:163], v[66:81]
	s_barrier
	v_add3_u32 v246, v244, v240, 0
	v_add3_u32 v247, v244, v241, 0
	v_add3_u32 v248, v244, v242, 0
	v_add3_u32 v249, v244, v243, 0
	ds_read_b128 v[130:133], v246 offset:16384
	ds_read_b128 v[134:137], v247 offset:16384
	ds_read_b128 v[138:141], v248 offset:16384
	ds_read_b128 v[142:145], v249 offset:16384
	ds_read_b128 v[146:149], v246 offset:20480
	ds_read_b128 v[150:153], v247 offset:20480
	ds_read_b128 v[156:159], v248 offset:20480
	ds_read_b128 v[160:163], v249 offset:20480
	s_waitcnt vmcnt(4)
	s_barrier
	s_waitcnt lgkmcnt(0)
	v_mfma_f32_32x32x16_bf16 v[50:65], v[170:173], v[130:133], v[50:65]
	v_mfma_f32_32x32x16_bf16 v[18:33], v[170:173], v[146:149], v[18:33]
	v_mfma_f32_32x32x16_bf16 v[50:65], v[174:177], v[134:137], v[50:65]
	v_mfma_f32_32x32x16_bf16 v[18:33], v[174:177], v[150:153], v[18:33]
	v_mfma_f32_32x32x16_bf16 v[50:65], v[178:181], v[138:141], v[50:65]
	v_mfma_f32_32x32x16_bf16 v[18:33], v[178:181], v[156:159], v[18:33]
	v_mfma_f32_32x32x16_bf16 v[50:65], v[186:189], v[142:145], v[50:65]
	v_mfma_f32_32x32x16_bf16 v[18:33], v[186:189], v[160:163], v[18:33]
	v_mfma_f32_32x32x16_bf16 v[34:49], v[190:193], v[130:133], v[34:49]
	v_mfma_f32_32x32x16_bf16 v[2:17], v[190:193], v[146:149], v[2:17]
	v_mfma_f32_32x32x16_bf16 v[34:49], v[194:197], v[134:137], v[34:49]
	v_mfma_f32_32x32x16_bf16 v[2:17], v[194:197], v[150:153], v[2:17]
	v_mfma_f32_32x32x16_bf16 v[34:49], v[198:201], v[138:141], v[34:49]
	v_mfma_f32_32x32x16_bf16 v[2:17], v[198:201], v[156:159], v[2:17]
	v_mfma_f32_32x32x16_bf16 v[34:49], v[228:231], v[142:145], v[34:49]
	v_mfma_f32_32x32x16_bf16 v[2:17], v[228:231], v[160:163], v[2:17]
	s_barrier
	v_add3_u32 v246, v245, v240, s10
	v_add3_u32 v247, v245, v241, s10
	v_add3_u32 v248, v245, v242, s10
	v_add3_u32 v249, v245, v243, s10
	ds_read_b128 v[170:173], v246 offset:32768
	ds_read_b128 v[174:177], v247 offset:32768
	ds_read_b128 v[178:181], v248 offset:32768
	ds_read_b128 v[186:189], v249 offset:32768
	v_add3_u32 v246, v244, v240, s10
	v_add3_u32 v247, v244, v241, s10
	v_add3_u32 v248, v244, v242, s10
	v_add3_u32 v249, v244, v243, s10
	ds_read_b128 v[130:133], v246
	ds_read_b128 v[134:137], v247
	ds_read_b128 v[138:141], v248
	ds_read_b128 v[142:145], v249
	ds_read_b128 v[146:149], v246 offset:4096
	ds_read_b128 v[150:153], v247 offset:4096
	ds_read_b128 v[156:159], v248 offset:4096
	ds_read_b128 v[160:163], v249 offset:4096
	s_waitcnt vmcnt(2)
	s_barrier
	s_waitcnt lgkmcnt(0)
	v_mfma_f32_32x32x16_bf16 v[114:129], v[170:173], v[130:133], v[114:129]
	v_mfma_f32_32x32x16_bf16 v[82:97], v[170:173], v[146:149], v[82:97]
	v_mfma_f32_32x32x16_bf16 v[114:129], v[174:177], v[134:137], v[114:129]
	v_mfma_f32_32x32x16_bf16 v[82:97], v[174:177], v[150:153], v[82:97]
	v_mfma_f32_32x32x16_bf16 v[114:129], v[178:181], v[138:141], v[114:129]
	v_mfma_f32_32x32x16_bf16 v[82:97], v[178:181], v[156:159], v[82:97]
	v_mfma_f32_32x32x16_bf16 v[114:129], v[186:189], v[142:145], v[114:129]
	v_mfma_f32_32x32x16_bf16 v[82:97], v[186:189], v[160:163], v[82:97]
	s_barrier
	v_add3_u32 v246, v245, v240, s10
	v_add3_u32 v247, v245, v241, s10
	v_add3_u32 v248, v245, v242, s10
	v_add3_u32 v249, v245, v243, s10
	ds_read_b128 v[190:193], v246 offset:49152
	ds_read_b128 v[194:197], v247 offset:49152
	ds_read_b128 v[198:201], v248 offset:49152
	ds_read_b128 v[228:231], v249 offset:49152
	s_waitcnt vmcnt(0)
	s_barrier
	s_waitcnt lgkmcnt(0)
	v_mfma_f32_32x32x16_bf16 v[98:113], v[190:193], v[130:133], v[98:113]
	v_mfma_f32_32x32x16_bf16 v[66:81], v[190:193], v[146:149], v[66:81]
	v_mfma_f32_32x32x16_bf16 v[98:113], v[194:197], v[134:137], v[98:113]
	v_mfma_f32_32x32x16_bf16 v[66:81], v[194:197], v[150:153], v[66:81]
	v_mfma_f32_32x32x16_bf16 v[98:113], v[198:201], v[138:141], v[98:113]
	v_mfma_f32_32x32x16_bf16 v[66:81], v[198:201], v[156:159], v[66:81]
	v_mfma_f32_32x32x16_bf16 v[98:113], v[228:231], v[142:145], v[98:113]
	v_mfma_f32_32x32x16_bf16 v[66:81], v[228:231], v[160:163], v[66:81]
	s_barrier
	v_add3_u32 v246, v244, v240, s10
	v_add3_u32 v247, v244, v241, s10
	v_add3_u32 v248, v244, v242, s10
	v_add3_u32 v249, v244, v243, s10
	ds_read_b128 v[130:133], v246 offset:16384
	ds_read_b128 v[134:137], v247 offset:16384
	ds_read_b128 v[138:141], v248 offset:16384
	ds_read_b128 v[142:145], v249 offset:16384
	ds_read_b128 v[146:149], v246 offset:20480
	ds_read_b128 v[150:153], v247 offset:20480
	ds_read_b128 v[156:159], v248 offset:20480
	ds_read_b128 v[160:163], v249 offset:20480
	s_barrier
	s_waitcnt lgkmcnt(0)
	v_mfma_f32_32x32x16_bf16 v[50:65], v[170:173], v[130:133], v[50:65]
	v_mfma_f32_32x32x16_bf16 v[18:33], v[170:173], v[146:149], v[18:33]
	v_mfma_f32_32x32x16_bf16 v[50:65], v[174:177], v[134:137], v[50:65]
	v_mfma_f32_32x32x16_bf16 v[18:33], v[174:177], v[150:153], v[18:33]
	v_mfma_f32_32x32x16_bf16 v[50:65], v[178:181], v[138:141], v[50:65]
	v_mfma_f32_32x32x16_bf16 v[18:33], v[178:181], v[156:159], v[18:33]
	v_mfma_f32_32x32x16_bf16 v[50:65], v[186:189], v[142:145], v[50:65]
	v_mfma_f32_32x32x16_bf16 v[18:33], v[186:189], v[160:163], v[18:33]
	v_mfma_f32_32x32x16_bf16 v[34:49], v[190:193], v[130:133], v[34:49]
	v_mfma_f32_32x32x16_bf16 v[2:17], v[190:193], v[146:149], v[2:17]
	v_mfma_f32_32x32x16_bf16 v[34:49], v[194:197], v[134:137], v[34:49]
	v_mfma_f32_32x32x16_bf16 v[2:17], v[194:197], v[150:153], v[2:17]
	v_mfma_f32_32x32x16_bf16 v[34:49], v[198:201], v[138:141], v[34:49]
	v_mfma_f32_32x32x16_bf16 v[2:17], v[198:201], v[156:159], v[2:17]
	v_mfma_f32_32x32x16_bf16 v[34:49], v[228:231], v[142:145], v[34:49]
	v_mfma_f32_32x32x16_bf16 v[2:17], v[228:231], v[160:163], v[2:17]
	s_barrier
	s_cmp_eq_u32 s101, 0
	s_cbranch_scc0 .Lg8_qb_p1
	s_barrier

; template <bool SWAP>
; DI void gemm_mainloop(f32x16 (&acc)[4][2], const u16* __restrict__ A, int lda, int rlo, int rhi,
;                       const u16* __restrict__ B, int ldb, int K, char* lds, const u16* zero_line) {
;     ...
;   for (int kt = 0; kt < nk; ++kt) {
;     const char* st = lds + (kt & 1) * 65536;
;     ldfrag(st, 0, 0);
;     mma(1);
;     pat_rd();
;     if (kt + 1 < nk) glds(kt + 1, (kt + 1) & 1);
;     ldfrag(st, 1, 1);
;     mma(0);
;     pat_rd();
;     ldfrag(st, 2, 0);
;     mma(1);
;     pat_rd();
;     ldfrag(st, 3, 1);
;     mma(0);
;     pat_rd();
;     asm volatile("s_waitcnt vmcnt(0)" ::: "memory");
;     __syncthreads();
.Lg8_m246:
	v_add3_u32 v242, v240, v236, 0
	v_add3_u32 v243, v240, v237, 0
	v_add3_u32 v244, v240, v238, 0
	v_add3_u32 v245, v240, v239, 0
	ds_read_b128 v[130:133], v242
	ds_read_b128 v[134:137], v243
	ds_read_b128 v[138:141], v244
	ds_read_b128 v[142:145], v245
	ds_read_b128 v[146:149], v242 offset:4096
	ds_read_b128 v[150:153], v243 offset:4096
	ds_read_b128 v[154:157], v244 offset:4096
	ds_read_b128 v[158:161], v245 offset:4096
	s_add_u32 m0, s100, 0x14000
	s_nop 0
	global_load_lds_dwordx4 v229, s[6:7]
	v_add_u32_e32 v229, 0x80, v229
	s_add_u32 m0, s100, 0x16000
	s_nop 0
	global_load_lds_dwordx4 v231, s[6:7]
	v_add_u32_e32 v231, 0x80, v231
	s_barrier
	s_waitcnt lgkmcnt(0)
	s_setprio 1
	v_mfma_f32_32x32x16_bf16 v[114:129], v[162:165], v[130:133], v[114:129]
	v_mfma_f32_32x32x16_bf16 v[82:97], v[162:165], v[146:149], v[82:97]
	v_mfma_f32_32x32x16_bf16 v[114:129], v[166:169], v[134:137], v[114:129]
	v_mfma_f32_32x32x16_bf16 v[82:97], v[166:169], v[150:153], v[82:97]
	v_mfma_f32_32x32x16_bf16 v[114:129], v[170:173], v[138:141], v[114:129]
	v_mfma_f32_32x32x16_bf16 v[82:97], v[170:173], v[154:157], v[82:97]
	v_mfma_f32_32x32x16_bf16 v[114:129], v[174:177], v[142:145], v[114:129]
	v_mfma_f32_32x32x16_bf16 v[82:97], v[174:177], v[158:161], v[82:97]
	s_setprio 0
	s_barrier
	v_add3_u32 v242, v241, v236, 0
	v_add3_u32 v243, v241, v237, 0
	v_add3_u32 v244, v241, v238, 0
	v_add3_u32 v245, v241, v239, 0
	ds_read_b128 v[180:183], v242 offset:49152
	ds_read_b128 v[186:189], v243 offset:49152
	ds_read_b128 v[190:193], v244 offset:49152
	ds_read_b128 v[194:197], v245 offset:49152
	s_add_u32 m0, s100, 0x8000
	s_nop 0
	global_load_lds_dwordx4 v232, s[8:9]
	v_add_u32_e32 v232, 0x80, v232
	s_add_u32 m0, s100, 0xa000
	s_nop 0
	global_load_lds_dwordx4 v234, s[8:9]
	v_add_u32_e32 v234, 0x80, v234
	s_barrier
	s_waitcnt lgkmcnt(0)
	s_setprio 1
	v_mfma_f32_32x32x16_bf16 v[98:113], v[180:183], v[130:133], v[98:113]
	v_mfma_f32_32x32x16_bf16 v[66:81], v[180:183], v[146:149], v[66:81]
	v_mfma_f32_32x32x16_bf16 v[98:113], v[186:189], v[134:137], v[98:113]
	v_mfma_f32_32x32x16_bf16 v[66:81], v[186:189], v[150:153], v[66:81]
	v_mfma_f32_32x32x16_bf16 v[98:113], v[190:193], v[138:141], v[98:113]
	v_mfma_f32_32x32x16_bf16 v[66:81], v[190:193], v[154:157], v[66:81]
	v_mfma_f32_32x32x16_bf16 v[98:113], v[194:197], v[142:145], v[98:113]
	v_mfma_f32_32x32x16_bf16 v[66:81], v[194:197], v[158:161], v[66:81]
	s_setprio 0
	s_barrier
	v_add3_u32 v242, v240, v236, 0
	v_add3_u32 v243, v240, v237, 0
	v_add3_u32 v244, v240, v238, 0
	v_add3_u32 v245, v240, v239, 0
	ds_read_b128 v[130:133], v242 offset:16384
	ds_read_b128 v[134:137], v243 offset:16384
	ds_read_b128 v[138:141], v244 offset:16384
	ds_read_b128 v[142:145], v245 offset:16384
	ds_read_b128 v[146:149], v242 offset:20480
	ds_read_b128 v[150:153], v243 offset:20480
	ds_read_b128 v[154:157], v244 offset:20480
	ds_read_b128 v[158:161], v245 offset:20480
	s_add_u32 m0, s100, 0x0
	s_nop 0
	global_load_lds_dwordx4 v228, s[6:7]
	v_add_u32_e32 v228, 0x80, v228
	s_add_u32 m0, s100, 0x2000
	s_nop 0
	global_load_lds_dwordx4 v230, s[6:7]
	v_add_u32_e32 v230, 0x80, v230
	s_waitcnt vmcnt(10)
	s_barrier
	s_waitcnt lgkmcnt(0)
	s_setprio 1
	v_mfma_f32_32x32x16_bf16 v[50:65], v[162:165], v[130:133], v[50:65]
	v_mfma_f32_32x32x16_bf16 v[18:33], v[162:165], v[146:149], v[18:33]
	v_mfma_f32_32x32x16_bf16 v[50:65], v[166:169], v[134:137], v[50:65]
	v_mfma_f32_32x32x16_bf16 v[18:33], v[166:169], v[150:153], v[18:33]
	v_mfma_f32_32x32x16_bf16 v[50:65], v[170:173], v[138:141], v[50:65]
	v_mfma_f32_32x32x16_bf16 v[18:33], v[170:173], v[154:157], v[18:33]
	v_mfma_f32_32x32x16_bf16 v[50:65], v[174:177], v[142:145], v[50:65]
	v_mfma_f32_32x32x16_bf16 v[18:33], v[174:177], v[158:161], v[18:33]
	s_setprio 0
	s_barrier
	v_add3_u32 v242, v241, v236, s10
	v_add3_u32 v243, v241, v237, s10
	v_add3_u32 v244, v241, v238, s10
	v_add3_u32 v245, v241, v239, s10
	ds_read_b128 v[162:165], v242 offset:32768
	ds_read_b128 v[166:169], v243 offset:32768
	ds_read_b128 v[170:173], v244 offset:32768
	ds_read_b128 v[174:177], v245 offset:32768
	s_add_u32 m0, s100, 0xc000
	s_nop 0
	global_load_lds_dwordx4 v233, s[8:9]
	v_add_u32_e32 v233, 0x80, v233
	s_add_u32 m0, s100, 0xe000
	s_nop 0
	global_load_lds_dwordx4 v235, s[8:9]
	v_add_u32_e32 v235, 0x80, v235
	s_waitcnt vmcnt(6)
	s_barrier
	s_waitcnt lgkmcnt(0)
	s_setprio 1
	v_mfma_f32_32x32x16_bf16 v[34:49], v[180:183], v[130:133], v[34:49]
	v_mfma_f32_32x32x16_bf16 v[2:17], v[180:183], v[146:149], v[2:17]
	v_mfma_f32_32x32x16_bf16 v[34:49], v[186:189], v[134:137], v[34:49]
	v_mfma_f32_32x32x16_bf16 v[2:17], v[186:189], v[150:153], v[2:17]
	v_mfma_f32_32x32x16_bf16 v[34:49], v[190:193], v[138:141], v[34:49]
	v_mfma_f32_32x32x16_bf16 v[2:17], v[190:193], v[154:157], v[2:17]
	v_mfma_f32_32x32x16_bf16 v[34:49], v[194:197], v[142:145], v[34:49]
	v_mfma_f32_32x32x16_bf16 v[2:17], v[194:197], v[158:161], v[2:17]
	s_setprio 0
	s_barrier
	v_add3_u32 v242, v240, v236, s10
	v_add3_u32 v243, v240, v237, s10
	v_add3_u32 v244, v240, v238, s10
	v_add3_u32 v245, v240, v239, s10
	ds_read_b128 v[130:133], v242
	ds_read_b128 v[134:137], v243
	ds_read_b128 v[138:141], v244
	ds_read_b128 v[142:145], v245
	ds_read_b128 v[146:149], v242 offset:4096
	ds_read_b128 v[150:153], v243 offset:4096
	ds_read_b128 v[154:157], v244 offset:4096
	ds_read_b128 v[158:161], v245 offset:4096
	s_add_u32 m0, s100, 0x4000
	s_nop 0
	global_load_lds_dwordx4 v229, s[6:7]
	v_add_u32_e32 v229, 0x80, v229
	s_add_u32 m0, s100, 0x6000
	s_nop 0
	global_load_lds_dwordx4 v231, s[6:7]
	v_add_u32_e32 v231, 0x80, v231
	s_barrier
; template <bool SWAP>
; DI void gemm_mainloop(f32x16 (&acc)[4][2], const u16* __restrict__ A, int lda, int rlo, int rhi,
;                       const u16* __restrict__ B, int ldb, int K, char* lds, const u16* zero_line) {
;     ...
;   for (int kt = 0; kt < nk; ++kt) {
;     const char* st = lds + (kt & 1) * 65536;
;     ldfrag(st, 0, 0);
;     mma(1);
;     pat_rd();
;     if (kt + 1 < nk) glds(kt + 1, (kt + 1) & 1);
;     ldfrag(st, 1, 1);
;     mma(0);
;     pat_rd();
;     ldfrag(st, 2, 0);
;     mma(1);
;     pat_rd();
;     ldfrag(st, 3, 1);
;     mma(0);
;     pat_rd();
;     asm volatile("s_waitcnt vmcnt(0)" ::: "memory");
;     __syncthreads();
	s_waitcnt lgkmcnt(0)
	s_setprio 1
	v_mfma_f32_32x32x16_bf16 v[114:129], v[162:165], v[130:133], v[114:129]
	v_mfma_f32_32x32x16_bf16 v[82:97], v[162:165], v[146:149], v[82:97]
	v_mfma_f32_32x32x16_bf16 v[114:129], v[166:169], v[134:137], v[114:129]
	v_mfma_f32_32x32x16_bf16 v[82:97], v[166:169], v[150:153], v[82:97]
	v_mfma_f32_32x32x16_bf16 v[114:129], v[170:173], v[138:141], v[114:129]
	v_mfma_f32_32x32x16_bf16 v[82:97], v[170:173], v[154:157], v[82:97]
	v_mfma_f32_32x32x16_bf16 v[114:129], v[174:177], v[142:145], v[114:129]
	v_mfma_f32_32x32x16_bf16 v[82:97], v[174:177], v[158:161], v[82:97]
	s_setprio 0
	s_barrier
	v_add3_u32 v242, v241, v236, s10
	v_add3_u32 v243, v241, v237, s10
	v_add3_u32 v244, v241, v238, s10
	v_add3_u32 v245, v241, v239, s10
	ds_read_b128 v[180:183], v242 offset:49152
	ds_read_b128 v[186:189], v243 offset:49152
	ds_read_b128 v[190:193], v244 offset:49152
	ds_read_b128 v[194:197], v245 offset:49152
	s_add_u32 m0, s100, 0x18000
	s_nop 0
	global_load_lds_dwordx4 v232, s[8:9]
	v_add_u32_e32 v232, 0x80, v232
	s_add_u32 m0, s100, 0x1a000
	s_nop 0
	global_load_lds_dwordx4 v234, s[8:9]
	v_add_u32_e32 v234, 0x80, v234
	s_barrier
	s_waitcnt lgkmcnt(0)
	s_setprio 1
	v_mfma_f32_32x32x16_bf16 v[98:113], v[180:183], v[130:133], v[98:113]
	v_mfma_f32_32x32x16_bf16 v[66:81], v[180:183], v[146:149], v[66:81]
	v_mfma_f32_32x32x16_bf16 v[98:113], v[186:189], v[134:137], v[98:113]
	v_mfma_f32_32x32x16_bf16 v[66:81], v[186:189], v[150:153], v[66:81]
	v_mfma_f32_32x32x16_bf16 v[98:113], v[190:193], v[138:141], v[98:113]
	v_mfma_f32_32x32x16_bf16 v[66:81], v[190:193], v[154:157], v[66:81]
	v_mfma_f32_32x32x16_bf16 v[98:113], v[194:197], v[142:145], v[98:113]
	v_mfma_f32_32x32x16_bf16 v[66:81], v[194:197], v[158:161], v[66:81]
	s_setprio 0
	s_barrier
	v_add3_u32 v242, v240, v236, s10
	v_add3_u32 v243, v240, v237, s10
	v_add3_u32 v244, v240, v238, s10
	v_add3_u32 v245, v240, v239, s10
	ds_read_b128 v[130:133], v242 offset:16384
	ds_read_b128 v[134:137], v243 offset:16384
	ds_read_b128 v[138:141], v244 offset:16384
	ds_read_b128 v[142:145], v245 offset:16384
	ds_read_b128 v[146:149], v242 offset:20480
	ds_read_b128 v[150:153], v243 offset:20480
	ds_read_b128 v[154:157], v244 offset:20480
	ds_read_b128 v[158:161], v245 offset:20480
	s_add_u32 m0, s100, 0x10000
	s_nop 0
	global_load_lds_dwordx4 v228, s[6:7]
	v_add_u32_e32 v228, 0x80, v228
	s_add_u32 m0, s100, 0x12000
	s_nop 0
	global_load_lds_dwordx4 v230, s[6:7]
	v_add_u32_e32 v230, 0x80, v230
	s_waitcnt vmcnt(10)
	s_barrier
	s_waitcnt lgkmcnt(0)
	s_setprio 1
	v_mfma_f32_32x32x16_bf16 v[50:65], v[162:165], v[130:133], v[50:65]
	v_mfma_f32_32x32x16_bf16 v[18:33], v[162:165], v[146:149], v[18:33]
	v_mfma_f32_32x32x16_bf16 v[50:65], v[166:169], v[134:137], v[50:65]
	v_mfma_f32_32x32x16_bf16 v[18:33], v[166:169], v[150:153], v[18:33]
	v_mfma_f32_32x32x16_bf16 v[50:65], v[170:173], v[138:141], v[50:65]
	v_mfma_f32_32x32x16_bf16 v[18:33], v[170:173], v[154:157], v[18:33]
	v_mfma_f32_32x32x16_bf16 v[50:65], v[174:177], v[142:145], v[50:65]
	v_mfma_f32_32x32x16_bf16 v[18:33], v[174:177], v[158:161], v[18:33]
	s_setprio 0
	s_barrier
	v_add3_u32 v242, v241, v236, 0
	v_add3_u32 v243, v241, v237, 0
	v_add3_u32 v244, v241, v238, 0
	v_add3_u32 v245, v241, v239, 0
	ds_read_b128 v[162:165], v242 offset:32768
	ds_read_b128 v[166:169], v243 offset:32768
	ds_read_b128 v[170:173], v244 offset:32768
	ds_read_b128 v[174:177], v245 offset:32768
	s_add_u32 m0, s100, 0x1c000
	s_nop 0
	global_load_lds_dwordx4 v233, s[8:9]
	v_add_u32_e32 v233, 0x80, v233
	s_add_u32 m0, s100, 0x1e000
	s_nop 0
	global_load_lds_dwordx4 v235, s[8:9]
	v_add_u32_e32 v235, 0x80, v235
	s_waitcnt vmcnt(6)
	s_barrier
	s_waitcnt lgkmcnt(0)
	s_setprio 1
	v_mfma_f32_32x32x16_bf16 v[34:49], v[180:183], v[130:133], v[34:49]
	v_mfma_f32_32x32x16_bf16 v[2:17], v[180:183], v[146:149], v[2:17]
	v_mfma_f32_32x32x16_bf16 v[34:49], v[186:189], v[134:137], v[34:49]
	v_mfma_f32_32x32x16_bf16 v[2:17], v[186:189], v[150:153], v[2:17]
	v_mfma_f32_32x32x16_bf16 v[34:49], v[190:193], v[138:141], v[34:49]
	v_mfma_f32_32x32x16_bf16 v[2:17], v[190:193], v[154:157], v[2:17]
	v_mfma_f32_32x32x16_bf16 v[34:49], v[194:197], v[142:145], v[34:49]
	v_mfma_f32_32x32x16_bf16 v[2:17], v[194:197], v[158:161], v[2:17]
	s_setprio 0
	s_barrier
	s_add_i32 s11, s11, 2
	s_cmp_lt_u32 s11, s25
	s_cbranch_scc1 .Lg8_m246
	v_add3_u32 v242, v240, v236, 0
	v_add3_u32 v243, v240, v237, 0
	v_add3_u32 v244, v240, v238, 0
	v_add3_u32 v245, v240, v239, 0
	ds_read_b128 v[130:133], v242
	ds_read_b128 v[134:137], v243
	ds_read_b128 v[138:141], v244
	ds_read_b128 v[142:145], v245
	ds_read_b128 v[146:149], v242 offset:4096
	ds_read_b128 v[150:153], v243 offset:4096
	ds_read_b128 v[154:157], v244 offset:4096
	ds_read_b128 v[158:161], v245 offset:4096
	s_add_u32 m0, s100, 0x14000
	s_nop 0
	global_load_lds_dwordx4 v229, s[6:7]
	v_add_u32_e32 v229, 0x80, v229
	s_add_u32 m0, s100, 0x16000
	s_nop 0
	global_load_lds_dwordx4 v231, s[6:7]
	v_add_u32_e32 v231, 0x80, v231
	s_barrier
	s_waitcnt lgkmcnt(0)
	v_mfma_f32_32x32x16_bf16 v[114:129], v[162:165], v[130:133], v[114:129]
	v_mfma_f32_32x32x16_bf16 v[82:97], v[162:165], v[146:149], v[82:97]
	v_mfma_f32_32x32x16_bf16 v[114:129], v[166:169], v[134:137], v[114:129]
	v_mfma_f32_32x32x16_bf16 v[82:97], v[166:169], v[150:153], v[82:97]
	v_mfma_f32_32x32x16_bf16 v[114:129], v[170:173], v[138:141], v[114:129]
	v_mfma_f32_32x32x16_bf16 v[82:97], v[170:173], v[154:157], v[82:97]
	v_mfma_f32_32x32x16_bf16 v[114:129], v[174:177], v[142:145], v[114:129]
	v_mfma_f32_32x32x16_bf16 v[82:97], v[174:177], v[158:161], v[82:97]
	s_barrier
; template <bool SWAP>
; DI void gemm_mainloop(f32x16 (&acc)[4][2], const u16* __restrict__ A, int lda, int rlo, int rhi,
;                       const u16* __restrict__ B, int ldb, int K, char* lds, const u16* zero_line) {
;     ...
; #pragma unroll 2
;   for (int kt = 0; kt < nk; ++kt) {
;     const char* st = lds + (kt & 1) * 65536;
;     ldfrag(st, 0, 0);
;     mma(1);
;     pat_rd();
;     if (kt + 1 < nk) glds(kt + 1, (kt + 1) & 1);
;     ldfrag(st, 1, 1);
;     mma(0);
;     pat_rd();
;     ldfrag(st, 2, 0);
;     mma(1);
;     pat_rd();
;     ldfrag(st, 3, 1);
;     mma(0);
;     pat_rd();
;     asm volatile("s_waitcnt vmcnt(0)" ::: "memory");
;     __syncthreads();
;   }
;   mma(1);
	v_add3_u32 v242, v241, v236, 0
	v_add3_u32 v243, v241, v237, 0
	v_add3_u32 v244, v241, v238, 0
	v_add3_u32 v245, v241, v239, 0
	ds_read_b128 v[180:183], v242 offset:49152
	ds_read_b128 v[186:189], v243 offset:49152
	ds_read_b128 v[190:193], v244 offset:49152
	ds_read_b128 v[194:197], v245 offset:49152
	s_barrier
	s_waitcnt lgkmcnt(0)
	v_mfma_f32_32x32x16_bf16 v[98:113], v[180:183], v[130:133], v[98:113]
	v_mfma_f32_32x32x16_bf16 v[66:81], v[180:183], v[146:149], v[66:81]
	v_mfma_f32_32x32x16_bf16 v[98:113], v[186:189], v[134:137], v[98:113]
	v_mfma_f32_32x32x16_bf16 v[66:81], v[186:189], v[150:153], v[66:81]
	v_mfma_f32_32x32x16_bf16 v[98:113], v[190:193], v[138:141], v[98:113]
	v_mfma_f32_32x32x16_bf16 v[66:81], v[190:193], v[154:157], v[66:81]
	v_mfma_f32_32x32x16_bf16 v[98:113], v[194:197], v[142:145], v[98:113]
	v_mfma_f32_32x32x16_bf16 v[66:81], v[194:197], v[158:161], v[66:81]
	s_barrier
	v_add3_u32 v242, v240, v236, 0
	v_add3_u32 v243, v240, v237, 0
	v_add3_u32 v244, v240, v238, 0
	v_add3_u32 v245, v240, v239, 0
	ds_read_b128 v[130:133], v242 offset:16384
	ds_read_b128 v[134:137], v243 offset:16384
	ds_read_b128 v[138:141], v244 offset:16384
	ds_read_b128 v[142:145], v245 offset:16384
	ds_read_b128 v[146:149], v242 offset:20480
	ds_read_b128 v[150:153], v243 offset:20480
	ds_read_b128 v[154:157], v244 offset:20480
	ds_read_b128 v[158:161], v245 offset:20480
	s_waitcnt vmcnt(4)
	s_barrier
	s_waitcnt lgkmcnt(0)
	v_mfma_f32_32x32x16_bf16 v[50:65], v[162:165], v[130:133], v[50:65]
	v_mfma_f32_32x32x16_bf16 v[18:33], v[162:165], v[146:149], v[18:33]
	v_mfma_f32_32x32x16_bf16 v[50:65], v[166:169], v[134:137], v[50:65]
	v_mfma_f32_32x32x16_bf16 v[18:33], v[166:169], v[150:153], v[18:33]
	v_mfma_f32_32x32x16_bf16 v[50:65], v[170:173], v[138:141], v[50:65]
	v_mfma_f32_32x32x16_bf16 v[18:33], v[170:173], v[154:157], v[18:33]
	v_mfma_f32_32x32x16_bf16 v[50:65], v[174:177], v[142:145], v[50:65]
	v_mfma_f32_32x32x16_bf16 v[18:33], v[174:177], v[158:161], v[18:33]
	v_mfma_f32_32x32x16_bf16 v[34:49], v[180:183], v[130:133], v[34:49]
	v_mfma_f32_32x32x16_bf16 v[2:17], v[180:183], v[146:149], v[2:17]
	v_mfma_f32_32x32x16_bf16 v[34:49], v[186:189], v[134:137], v[34:49]
	v_mfma_f32_32x32x16_bf16 v[2:17], v[186:189], v[150:153], v[2:17]
	v_mfma_f32_32x32x16_bf16 v[34:49], v[190:193], v[138:141], v[34:49]
	v_mfma_f32_32x32x16_bf16 v[2:17], v[190:193], v[154:157], v[2:17]
	v_mfma_f32_32x32x16_bf16 v[34:49], v[194:197], v[142:145], v[34:49]
	v_mfma_f32_32x32x16_bf16 v[2:17], v[194:197], v[158:161], v[2:17]
	s_barrier
	v_add3_u32 v242, v241, v236, s10
	v_add3_u32 v243, v241, v237, s10
	v_add3_u32 v244, v241, v238, s10
	v_add3_u32 v245, v241, v239, s10
	ds_read_b128 v[162:165], v242 offset:32768
	ds_read_b128 v[166:169], v243 offset:32768
	ds_read_b128 v[170:173], v244 offset:32768
	ds_read_b128 v[174:177], v245 offset:32768
	v_add3_u32 v242, v240, v236, s10
	v_add3_u32 v243, v240, v237, s10
	v_add3_u32 v244, v240, v238, s10
	v_add3_u32 v245, v240, v239, s10
	ds_read_b128 v[130:133], v242
	ds_read_b128 v[134:137], v243
	ds_read_b128 v[138:141], v244
	ds_read_b128 v[142:145], v245
	ds_read_b128 v[146:149], v242 offset:4096
	ds_read_b128 v[150:153], v243 offset:4096
	ds_read_b128 v[154:157], v244 offset:4096
	ds_read_b128 v[158:161], v245 offset:4096
	s_waitcnt vmcnt(2)
	s_barrier
	s_waitcnt lgkmcnt(0)
	v_mfma_f32_32x32x16_bf16 v[114:129], v[162:165], v[130:133], v[114:129]
	v_mfma_f32_32x32x16_bf16 v[82:97], v[162:165], v[146:149], v[82:97]
	v_mfma_f32_32x32x16_bf16 v[114:129], v[166:169], v[134:137], v[114:129]
	v_mfma_f32_32x32x16_bf16 v[82:97], v[166:169], v[150:153], v[82:97]
	v_mfma_f32_32x32x16_bf16 v[114:129], v[170:173], v[138:141], v[114:129]
	v_mfma_f32_32x32x16_bf16 v[82:97], v[170:173], v[154:157], v[82:97]
	v_mfma_f32_32x32x16_bf16 v[114:129], v[174:177], v[142:145], v[114:129]
	v_mfma_f32_32x32x16_bf16 v[82:97], v[174:177], v[158:161], v[82:97]
	s_barrier
	v_add3_u32 v242, v241, v236, s10
	v_add3_u32 v243, v241, v237, s10
	v_add3_u32 v244, v241, v238, s10
	v_add3_u32 v245, v241, v239, s10
	ds_read_b128 v[180:183], v242 offset:49152
	ds_read_b128 v[186:189], v243 offset:49152
	ds_read_b128 v[190:193], v244 offset:49152
	ds_read_b128 v[194:197], v245 offset:49152
	s_waitcnt vmcnt(0)
	s_barrier
	s_waitcnt lgkmcnt(0)
	v_mfma_f32_32x32x16_bf16 v[98:113], v[180:183], v[130:133], v[98:113]
	v_mfma_f32_32x32x16_bf16 v[66:81], v[180:183], v[146:149], v[66:81]
	v_mfma_f32_32x32x16_bf16 v[98:113], v[186:189], v[134:137], v[98:113]
	v_mfma_f32_32x32x16_bf16 v[66:81], v[186:189], v[150:153], v[66:81]
	v_mfma_f32_32x32x16_bf16 v[98:113], v[190:193], v[138:141], v[98:113]
	v_mfma_f32_32x32x16_bf16 v[66:81], v[190:193], v[154:157], v[66:81]
	v_mfma_f32_32x32x16_bf16 v[98:113], v[194:197], v[142:145], v[98:113]
	v_mfma_f32_32x32x16_bf16 v[66:81], v[194:197], v[158:161], v[66:81]
	s_barrier
	v_add3_u32 v242, v240, v236, s10
	v_add3_u32 v243, v240, v237, s10
	v_add3_u32 v244, v240, v238, s10
	v_add3_u32 v245, v240, v239, s10
	ds_read_b128 v[130:133], v242 offset:16384
	ds_read_b128 v[134:137], v243 offset:16384
	ds_read_b128 v[138:141], v244 offset:16384
	ds_read_b128 v[142:145], v245 offset:16384
	ds_read_b128 v[146:149], v242 offset:20480
	ds_read_b128 v[150:153], v243 offset:20480
	ds_read_b128 v[154:157], v244 offset:20480
	ds_read_b128 v[158:161], v245 offset:20480
	s_barrier
	s_waitcnt lgkmcnt(0)
	v_mfma_f32_32x32x16_bf16 v[50:65], v[162:165], v[130:133], v[50:65]
	v_mfma_f32_32x32x16_bf16 v[18:33], v[162:165], v[146:149], v[18:33]
	v_mfma_f32_32x32x16_bf16 v[50:65], v[166:169], v[134:137], v[50:65]
	v_mfma_f32_32x32x16_bf16 v[18:33], v[166:169], v[150:153], v[18:33]
	v_mfma_f32_32x32x16_bf16 v[50:65], v[170:173], v[138:141], v[50:65]
	v_mfma_f32_32x32x16_bf16 v[18:33], v[170:173], v[154:157], v[18:33]
	v_mfma_f32_32x32x16_bf16 v[50:65], v[174:177], v[142:145], v[50:65]
	v_mfma_f32_32x32x16_bf16 v[18:33], v[174:177], v[158:161], v[18:33]
	v_mfma_f32_32x32x16_bf16 v[34:49], v[180:183], v[130:133], v[34:49]
	v_mfma_f32_32x32x16_bf16 v[2:17], v[180:183], v[146:149], v[2:17]
	v_mfma_f32_32x32x16_bf16 v[34:49], v[186:189], v[134:137], v[34:49]
	v_mfma_f32_32x32x16_bf16 v[2:17], v[186:189], v[150:153], v[2:17]
	v_mfma_f32_32x32x16_bf16 v[34:49], v[190:193], v[138:141], v[34:49]
	v_mfma_f32_32x32x16_bf16 v[2:17], v[190:193], v[154:157], v[2:17]
	v_mfma_f32_32x32x16_bf16 v[34:49], v[194:197], v[142:145], v[34:49]
	v_mfma_f32_32x32x16_bf16 v[2:17], v[194:197], v[158:161], v[2:17]
	s_barrier
	s_cmp_eq_u32 s101, 0
	s_cbranch_scc0 .Lg8_m246_p1
	s_barrier

; template <bool SWAP>
; DI void gemm_mainloop(f32x16 (&acc)[4][2], const u16* __restrict__ A, int lda, int rlo, int rhi,
;                       const u16* __restrict__ B, int ldb, int K, char* lds, const u16* zero_line) {
;     ...
; #pragma unroll 2
;   for (int kt = 0; kt < nk; ++kt) {
;     const char* st = lds + (kt & 1) * 65536;
;     ldfrag(st, 0, 0);
;     mma(1);
;     pat_rd();
;     if (kt + 1 < nk) glds(kt + 1, (kt + 1) & 1);
;     ldfrag(st, 1, 1);
;     mma(0);
;     pat_rd();
;     ldfrag(st, 2, 0);
;     mma(1);
;     pat_rd();
;     ldfrag(st, 3, 1);
;     mma(0);
;     pat_rd();
;     asm volatile("s_waitcnt vmcnt(0)" ::: "memory");
;     __syncthreads();
;   }
.Lg8_ia:
	v_add3_u32 v187, v166, v161, 0
	v_add3_u32 v248, v166, v163, 0
	ds_read_b128 v[130:133], v187
	ds_read_b128 v[134:137], v248
	ds_read_b128 v[146:149], v187 offset:4096
	ds_read_b128 v[150:153], v248 offset:4096
	v_add3_u32 v187, v166, v164, 0
	v_add3_u32 v248, v166, v165, 0
	ds_read_b128 v[138:141], v187
	ds_read_b128 v[142:145], v248
	ds_read_b128 v[168:171], v187 offset:4096
	ds_read_b128 v[172:175], v248 offset:4096
	s_add_u32 m0, s100, 0x14000
	s_nop 0
	global_load_lds_dwordx4 v241, s[6:7]
	v_add_u32_e32 v241, 0x80, v241
	s_add_u32 m0, s100, 0x16000
	s_nop 0
	global_load_lds_dwordx4 v243, s[6:7]
	v_add_u32_e32 v243, 0x80, v243
	s_barrier
	s_waitcnt lgkmcnt(0)
	s_setprio 1
	v_mfma_f32_32x32x16_bf16 v[114:129], v[176:179], v[130:133], v[114:129]
	v_mfma_f32_32x32x16_bf16 v[98:113], v[176:179], v[146:149], v[98:113]
	v_mfma_f32_32x32x16_bf16 v[114:129], v[180:183], v[134:137], v[114:129]
	v_mfma_f32_32x32x16_bf16 v[98:113], v[180:183], v[150:153], v[98:113]
	v_mfma_f32_32x32x16_bf16 v[114:129], v[192:195], v[138:141], v[114:129]
	v_mfma_f32_32x32x16_bf16 v[98:113], v[192:195], v[168:171], v[98:113]
	v_mfma_f32_32x32x16_bf16 v[114:129], v[196:199], v[142:145], v[114:129]
	v_mfma_f32_32x32x16_bf16 v[98:113], v[196:199], v[172:175], v[98:113]
	s_setprio 0
	s_barrier
	v_add3_u32 v187, v186, v161, 0
	v_add3_u32 v248, v186, v163, 0
	ds_read_b128 v[200:203], v187 offset:49152
	ds_read_b128 v[228:231], v248 offset:49152
	v_add3_u32 v187, v186, v164, 0
	v_add3_u32 v248, v186, v165, 0
	ds_read_b128 v[232:235], v187 offset:49152
	ds_read_b128 v[236:239], v248 offset:49152
	s_add_u32 m0, s100, 0x8000
	s_nop 0
	global_load_lds_dwordx4 v244, s[8:9]
	v_add_u32_e32 v244, 0x80, v244
	s_add_u32 m0, s100, 0xa000
	s_nop 0
	global_load_lds_dwordx4 v246, s[8:9]
	v_add_u32_e32 v246, 0x80, v246
	s_barrier
	s_waitcnt lgkmcnt(0)
	s_setprio 1
	v_mfma_f32_32x32x16_bf16 v[82:97], v[200:203], v[130:133], v[82:97]
	v_mfma_f32_32x32x16_bf16 v[50:65], v[200:203], v[146:149], v[50:65]
	v_mfma_f32_32x32x16_bf16 v[82:97], v[228:231], v[134:137], v[82:97]
	v_mfma_f32_32x32x16_bf16 v[50:65], v[228:231], v[150:153], v[50:65]
	v_mfma_f32_32x32x16_bf16 v[82:97], v[232:235], v[138:141], v[82:97]
	v_mfma_f32_32x32x16_bf16 v[50:65], v[232:235], v[168:171], v[50:65]
	v_mfma_f32_32x32x16_bf16 v[82:97], v[236:239], v[142:145], v[82:97]
	v_mfma_f32_32x32x16_bf16 v[50:65], v[236:239], v[172:175], v[50:65]
	s_setprio 0
	s_barrier
	v_add3_u32 v187, v166, v161, 0
	v_add3_u32 v248, v166, v163, 0
	ds_read_b128 v[130:133], v187 offset:16384
	ds_read_b128 v[134:137], v248 offset:16384
	ds_read_b128 v[146:149], v187 offset:20480
	ds_read_b128 v[150:153], v248 offset:20480
	v_add3_u32 v187, v166, v164, 0
	v_add3_u32 v248, v166, v165, 0
	ds_read_b128 v[138:141], v187 offset:16384
	ds_read_b128 v[142:145], v248 offset:16384
	ds_read_b128 v[168:171], v187 offset:20480
	ds_read_b128 v[172:175], v248 offset:20480
	s_add_u32 m0, s100, 0x0
	s_nop 0
	global_load_lds_dwordx4 v240, s[6:7]
	v_add_u32_e32 v240, 0x80, v240
	s_add_u32 m0, s100, 0x2000
	s_nop 0
	global_load_lds_dwordx4 v242, s[6:7]
	v_add_u32_e32 v242, 0x80, v242
	s_waitcnt vmcnt(10)
	s_barrier
	s_waitcnt lgkmcnt(0)
	s_setprio 1
	v_mfma_f32_32x32x16_bf16 v[66:81], v[176:179], v[130:133], v[66:81]
	v_mfma_f32_32x32x16_bf16 v[34:49], v[176:179], v[146:149], v[34:49]
	v_mfma_f32_32x32x16_bf16 v[66:81], v[180:183], v[134:137], v[66:81]
	v_mfma_f32_32x32x16_bf16 v[34:49], v[180:183], v[150:153], v[34:49]
	v_mfma_f32_32x32x16_bf16 v[66:81], v[192:195], v[138:141], v[66:81]
	v_mfma_f32_32x32x16_bf16 v[34:49], v[192:195], v[168:171], v[34:49]
	v_mfma_f32_32x32x16_bf16 v[66:81], v[196:199], v[142:145], v[66:81]
	v_mfma_f32_32x32x16_bf16 v[34:49], v[196:199], v[172:175], v[34:49]
	s_setprio 0
	s_barrier
	v_add3_u32 v187, v186, v161, s10
	v_add3_u32 v248, v186, v163, s10
	ds_read_b128 v[176:179], v187 offset:32768
	ds_read_b128 v[180:183], v248 offset:32768
	v_add3_u32 v187, v186, v164, s10
	v_add3_u32 v248, v186, v165, s10
	ds_read_b128 v[192:195], v187 offset:32768
	ds_read_b128 v[196:199], v248 offset:32768
	s_add_u32 m0, s100, 0xc000
	s_nop 0
	global_load_lds_dwordx4 v245, s[8:9]
	v_add_u32_e32 v245, 0x80, v245
	s_add_u32 m0, s100, 0xe000
	s_nop 0
	global_load_lds_dwordx4 v247, s[8:9]
	v_add_u32_e32 v247, 0x80, v247
	s_waitcnt vmcnt(6)
	s_barrier
	s_waitcnt lgkmcnt(0)
	s_setprio 1
	v_mfma_f32_32x32x16_bf16 v[18:33], v[200:203], v[130:133], v[18:33]
	v_mfma_f32_32x32x16_bf16 v[2:17], v[200:203], v[146:149], v[2:17]
	v_mfma_f32_32x32x16_bf16 v[18:33], v[228:231], v[134:137], v[18:33]
	v_mfma_f32_32x32x16_bf16 v[2:17], v[228:231], v[150:153], v[2:17]
	v_mfma_f32_32x32x16_bf16 v[18:33], v[232:235], v[138:141], v[18:33]
	v_mfma_f32_32x32x16_bf16 v[2:17], v[232:235], v[168:171], v[2:17]
	v_mfma_f32_32x32x16_bf16 v[18:33], v[236:239], v[142:145], v[18:33]
	v_mfma_f32_32x32x16_bf16 v[2:17], v[236:239], v[172:175], v[2:17]
	s_setprio 0
	s_barrier
	v_add3_u32 v187, v166, v161, s10
	v_add3_u32 v248, v166, v163, s10
	ds_read_b128 v[130:133], v187
	ds_read_b128 v[134:137], v248
	ds_read_b128 v[146:149], v187 offset:4096
	ds_read_b128 v[150:153], v248 offset:4096
	v_add3_u32 v187, v166, v164, s10
	v_add3_u32 v248, v166, v165, s10
	ds_read_b128 v[138:141], v187
	ds_read_b128 v[142:145], v248
	ds_read_b128 v[168:171], v187 offset:4096
	ds_read_b128 v[172:175], v248 offset:4096
	s_add_u32 m0, s100, 0x4000
	s_nop 0
	global_load_lds_dwordx4 v241, s[6:7]
	v_add_u32_e32 v241, 0x80, v241
	s_add_u32 m0, s100, 0x6000
	s_nop 0
	global_load_lds_dwordx4 v243, s[6:7]
	v_add_u32_e32 v243, 0x80, v243
	s_barrier
; template <bool SWAP>
; DI void gemm_mainloop(f32x16 (&acc)[4][2], const u16* __restrict__ A, int lda, int rlo, int rhi,
;                       const u16* __restrict__ B, int ldb, int K, char* lds, const u16* zero_line) {
;     ...
; #pragma unroll 2
;   for (int kt = 0; kt < nk; ++kt) {
;     const char* st = lds + (kt & 1) * 65536;
;     ldfrag(st, 0, 0);
;     mma(1);
;     pat_rd();
;     if (kt + 1 < nk) glds(kt + 1, (kt + 1) & 1);
;     ldfrag(st, 1, 1);
;     mma(0);
;     pat_rd();
;     ldfrag(st, 2, 0);
;     mma(1);
;     pat_rd();
;     ldfrag(st, 3, 1);
;     mma(0);
;     pat_rd();
;     asm volatile("s_waitcnt vmcnt(0)" ::: "memory");
;     __syncthreads();
;   }
	s_waitcnt lgkmcnt(0)
	s_setprio 1
	v_mfma_f32_32x32x16_bf16 v[114:129], v[176:179], v[130:133], v[114:129]
	v_mfma_f32_32x32x16_bf16 v[98:113], v[176:179], v[146:149], v[98:113]
	v_mfma_f32_32x32x16_bf16 v[114:129], v[180:183], v[134:137], v[114:129]
	v_mfma_f32_32x32x16_bf16 v[98:113], v[180:183], v[150:153], v[98:113]
	v_mfma_f32_32x32x16_bf16 v[114:129], v[192:195], v[138:141], v[114:129]
	v_mfma_f32_32x32x16_bf16 v[98:113], v[192:195], v[168:171], v[98:113]
	v_mfma_f32_32x32x16_bf16 v[114:129], v[196:199], v[142:145], v[114:129]
	v_mfma_f32_32x32x16_bf16 v[98:113], v[196:199], v[172:175], v[98:113]
	s_setprio 0
	s_barrier
	v_add3_u32 v187, v186, v161, s10
	v_add3_u32 v248, v186, v163, s10
	ds_read_b128 v[200:203], v187 offset:49152
	ds_read_b128 v[228:231], v248 offset:49152
	v_add3_u32 v187, v186, v164, s10
	v_add3_u32 v248, v186, v165, s10
	ds_read_b128 v[232:235], v187 offset:49152
	ds_read_b128 v[236:239], v248 offset:49152
	s_add_u32 m0, s100, 0x18000
	s_nop 0
	global_load_lds_dwordx4 v244, s[8:9]
	v_add_u32_e32 v244, 0x80, v244
	s_add_u32 m0, s100, 0x1a000
	s_nop 0
	global_load_lds_dwordx4 v246, s[8:9]
	v_add_u32_e32 v246, 0x80, v246
	s_barrier
	s_waitcnt lgkmcnt(0)
	s_setprio 1
	v_mfma_f32_32x32x16_bf16 v[82:97], v[200:203], v[130:133], v[82:97]
	v_mfma_f32_32x32x16_bf16 v[50:65], v[200:203], v[146:149], v[50:65]
	v_mfma_f32_32x32x16_bf16 v[82:97], v[228:231], v[134:137], v[82:97]
	v_mfma_f32_32x32x16_bf16 v[50:65], v[228:231], v[150:153], v[50:65]
	v_mfma_f32_32x32x16_bf16 v[82:97], v[232:235], v[138:141], v[82:97]
	v_mfma_f32_32x32x16_bf16 v[50:65], v[232:235], v[168:171], v[50:65]
	v_mfma_f32_32x32x16_bf16 v[82:97], v[236:239], v[142:145], v[82:97]
	v_mfma_f32_32x32x16_bf16 v[50:65], v[236:239], v[172:175], v[50:65]
	s_setprio 0
	s_barrier
	v_add3_u32 v187, v166, v161, s10
	v_add3_u32 v248, v166, v163, s10
	ds_read_b128 v[130:133], v187 offset:16384
	ds_read_b128 v[134:137], v248 offset:16384
	ds_read_b128 v[146:149], v187 offset:20480
	ds_read_b128 v[150:153], v248 offset:20480
	v_add3_u32 v187, v166, v164, s10
	v_add3_u32 v248, v166, v165, s10
	ds_read_b128 v[138:141], v187 offset:16384
	ds_read_b128 v[142:145], v248 offset:16384
	ds_read_b128 v[168:171], v187 offset:20480
	ds_read_b128 v[172:175], v248 offset:20480
	s_add_u32 m0, s100, 0x10000
	s_nop 0
	global_load_lds_dwordx4 v240, s[6:7]
	v_add_u32_e32 v240, 0x80, v240
	s_add_u32 m0, s100, 0x12000
	s_nop 0
	global_load_lds_dwordx4 v242, s[6:7]
	v_add_u32_e32 v242, 0x80, v242
	s_waitcnt vmcnt(10)
	s_barrier
	s_waitcnt lgkmcnt(0)
	s_setprio 1
	v_mfma_f32_32x32x16_bf16 v[66:81], v[176:179], v[130:133], v[66:81]
	v_mfma_f32_32x32x16_bf16 v[34:49], v[176:179], v[146:149], v[34:49]
	v_mfma_f32_32x32x16_bf16 v[66:81], v[180:183], v[134:137], v[66:81]
	v_mfma_f32_32x32x16_bf16 v[34:49], v[180:183], v[150:153], v[34:49]
	v_mfma_f32_32x32x16_bf16 v[66:81], v[192:195], v[138:141], v[66:81]
	v_mfma_f32_32x32x16_bf16 v[34:49], v[192:195], v[168:171], v[34:49]
	v_mfma_f32_32x32x16_bf16 v[66:81], v[196:199], v[142:145], v[66:81]
	v_mfma_f32_32x32x16_bf16 v[34:49], v[196:199], v[172:175], v[34:49]
	s_setprio 0
	s_barrier
	v_add3_u32 v187, v186, v161, 0
	v_add3_u32 v248, v186, v163, 0
	ds_read_b128 v[176:179], v187 offset:32768
	ds_read_b128 v[180:183], v248 offset:32768
	v_add3_u32 v187, v186, v164, 0
	v_add3_u32 v248, v186, v165, 0
	ds_read_b128 v[192:195], v187 offset:32768
	ds_read_b128 v[196:199], v248 offset:32768
	s_add_u32 m0, s100, 0x1c000
	s_nop 0
	global_load_lds_dwordx4 v245, s[8:9]
	v_add_u32_e32 v245, 0x80, v245
	s_add_u32 m0, s100, 0x1e000
	s_nop 0
	global_load_lds_dwordx4 v247, s[8:9]
	v_add_u32_e32 v247, 0x80, v247
	s_waitcnt vmcnt(6)
	s_barrier
	s_waitcnt lgkmcnt(0)
	s_setprio 1
	v_mfma_f32_32x32x16_bf16 v[18:33], v[200:203], v[130:133], v[18:33]
	v_mfma_f32_32x32x16_bf16 v[2:17], v[200:203], v[146:149], v[2:17]
	v_mfma_f32_32x32x16_bf16 v[18:33], v[228:231], v[134:137], v[18:33]
	v_mfma_f32_32x32x16_bf16 v[2:17], v[228:231], v[150:153], v[2:17]
	v_mfma_f32_32x32x16_bf16 v[18:33], v[232:235], v[138:141], v[18:33]
	v_mfma_f32_32x32x16_bf16 v[2:17], v[232:235], v[168:171], v[2:17]
	v_mfma_f32_32x32x16_bf16 v[18:33], v[236:239], v[142:145], v[18:33]
	v_mfma_f32_32x32x16_bf16 v[2:17], v[236:239], v[172:175], v[2:17]
	s_setprio 0
	s_barrier
	s_add_i32 s11, s11, 2
	s_cmp_lt_u32 s11, 14
	s_cbranch_scc1 .Lg8_ia
	v_add3_u32 v187, v166, v161, 0
	v_add3_u32 v248, v166, v163, 0
	ds_read_b128 v[130:133], v187
	ds_read_b128 v[134:137], v248
	ds_read_b128 v[146:149], v187 offset:4096
	ds_read_b128 v[150:153], v248 offset:4096
	v_add3_u32 v187, v166, v164, 0
	v_add3_u32 v248, v166, v165, 0
	ds_read_b128 v[138:141], v187
	ds_read_b128 v[142:145], v248
	ds_read_b128 v[168:171], v187 offset:4096
	ds_read_b128 v[172:175], v248 offset:4096
	s_add_u32 m0, s100, 0x14000
	s_nop 0
	global_load_lds_dwordx4 v241, s[6:7]
	v_add_u32_e32 v241, 0x80, v241
	s_add_u32 m0, s100, 0x16000
	s_nop 0
	global_load_lds_dwordx4 v243, s[6:7]
	v_add_u32_e32 v243, 0x80, v243
	s_barrier
	s_waitcnt lgkmcnt(0)
	v_mfma_f32_32x32x16_bf16 v[114:129], v[176:179], v[130:133], v[114:129]
	v_mfma_f32_32x32x16_bf16 v[98:113], v[176:179], v[146:149], v[98:113]
	v_mfma_f32_32x32x16_bf16 v[114:129], v[180:183], v[134:137], v[114:129]
	v_mfma_f32_32x32x16_bf16 v[98:113], v[180:183], v[150:153], v[98:113]
	v_mfma_f32_32x32x16_bf16 v[114:129], v[192:195], v[138:141], v[114:129]
	v_mfma_f32_32x32x16_bf16 v[98:113], v[192:195], v[168:171], v[98:113]
	v_mfma_f32_32x32x16_bf16 v[114:129], v[196:199], v[142:145], v[114:129]
	v_mfma_f32_32x32x16_bf16 v[98:113], v[196:199], v[172:175], v[98:113]
	s_barrier
; template <bool SWAP>
; DI void gemm_mainloop(f32x16 (&acc)[4][2], const u16* __restrict__ A, int lda, int rlo, int rhi,
;                       const u16* __restrict__ B, int ldb, int K, char* lds, const u16* zero_line) {
;     ...
; #pragma unroll 2
;   for (int kt = 0; kt < nk; ++kt) {
;     const char* st = lds + (kt & 1) * 65536;
;     ldfrag(st, 0, 0);
;     mma(1);
;     pat_rd();
;     if (kt + 1 < nk) glds(kt + 1, (kt + 1) & 1);
;     ldfrag(st, 1, 1);
;     mma(0);
;     pat_rd();
;     ldfrag(st, 2, 0);
;     mma(1);
;     pat_rd();
;     ldfrag(st, 3, 1);
;     mma(0);
;     pat_rd();
;     asm volatile("s_waitcnt vmcnt(0)" ::: "memory");
;     __syncthreads();
;   }
;   mma(1);
	v_add3_u32 v187, v186, v161, 0
	v_add3_u32 v248, v186, v163, 0
	ds_read_b128 v[200:203], v187 offset:49152
	ds_read_b128 v[228:231], v248 offset:49152
	v_add3_u32 v187, v186, v164, 0
	v_add3_u32 v248, v186, v165, 0
	ds_read_b128 v[232:235], v187 offset:49152
	ds_read_b128 v[236:239], v248 offset:49152
	s_barrier
	s_waitcnt lgkmcnt(0)
	v_mfma_f32_32x32x16_bf16 v[82:97], v[200:203], v[130:133], v[82:97]
	v_mfma_f32_32x32x16_bf16 v[50:65], v[200:203], v[146:149], v[50:65]
	v_mfma_f32_32x32x16_bf16 v[82:97], v[228:231], v[134:137], v[82:97]
	v_mfma_f32_32x32x16_bf16 v[50:65], v[228:231], v[150:153], v[50:65]
	v_mfma_f32_32x32x16_bf16 v[82:97], v[232:235], v[138:141], v[82:97]
	v_mfma_f32_32x32x16_bf16 v[50:65], v[232:235], v[168:171], v[50:65]
	v_mfma_f32_32x32x16_bf16 v[82:97], v[236:239], v[142:145], v[82:97]
	v_mfma_f32_32x32x16_bf16 v[50:65], v[236:239], v[172:175], v[50:65]
	s_barrier
	v_add3_u32 v187, v166, v161, 0
	v_add3_u32 v248, v166, v163, 0
	ds_read_b128 v[130:133], v187 offset:16384
	ds_read_b128 v[134:137], v248 offset:16384
	ds_read_b128 v[146:149], v187 offset:20480
	ds_read_b128 v[150:153], v248 offset:20480
	v_add3_u32 v187, v166, v164, 0
	v_add3_u32 v248, v166, v165, 0
	ds_read_b128 v[138:141], v187 offset:16384
	ds_read_b128 v[142:145], v248 offset:16384
	ds_read_b128 v[168:171], v187 offset:20480
	ds_read_b128 v[172:175], v248 offset:20480
	s_waitcnt vmcnt(4)
	s_barrier
	s_waitcnt lgkmcnt(0)
	v_mfma_f32_32x32x16_bf16 v[66:81], v[176:179], v[130:133], v[66:81]
	v_mfma_f32_32x32x16_bf16 v[34:49], v[176:179], v[146:149], v[34:49]
	v_mfma_f32_32x32x16_bf16 v[66:81], v[180:183], v[134:137], v[66:81]
	v_mfma_f32_32x32x16_bf16 v[34:49], v[180:183], v[150:153], v[34:49]
	v_mfma_f32_32x32x16_bf16 v[66:81], v[192:195], v[138:141], v[66:81]
	v_mfma_f32_32x32x16_bf16 v[34:49], v[192:195], v[168:171], v[34:49]
	v_mfma_f32_32x32x16_bf16 v[66:81], v[196:199], v[142:145], v[66:81]
	v_mfma_f32_32x32x16_bf16 v[34:49], v[196:199], v[172:175], v[34:49]
	v_mfma_f32_32x32x16_bf16 v[18:33], v[200:203], v[130:133], v[18:33]
	v_mfma_f32_32x32x16_bf16 v[2:17], v[200:203], v[146:149], v[2:17]
	v_mfma_f32_32x32x16_bf16 v[18:33], v[228:231], v[134:137], v[18:33]
	v_mfma_f32_32x32x16_bf16 v[2:17], v[228:231], v[150:153], v[2:17]
	v_mfma_f32_32x32x16_bf16 v[18:33], v[232:235], v[138:141], v[18:33]
	v_mfma_f32_32x32x16_bf16 v[2:17], v[232:235], v[168:171], v[2:17]
	v_mfma_f32_32x32x16_bf16 v[18:33], v[236:239], v[142:145], v[18:33]
	v_mfma_f32_32x32x16_bf16 v[2:17], v[236:239], v[172:175], v[2:17]
	s_barrier
	v_add3_u32 v187, v186, v161, s10
	v_add3_u32 v248, v186, v163, s10
	ds_read_b128 v[176:179], v187 offset:32768
	ds_read_b128 v[180:183], v248 offset:32768
	v_add3_u32 v187, v186, v164, s10
	v_add3_u32 v248, v186, v165, s10
	ds_read_b128 v[192:195], v187 offset:32768
	ds_read_b128 v[196:199], v248 offset:32768
	v_add3_u32 v187, v166, v161, s10
	v_add3_u32 v248, v166, v163, s10
	ds_read_b128 v[130:133], v187
	ds_read_b128 v[134:137], v248
	ds_read_b128 v[146:149], v187 offset:4096
	ds_read_b128 v[150:153], v248 offset:4096
	v_add3_u32 v187, v166, v164, s10
	v_add3_u32 v248, v166, v165, s10
	ds_read_b128 v[138:141], v187
	ds_read_b128 v[142:145], v248
	ds_read_b128 v[168:171], v187 offset:4096
	ds_read_b128 v[172:175], v248 offset:4096
	s_waitcnt vmcnt(2)
	s_barrier
	s_waitcnt lgkmcnt(0)
	v_mfma_f32_32x32x16_bf16 v[114:129], v[176:179], v[130:133], v[114:129]
	v_mfma_f32_32x32x16_bf16 v[98:113], v[176:179], v[146:149], v[98:113]
	v_mfma_f32_32x32x16_bf16 v[114:129], v[180:183], v[134:137], v[114:129]
	v_mfma_f32_32x32x16_bf16 v[98:113], v[180:183], v[150:153], v[98:113]
	v_mfma_f32_32x32x16_bf16 v[114:129], v[192:195], v[138:141], v[114:129]
	v_mfma_f32_32x32x16_bf16 v[98:113], v[192:195], v[168:171], v[98:113]
	v_mfma_f32_32x32x16_bf16 v[114:129], v[196:199], v[142:145], v[114:129]
	v_mfma_f32_32x32x16_bf16 v[98:113], v[196:199], v[172:175], v[98:113]
	s_barrier
	v_add3_u32 v187, v186, v161, s10
	v_add3_u32 v248, v186, v163, s10
	ds_read_b128 v[200:203], v187 offset:49152
	ds_read_b128 v[228:231], v248 offset:49152
	v_add3_u32 v187, v186, v164, s10
	v_add3_u32 v248, v186, v165, s10
	ds_read_b128 v[232:235], v187 offset:49152
	ds_read_b128 v[236:239], v248 offset:49152
	s_waitcnt vmcnt(0)
	s_barrier
	s_waitcnt lgkmcnt(0)
	v_mfma_f32_32x32x16_bf16 v[82:97], v[200:203], v[130:133], v[82:97]
	v_mfma_f32_32x32x16_bf16 v[50:65], v[200:203], v[146:149], v[50:65]
	v_mfma_f32_32x32x16_bf16 v[82:97], v[228:231], v[134:137], v[82:97]
	v_mfma_f32_32x32x16_bf16 v[50:65], v[228:231], v[150:153], v[50:65]
	v_mfma_f32_32x32x16_bf16 v[82:97], v[232:235], v[138:141], v[82:97]
	v_mfma_f32_32x32x16_bf16 v[50:65], v[232:235], v[168:171], v[50:65]
	v_mfma_f32_32x32x16_bf16 v[82:97], v[236:239], v[142:145], v[82:97]
	v_mfma_f32_32x32x16_bf16 v[50:65], v[236:239], v[172:175], v[50:65]
	s_barrier
	v_add3_u32 v187, v166, v161, s10
	v_add3_u32 v248, v166, v163, s10
	ds_read_b128 v[130:133], v187 offset:16384
	ds_read_b128 v[134:137], v248 offset:16384
	ds_read_b128 v[146:149], v187 offset:20480
	ds_read_b128 v[150:153], v248 offset:20480
	v_add3_u32 v187, v166, v164, s10
	v_add3_u32 v248, v166, v165, s10
	ds_read_b128 v[138:141], v187 offset:16384
	ds_read_b128 v[142:145], v248 offset:16384
	ds_read_b128 v[168:171], v187 offset:20480
	ds_read_b128 v[172:175], v248 offset:20480
	s_barrier
	s_waitcnt lgkmcnt(0)
	v_mfma_f32_32x32x16_bf16 v[66:81], v[176:179], v[130:133], v[66:81]
	v_mfma_f32_32x32x16_bf16 v[34:49], v[176:179], v[146:149], v[34:49]
	v_mfma_f32_32x32x16_bf16 v[66:81], v[180:183], v[134:137], v[66:81]
	v_mfma_f32_32x32x16_bf16 v[34:49], v[180:183], v[150:153], v[34:49]
	v_mfma_f32_32x32x16_bf16 v[66:81], v[192:195], v[138:141], v[66:81]
	v_mfma_f32_32x32x16_bf16 v[34:49], v[192:195], v[168:171], v[34:49]
	v_mfma_f32_32x32x16_bf16 v[66:81], v[196:199], v[142:145], v[66:81]
	v_mfma_f32_32x32x16_bf16 v[34:49], v[196:199], v[172:175], v[34:49]
	v_mfma_f32_32x32x16_bf16 v[18:33], v[200:203], v[130:133], v[18:33]
	v_mfma_f32_32x32x16_bf16 v[2:17], v[200:203], v[146:149], v[2:17]
	v_mfma_f32_32x32x16_bf16 v[18:33], v[228:231], v[134:137], v[18:33]
	v_mfma_f32_32x32x16_bf16 v[2:17], v[228:231], v[150:153], v[2:17]
	v_mfma_f32_32x32x16_bf16 v[18:33], v[232:235], v[138:141], v[18:33]
	v_mfma_f32_32x32x16_bf16 v[2:17], v[232:235], v[168:171], v[2:17]
	v_mfma_f32_32x32x16_bf16 v[18:33], v[236:239], v[142:145], v[18:33]
	v_mfma_f32_32x32x16_bf16 v[2:17], v[236:239], v[172:175], v[2:17]
	s_barrier
	s_cmp_eq_u32 s101, 0
	s_cbranch_scc0 .Lg8_ia_p1
	s_barrier

; template <bool SWAP>
; DI void gemm_mainloop(f32x16 (&acc)[4][2], const u16* __restrict__ A, int lda, int rlo, int rhi,
;                       const u16* __restrict__ B, int ldb, int K, char* lds, const u16* zero_line) {
;     ...
; #pragma unroll 2
;   for (int kt = 0; kt < nk; ++kt) {
;     const char* st = lds + (kt & 1) * 65536;
;     ldfrag(st, 0, 0);
;     mma(1);
;     pat_rd();
;     if (kt + 1 < nk) glds(kt + 1, (kt + 1) & 1);
;     ldfrag(st, 1, 1);
;     mma(0);
;     pat_rd();
;     ldfrag(st, 2, 0);
;     mma(1);
;     pat_rd();
;     ldfrag(st, 3, 1);
;     mma(0);
;     pat_rd();
;     asm volatile("s_waitcnt vmcnt(0)" ::: "memory");
;     __syncthreads();
;   }
.Lg8_ib:
	v_add3_u32 v187, v166, v161, 0
	v_add3_u32 v248, v166, v163, 0
	ds_read_b128 v[130:133], v187
	ds_read_b128 v[134:137], v248
	ds_read_b128 v[146:149], v187 offset:4096
	ds_read_b128 v[150:153], v248 offset:4096
	v_add3_u32 v187, v166, v164, 0
	v_add3_u32 v248, v166, v165, 0
	ds_read_b128 v[138:141], v187
	ds_read_b128 v[142:145], v248
	ds_read_b128 v[168:171], v187 offset:4096
	ds_read_b128 v[172:175], v248 offset:4096
	s_add_u32 m0, s100, 0x14000
	s_nop 0
	global_load_lds_dwordx4 v241, s[6:7]
	v_add_u32_e32 v241, 0x80, v241
	s_add_u32 m0, s100, 0x16000
	s_nop 0
	global_load_lds_dwordx4 v243, s[6:7]
	v_add_u32_e32 v243, 0x80, v243
	s_barrier
	s_waitcnt lgkmcnt(0)
	s_setprio 1
	v_mfma_f32_32x32x16_bf16 v[114:129], v[130:133], v[176:179], v[114:129]
	v_mfma_f32_32x32x16_bf16 v[98:113], v[146:149], v[176:179], v[98:113]
	v_mfma_f32_32x32x16_bf16 v[114:129], v[134:137], v[180:183], v[114:129]
	v_mfma_f32_32x32x16_bf16 v[98:113], v[150:153], v[180:183], v[98:113]
	v_mfma_f32_32x32x16_bf16 v[114:129], v[138:141], v[192:195], v[114:129]
	v_mfma_f32_32x32x16_bf16 v[98:113], v[168:171], v[192:195], v[98:113]
	v_mfma_f32_32x32x16_bf16 v[114:129], v[142:145], v[196:199], v[114:129]
	v_mfma_f32_32x32x16_bf16 v[98:113], v[172:175], v[196:199], v[98:113]
	s_setprio 0
	s_barrier
	v_add3_u32 v187, v186, v161, 0
	v_add3_u32 v248, v186, v163, 0
	ds_read_b128 v[200:203], v187 offset:49152
	ds_read_b128 v[228:231], v248 offset:49152
	v_add3_u32 v187, v186, v164, 0
	v_add3_u32 v248, v186, v165, 0
	ds_read_b128 v[232:235], v187 offset:49152
	ds_read_b128 v[236:239], v248 offset:49152
	s_add_u32 m0, s100, 0x8000
	s_nop 0
	global_load_lds_dwordx4 v244, s[8:9]
	v_add_u32_e32 v244, 0x80, v244
	s_add_u32 m0, s100, 0xa000
	s_nop 0
	global_load_lds_dwordx4 v246, s[8:9]
	v_add_u32_e32 v246, 0x80, v246
	s_barrier
	s_waitcnt lgkmcnt(0)
	s_setprio 1
	v_mfma_f32_32x32x16_bf16 v[82:97], v[130:133], v[200:203], v[82:97]
	v_mfma_f32_32x32x16_bf16 v[50:65], v[146:149], v[200:203], v[50:65]
	v_mfma_f32_32x32x16_bf16 v[82:97], v[134:137], v[228:231], v[82:97]
	v_mfma_f32_32x32x16_bf16 v[50:65], v[150:153], v[228:231], v[50:65]
	v_mfma_f32_32x32x16_bf16 v[82:97], v[138:141], v[232:235], v[82:97]
	v_mfma_f32_32x32x16_bf16 v[50:65], v[168:171], v[232:235], v[50:65]
	v_mfma_f32_32x32x16_bf16 v[82:97], v[142:145], v[236:239], v[82:97]
	v_mfma_f32_32x32x16_bf16 v[50:65], v[172:175], v[236:239], v[50:65]
	s_setprio 0
	s_barrier
	v_add3_u32 v187, v166, v161, 0
	v_add3_u32 v248, v166, v163, 0
	ds_read_b128 v[130:133], v187 offset:16384
	ds_read_b128 v[134:137], v248 offset:16384
	ds_read_b128 v[146:149], v187 offset:20480
	ds_read_b128 v[150:153], v248 offset:20480
	v_add3_u32 v187, v166, v164, 0
	v_add3_u32 v248, v166, v165, 0
	ds_read_b128 v[138:141], v187 offset:16384
	ds_read_b128 v[142:145], v248 offset:16384
	ds_read_b128 v[168:171], v187 offset:20480
	ds_read_b128 v[172:175], v248 offset:20480
	s_add_u32 m0, s100, 0x0
	s_nop 0
	global_load_lds_dwordx4 v240, s[6:7]
	v_add_u32_e32 v240, 0x80, v240
	s_add_u32 m0, s100, 0x2000
	s_nop 0
	global_load_lds_dwordx4 v242, s[6:7]
	v_add_u32_e32 v242, 0x80, v242
	s_waitcnt vmcnt(10)
	s_barrier
	s_waitcnt lgkmcnt(0)
	s_setprio 1
	v_mfma_f32_32x32x16_bf16 v[66:81], v[130:133], v[176:179], v[66:81]
	v_mfma_f32_32x32x16_bf16 v[34:49], v[146:149], v[176:179], v[34:49]
	v_mfma_f32_32x32x16_bf16 v[66:81], v[134:137], v[180:183], v[66:81]
	v_mfma_f32_32x32x16_bf16 v[34:49], v[150:153], v[180:183], v[34:49]
	v_mfma_f32_32x32x16_bf16 v[66:81], v[138:141], v[192:195], v[66:81]
	v_mfma_f32_32x32x16_bf16 v[34:49], v[168:171], v[192:195], v[34:49]
	v_mfma_f32_32x32x16_bf16 v[66:81], v[142:145], v[196:199], v[66:81]
	v_mfma_f32_32x32x16_bf16 v[34:49], v[172:175], v[196:199], v[34:49]
	s_setprio 0
	s_barrier
	v_add3_u32 v187, v186, v161, s10
	v_add3_u32 v248, v186, v163, s10
	ds_read_b128 v[176:179], v187 offset:32768
	ds_read_b128 v[180:183], v248 offset:32768
	v_add3_u32 v187, v186, v164, s10
	v_add3_u32 v248, v186, v165, s10
	ds_read_b128 v[192:195], v187 offset:32768
	ds_read_b128 v[196:199], v248 offset:32768
	s_add_u32 m0, s100, 0xc000
	s_nop 0
	global_load_lds_dwordx4 v245, s[8:9]
	v_add_u32_e32 v245, 0x80, v245
	s_add_u32 m0, s100, 0xe000
	s_nop 0
	global_load_lds_dwordx4 v247, s[8:9]
	v_add_u32_e32 v247, 0x80, v247
	s_waitcnt vmcnt(6)
	s_barrier
	s_waitcnt lgkmcnt(0)
	s_setprio 1
	v_mfma_f32_32x32x16_bf16 v[18:33], v[130:133], v[200:203], v[18:33]
	v_mfma_f32_32x32x16_bf16 v[2:17], v[146:149], v[200:203], v[2:17]
	v_mfma_f32_32x32x16_bf16 v[18:33], v[134:137], v[228:231], v[18:33]
	v_mfma_f32_32x32x16_bf16 v[2:17], v[150:153], v[228:231], v[2:17]
	v_mfma_f32_32x32x16_bf16 v[18:33], v[138:141], v[232:235], v[18:33]
	v_mfma_f32_32x32x16_bf16 v[2:17], v[168:171], v[232:235], v[2:17]
	v_mfma_f32_32x32x16_bf16 v[18:33], v[142:145], v[236:239], v[18:33]
	v_mfma_f32_32x32x16_bf16 v[2:17], v[172:175], v[236:239], v[2:17]
	s_setprio 0
	s_barrier
	v_add3_u32 v187, v166, v161, s10
	v_add3_u32 v248, v166, v163, s10
	ds_read_b128 v[130:133], v187
	ds_read_b128 v[134:137], v248
	ds_read_b128 v[146:149], v187 offset:4096
	ds_read_b128 v[150:153], v248 offset:4096
	v_add3_u32 v187, v166, v164, s10
	v_add3_u32 v248, v166, v165, s10
	ds_read_b128 v[138:141], v187
	ds_read_b128 v[142:145], v248
	ds_read_b128 v[168:171], v187 offset:4096
	ds_read_b128 v[172:175], v248 offset:4096
	s_add_u32 m0, s100, 0x4000
	s_nop 0
	global_load_lds_dwordx4 v241, s[6:7]
	v_add_u32_e32 v241, 0x80, v241
	s_add_u32 m0, s100, 0x6000
	s_nop 0
	global_load_lds_dwordx4 v243, s[6:7]
	v_add_u32_e32 v243, 0x80, v243
	s_barrier
; template <bool SWAP>
; DI void gemm_mainloop(f32x16 (&acc)[4][2], const u16* __restrict__ A, int lda, int rlo, int rhi,
;                       const u16* __restrict__ B, int ldb, int K, char* lds, const u16* zero_line) {
;     ...
; #pragma unroll 2
;   for (int kt = 0; kt < nk; ++kt) {
;     const char* st = lds + (kt & 1) * 65536;
;     ldfrag(st, 0, 0);
;     mma(1);
;     pat_rd();
;     if (kt + 1 < nk) glds(kt + 1, (kt + 1) & 1);
;     ldfrag(st, 1, 1);
;     mma(0);
;     pat_rd();
;     ldfrag(st, 2, 0);
;     mma(1);
;     pat_rd();
;     ldfrag(st, 3, 1);
;     mma(0);
;     pat_rd();
;     asm volatile("s_waitcnt vmcnt(0)" ::: "memory");
;     __syncthreads();
;   }
	s_waitcnt lgkmcnt(0)
	s_setprio 1
	v_mfma_f32_32x32x16_bf16 v[114:129], v[130:133], v[176:179], v[114:129]
	v_mfma_f32_32x32x16_bf16 v[98:113], v[146:149], v[176:179], v[98:113]
	v_mfma_f32_32x32x16_bf16 v[114:129], v[134:137], v[180:183], v[114:129]
	v_mfma_f32_32x32x16_bf16 v[98:113], v[150:153], v[180:183], v[98:113]
	v_mfma_f32_32x32x16_bf16 v[114:129], v[138:141], v[192:195], v[114:129]
	v_mfma_f32_32x32x16_bf16 v[98:113], v[168:171], v[192:195], v[98:113]
	v_mfma_f32_32x32x16_bf16 v[114:129], v[142:145], v[196:199], v[114:129]
	v_mfma_f32_32x32x16_bf16 v[98:113], v[172:175], v[196:199], v[98:113]
	s_setprio 0
	s_barrier
	v_add3_u32 v187, v186, v161, s10
	v_add3_u32 v248, v186, v163, s10
	ds_read_b128 v[200:203], v187 offset:49152
	ds_read_b128 v[228:231], v248 offset:49152
	v_add3_u32 v187, v186, v164, s10
	v_add3_u32 v248, v186, v165, s10
	ds_read_b128 v[232:235], v187 offset:49152
	ds_read_b128 v[236:239], v248 offset:49152
	s_add_u32 m0, s100, 0x18000
	s_nop 0
	global_load_lds_dwordx4 v244, s[8:9]
	v_add_u32_e32 v244, 0x80, v244
	s_add_u32 m0, s100, 0x1a000
	s_nop 0
	global_load_lds_dwordx4 v246, s[8:9]
	v_add_u32_e32 v246, 0x80, v246
	s_barrier
	s_waitcnt lgkmcnt(0)
	s_setprio 1
	v_mfma_f32_32x32x16_bf16 v[82:97], v[130:133], v[200:203], v[82:97]
	v_mfma_f32_32x32x16_bf16 v[50:65], v[146:149], v[200:203], v[50:65]
	v_mfma_f32_32x32x16_bf16 v[82:97], v[134:137], v[228:231], v[82:97]
	v_mfma_f32_32x32x16_bf16 v[50:65], v[150:153], v[228:231], v[50:65]
	v_mfma_f32_32x32x16_bf16 v[82:97], v[138:141], v[232:235], v[82:97]
	v_mfma_f32_32x32x16_bf16 v[50:65], v[168:171], v[232:235], v[50:65]
	v_mfma_f32_32x32x16_bf16 v[82:97], v[142:145], v[236:239], v[82:97]
	v_mfma_f32_32x32x16_bf16 v[50:65], v[172:175], v[236:239], v[50:65]
	s_setprio 0
	s_barrier
	v_add3_u32 v187, v166, v161, s10
	v_add3_u32 v248, v166, v163, s10
	ds_read_b128 v[130:133], v187 offset:16384
	ds_read_b128 v[134:137], v248 offset:16384
	ds_read_b128 v[146:149], v187 offset:20480
	ds_read_b128 v[150:153], v248 offset:20480
	v_add3_u32 v187, v166, v164, s10
	v_add3_u32 v248, v166, v165, s10
	ds_read_b128 v[138:141], v187 offset:16384
	ds_read_b128 v[142:145], v248 offset:16384
	ds_read_b128 v[168:171], v187 offset:20480
	ds_read_b128 v[172:175], v248 offset:20480
	s_add_u32 m0, s100, 0x10000
	s_nop 0
	global_load_lds_dwordx4 v240, s[6:7]
	v_add_u32_e32 v240, 0x80, v240
	s_add_u32 m0, s100, 0x12000
	s_nop 0
	global_load_lds_dwordx4 v242, s[6:7]
	v_add_u32_e32 v242, 0x80, v242
	s_waitcnt vmcnt(10)
	s_barrier
	s_waitcnt lgkmcnt(0)
	s_setprio 1
	v_mfma_f32_32x32x16_bf16 v[66:81], v[130:133], v[176:179], v[66:81]
	v_mfma_f32_32x32x16_bf16 v[34:49], v[146:149], v[176:179], v[34:49]
	v_mfma_f32_32x32x16_bf16 v[66:81], v[134:137], v[180:183], v[66:81]
	v_mfma_f32_32x32x16_bf16 v[34:49], v[150:153], v[180:183], v[34:49]
	v_mfma_f32_32x32x16_bf16 v[66:81], v[138:141], v[192:195], v[66:81]
	v_mfma_f32_32x32x16_bf16 v[34:49], v[168:171], v[192:195], v[34:49]
	v_mfma_f32_32x32x16_bf16 v[66:81], v[142:145], v[196:199], v[66:81]
	v_mfma_f32_32x32x16_bf16 v[34:49], v[172:175], v[196:199], v[34:49]
	s_setprio 0
	s_barrier
	v_add3_u32 v187, v186, v161, 0
	v_add3_u32 v248, v186, v163, 0
	ds_read_b128 v[176:179], v187 offset:32768
	ds_read_b128 v[180:183], v248 offset:32768
	v_add3_u32 v187, v186, v164, 0
	v_add3_u32 v248, v186, v165, 0
	ds_read_b128 v[192:195], v187 offset:32768
	ds_read_b128 v[196:199], v248 offset:32768
	s_add_u32 m0, s100, 0x1c000
	s_nop 0
	global_load_lds_dwordx4 v245, s[8:9]
	v_add_u32_e32 v245, 0x80, v245
	s_add_u32 m0, s100, 0x1e000
	s_nop 0
	global_load_lds_dwordx4 v247, s[8:9]
	v_add_u32_e32 v247, 0x80, v247
	s_waitcnt vmcnt(6)
	s_barrier
	s_waitcnt lgkmcnt(0)
	s_setprio 1
	v_mfma_f32_32x32x16_bf16 v[18:33], v[130:133], v[200:203], v[18:33]
	v_mfma_f32_32x32x16_bf16 v[2:17], v[146:149], v[200:203], v[2:17]
	v_mfma_f32_32x32x16_bf16 v[18:33], v[134:137], v[228:231], v[18:33]
	v_mfma_f32_32x32x16_bf16 v[2:17], v[150:153], v[228:231], v[2:17]
	v_mfma_f32_32x32x16_bf16 v[18:33], v[138:141], v[232:235], v[18:33]
	v_mfma_f32_32x32x16_bf16 v[2:17], v[168:171], v[232:235], v[2:17]
	v_mfma_f32_32x32x16_bf16 v[18:33], v[142:145], v[236:239], v[18:33]
	v_mfma_f32_32x32x16_bf16 v[2:17], v[172:175], v[236:239], v[2:17]
	s_setprio 0
	s_barrier
	s_add_i32 s11, s11, 2
	s_cmp_lt_u32 s11, 14
	s_cbranch_scc1 .Lg8_ib
	v_add3_u32 v187, v166, v161, 0
	v_add3_u32 v248, v166, v163, 0
	ds_read_b128 v[130:133], v187
	ds_read_b128 v[134:137], v248
	ds_read_b128 v[146:149], v187 offset:4096
	ds_read_b128 v[150:153], v248 offset:4096
	v_add3_u32 v187, v166, v164, 0
	v_add3_u32 v248, v166, v165, 0
	ds_read_b128 v[138:141], v187
	ds_read_b128 v[142:145], v248
	ds_read_b128 v[168:171], v187 offset:4096
	ds_read_b128 v[172:175], v248 offset:4096
	s_add_u32 m0, s100, 0x14000
	s_nop 0
	global_load_lds_dwordx4 v241, s[6:7]
	v_add_u32_e32 v241, 0x80, v241
	s_add_u32 m0, s100, 0x16000
	s_nop 0
	global_load_lds_dwordx4 v243, s[6:7]
	v_add_u32_e32 v243, 0x80, v243
	s_barrier
	s_waitcnt lgkmcnt(0)
	v_mfma_f32_32x32x16_bf16 v[114:129], v[130:133], v[176:179], v[114:129]
	v_mfma_f32_32x32x16_bf16 v[98:113], v[146:149], v[176:179], v[98:113]
	v_mfma_f32_32x32x16_bf16 v[114:129], v[134:137], v[180:183], v[114:129]
	v_mfma_f32_32x32x16_bf16 v[98:113], v[150:153], v[180:183], v[98:113]
	v_mfma_f32_32x32x16_bf16 v[114:129], v[138:141], v[192:195], v[114:129]
	v_mfma_f32_32x32x16_bf16 v[98:113], v[168:171], v[192:195], v[98:113]
	v_mfma_f32_32x32x16_bf16 v[114:129], v[142:145], v[196:199], v[114:129]
	v_mfma_f32_32x32x16_bf16 v[98:113], v[172:175], v[196:199], v[98:113]
	s_barrier
; template <bool SWAP>
; DI void gemm_mainloop(f32x16 (&acc)[4][2], const u16* __restrict__ A, int lda, int rlo, int rhi,
;                       const u16* __restrict__ B, int ldb, int K, char* lds, const u16* zero_line) {
;     ...
; #pragma unroll 2
;   for (int kt = 0; kt < nk; ++kt) {
;     const char* st = lds + (kt & 1) * 65536;
;     ldfrag(st, 0, 0);
;     mma(1);
;     pat_rd();
;     if (kt + 1 < nk) glds(kt + 1, (kt + 1) & 1);
;     ldfrag(st, 1, 1);
;     mma(0);
;     pat_rd();
;     ldfrag(st, 2, 0);
;     mma(1);
;     pat_rd();
;     ldfrag(st, 3, 1);
;     mma(0);
;     pat_rd();
;     asm volatile("s_waitcnt vmcnt(0)" ::: "memory");
;     __syncthreads();
;   }
;   mma(1);
	v_add3_u32 v187, v186, v161, 0
	v_add3_u32 v248, v186, v163, 0
	ds_read_b128 v[200:203], v187 offset:49152
	ds_read_b128 v[228:231], v248 offset:49152
	v_add3_u32 v187, v186, v164, 0
	v_add3_u32 v248, v186, v165, 0
	ds_read_b128 v[232:235], v187 offset:49152
	ds_read_b128 v[236:239], v248 offset:49152
	s_barrier
	s_waitcnt lgkmcnt(0)
	v_mfma_f32_32x32x16_bf16 v[82:97], v[130:133], v[200:203], v[82:97]
	v_mfma_f32_32x32x16_bf16 v[50:65], v[146:149], v[200:203], v[50:65]
	v_mfma_f32_32x32x16_bf16 v[82:97], v[134:137], v[228:231], v[82:97]
	v_mfma_f32_32x32x16_bf16 v[50:65], v[150:153], v[228:231], v[50:65]
	v_mfma_f32_32x32x16_bf16 v[82:97], v[138:141], v[232:235], v[82:97]
	v_mfma_f32_32x32x16_bf16 v[50:65], v[168:171], v[232:235], v[50:65]
	v_mfma_f32_32x32x16_bf16 v[82:97], v[142:145], v[236:239], v[82:97]
	v_mfma_f32_32x32x16_bf16 v[50:65], v[172:175], v[236:239], v[50:65]
	s_barrier
	v_add3_u32 v187, v166, v161, 0
	v_add3_u32 v248, v166, v163, 0
	ds_read_b128 v[130:133], v187 offset:16384
	ds_read_b128 v[134:137], v248 offset:16384
	ds_read_b128 v[146:149], v187 offset:20480
	ds_read_b128 v[150:153], v248 offset:20480
	v_add3_u32 v187, v166, v164, 0
	v_add3_u32 v248, v166, v165, 0
	ds_read_b128 v[138:141], v187 offset:16384
	ds_read_b128 v[142:145], v248 offset:16384
	ds_read_b128 v[168:171], v187 offset:20480
	ds_read_b128 v[172:175], v248 offset:20480
	s_waitcnt vmcnt(4)
	s_barrier
	s_waitcnt lgkmcnt(0)
	v_mfma_f32_32x32x16_bf16 v[66:81], v[130:133], v[176:179], v[66:81]
	v_mfma_f32_32x32x16_bf16 v[34:49], v[146:149], v[176:179], v[34:49]
	v_mfma_f32_32x32x16_bf16 v[66:81], v[134:137], v[180:183], v[66:81]
	v_mfma_f32_32x32x16_bf16 v[34:49], v[150:153], v[180:183], v[34:49]
	v_mfma_f32_32x32x16_bf16 v[66:81], v[138:141], v[192:195], v[66:81]
	v_mfma_f32_32x32x16_bf16 v[34:49], v[168:171], v[192:195], v[34:49]
	v_mfma_f32_32x32x16_bf16 v[66:81], v[142:145], v[196:199], v[66:81]
	v_mfma_f32_32x32x16_bf16 v[34:49], v[172:175], v[196:199], v[34:49]
	v_mfma_f32_32x32x16_bf16 v[18:33], v[130:133], v[200:203], v[18:33]
	v_mfma_f32_32x32x16_bf16 v[2:17], v[146:149], v[200:203], v[2:17]
	v_mfma_f32_32x32x16_bf16 v[18:33], v[134:137], v[228:231], v[18:33]
	v_mfma_f32_32x32x16_bf16 v[2:17], v[150:153], v[228:231], v[2:17]
	v_mfma_f32_32x32x16_bf16 v[18:33], v[138:141], v[232:235], v[18:33]
	v_mfma_f32_32x32x16_bf16 v[2:17], v[168:171], v[232:235], v[2:17]
	v_mfma_f32_32x32x16_bf16 v[18:33], v[142:145], v[236:239], v[18:33]
	v_mfma_f32_32x32x16_bf16 v[2:17], v[172:175], v[236:239], v[2:17]
	s_barrier
	v_add3_u32 v187, v186, v161, s10
	v_add3_u32 v248, v186, v163, s10
	ds_read_b128 v[176:179], v187 offset:32768
	ds_read_b128 v[180:183], v248 offset:32768
	v_add3_u32 v187, v186, v164, s10
	v_add3_u32 v248, v186, v165, s10
	ds_read_b128 v[192:195], v187 offset:32768
	ds_read_b128 v[196:199], v248 offset:32768
	v_add3_u32 v187, v166, v161, s10
	v_add3_u32 v248, v166, v163, s10
	ds_read_b128 v[130:133], v187
	ds_read_b128 v[134:137], v248
	ds_read_b128 v[146:149], v187 offset:4096
	ds_read_b128 v[150:153], v248 offset:4096
	v_add3_u32 v187, v166, v164, s10
	v_add3_u32 v248, v166, v165, s10
	ds_read_b128 v[138:141], v187
	ds_read_b128 v[142:145], v248
	ds_read_b128 v[168:171], v187 offset:4096
	ds_read_b128 v[172:175], v248 offset:4096
	s_waitcnt vmcnt(2)
	s_barrier
	s_waitcnt lgkmcnt(0)
	v_mfma_f32_32x32x16_bf16 v[114:129], v[130:133], v[176:179], v[114:129]
	v_mfma_f32_32x32x16_bf16 v[98:113], v[146:149], v[176:179], v[98:113]
	v_mfma_f32_32x32x16_bf16 v[114:129], v[134:137], v[180:183], v[114:129]
	v_mfma_f32_32x32x16_bf16 v[98:113], v[150:153], v[180:183], v[98:113]
	v_mfma_f32_32x32x16_bf16 v[114:129], v[138:141], v[192:195], v[114:129]
	v_mfma_f32_32x32x16_bf16 v[98:113], v[168:171], v[192:195], v[98:113]
	v_mfma_f32_32x32x16_bf16 v[114:129], v[142:145], v[196:199], v[114:129]
	v_mfma_f32_32x32x16_bf16 v[98:113], v[172:175], v[196:199], v[98:113]
	s_barrier
	v_add3_u32 v187, v186, v161, s10
	v_add3_u32 v248, v186, v163, s10
	ds_read_b128 v[200:203], v187 offset:49152
	ds_read_b128 v[228:231], v248 offset:49152
	v_add3_u32 v187, v186, v164, s10
	v_add3_u32 v248, v186, v165, s10
	ds_read_b128 v[232:235], v187 offset:49152
	ds_read_b128 v[236:239], v248 offset:49152
	s_waitcnt vmcnt(0)
	s_barrier
	s_waitcnt lgkmcnt(0)
	v_mfma_f32_32x32x16_bf16 v[82:97], v[130:133], v[200:203], v[82:97]
	v_mfma_f32_32x32x16_bf16 v[50:65], v[146:149], v[200:203], v[50:65]
	v_mfma_f32_32x32x16_bf16 v[82:97], v[134:137], v[228:231], v[82:97]
	v_mfma_f32_32x32x16_bf16 v[50:65], v[150:153], v[228:231], v[50:65]
	v_mfma_f32_32x32x16_bf16 v[82:97], v[138:141], v[232:235], v[82:97]
	v_mfma_f32_32x32x16_bf16 v[50:65], v[168:171], v[232:235], v[50:65]
	v_mfma_f32_32x32x16_bf16 v[82:97], v[142:145], v[236:239], v[82:97]
	v_mfma_f32_32x32x16_bf16 v[50:65], v[172:175], v[236:239], v[50:65]
	s_barrier
	v_add3_u32 v187, v166, v161, s10
	v_add3_u32 v248, v166, v163, s10
	ds_read_b128 v[130:133], v187 offset:16384
	ds_read_b128 v[134:137], v248 offset:16384
	ds_read_b128 v[146:149], v187 offset:20480
	ds_read_b128 v[150:153], v248 offset:20480
	v_add3_u32 v187, v166, v164, s10
	v_add3_u32 v248, v166, v165, s10
	ds_read_b128 v[138:141], v187 offset:16384
	ds_read_b128 v[142:145], v248 offset:16384
	ds_read_b128 v[168:171], v187 offset:20480
	ds_read_b128 v[172:175], v248 offset:20480
	s_barrier
	s_waitcnt lgkmcnt(0)
	v_mfma_f32_32x32x16_bf16 v[66:81], v[130:133], v[176:179], v[66:81]
	v_mfma_f32_32x32x16_bf16 v[34:49], v[146:149], v[176:179], v[34:49]
	v_mfma_f32_32x32x16_bf16 v[66:81], v[134:137], v[180:183], v[66:81]
	v_mfma_f32_32x32x16_bf16 v[34:49], v[150:153], v[180:183], v[34:49]
	v_mfma_f32_32x32x16_bf16 v[66:81], v[138:141], v[192:195], v[66:81]
	v_mfma_f32_32x32x16_bf16 v[34:49], v[168:171], v[192:195], v[34:49]
	v_mfma_f32_32x32x16_bf16 v[66:81], v[142:145], v[196:199], v[66:81]
	v_mfma_f32_32x32x16_bf16 v[34:49], v[172:175], v[196:199], v[34:49]
	v_mfma_f32_32x32x16_bf16 v[18:33], v[130:133], v[200:203], v[18:33]
	v_mfma_f32_32x32x16_bf16 v[2:17], v[146:149], v[200:203], v[2:17]
	v_mfma_f32_32x32x16_bf16 v[18:33], v[134:137], v[228:231], v[18:33]
	v_mfma_f32_32x32x16_bf16 v[2:17], v[150:153], v[228:231], v[2:17]
	v_mfma_f32_32x32x16_bf16 v[18:33], v[138:141], v[232:235], v[18:33]
	v_mfma_f32_32x32x16_bf16 v[2:17], v[168:171], v[232:235], v[2:17]
	v_mfma_f32_32x32x16_bf16 v[18:33], v[142:145], v[236:239], v[18:33]
	v_mfma_f32_32x32x16_bf16 v[2:17], v[172:175], v[236:239], v[2:17]
	s_barrier
	s_cmp_eq_u32 s101, 0
	s_cbranch_scc0 .Lg8_ib_p1
	s_barrier
